# v64 + GEMM epilogues (QKG, QKV x2, W1 x2): all rstd4 row-scale loads issued up front instead of a load/wait/store ladder per row
# speedup vs baseline: 1.0121x; 1.0121x over previous
.LBB0_106:
	s_andn2_b64 vcc, exec, s[34:35]
	s_cbranch_vccnz .LBB0_97
	v_readlane_b32 s34, v254, 52
	v_ashrrev_i32_e32 v161, 31, v160
	v_readlane_b32 s35, v254, 53
	s_cmpk_lt_i32 s4, 0x200
	s_cselect_b32 s33, s93, s45
	v_lshl_add_u64 v[128:129], v[160:161], 2, s[34:35]
	v_add_co_u32_e32 v130, vcc, s51, v128
	s_cselect_b32 s34, s92, s44
	s_nop 0
	v_addc_co_u32_e32 v131, vcc, 0, v129, vcc
	v_add_co_u32_e32 v132, vcc, s52, v128
	s_add_u32 s36, s34, s59
	s_nop 0
	v_addc_co_u32_e32 v133, vcc, 0, v129, vcc
	v_add_co_u32_e32 v134, vcc, s53, v128
	s_addc_u32 s37, s33, 0
	s_nop 0
	v_addc_co_u32_e32 v135, vcc, 0, v129, vcc
	global_load_dword v138, v[128:129], off
	global_load_dword v162, v[130:131], off
	global_load_dword v139, v[132:133], off
	global_load_dword v163, v[134:135], off
	global_load_dword v226, v[128:129], off offset:64
	global_load_dword v227, v[130:131], off offset:64
	global_load_dword v228, v[132:133], off offset:64
	global_load_dword v229, v[134:135], off offset:64
	global_load_dword v230, v[128:129], off offset:128
	global_load_dword v231, v[130:131], off offset:128
	global_load_dword v232, v[132:133], off offset:128
	global_load_dword v233, v[134:135], off offset:128
	global_load_dword v234, v[128:129], off offset:192
	global_load_dword v235, v[130:131], off offset:192
	global_load_dword v236, v[132:133], off offset:192
	global_load_dword v237, v[134:135], off offset:192
	global_load_dword v238, v[128:129], off offset:512
	global_load_dword v239, v[130:131], off offset:512
	global_load_dword v240, v[132:133], off offset:512
	global_load_dword v241, v[134:135], off offset:512
	global_load_dword v242, v[128:129], off offset:576
	global_load_dword v243, v[130:131], off offset:576
	global_load_dword v244, v[132:133], off offset:576
	global_load_dword v245, v[134:135], off offset:576
	global_load_dword v246, v[128:129], off offset:640
	global_load_dword v247, v[130:131], off offset:640
	global_load_dword v248, v[132:133], off offset:640
	global_load_dword v249, v[134:135], off offset:640
	global_load_dword v250, v[128:129], off offset:704
	global_load_dword v251, v[130:131], off offset:704
	global_load_dword v252, v[132:133], off offset:704
	global_load_dword v253, v[134:135], off offset:704
	s_lshl_b32 s4, s4, 9
	s_and_b32 s4, s4, 0x30000
	s_mov_b32 s35, s5
	s_add_i32 s34, s4, 0x10000
	v_lshl_add_u64 v[164:165], v[160:161], 0, s[4:5]
	v_lshl_add_u64 v[166:167], s[34:35], 0, v[160:161]
	v_lshl_add_u64 v[136:137], s[36:37], 0, v[148:149]
	v_lshlrev_b64 v[164:165], 8, v[164:165]
	s_waitcnt vmcnt(0)
	v_pk_add_f32 v[138:139], v[138:139], v[162:163]
	s_nop 0
	v_add_f32_e32 v138, v138, v139
	v_fmamk_f32 v138, v138, 0x3a800000, v182
	v_mul_f32_e32 v139, 0x4b800000, v138
	v_cmp_gt_f32_e32 vcc, s54, v138
	v_lshlrev_b64 v[162:163], 8, v[166:167]
	v_lshl_add_u64 v[162:163], v[136:137], 0, v[162:163]
	v_cndmask_b32_e32 v138, v138, v139, vcc
	v_rsq_f32_e32 v161, v138
	v_lshl_add_u64 v[138:139], v[136:137], 0, v[164:165]
	v_mul_f32_e32 v164, 0x45800000, v161
	v_cndmask_b32_e32 v164, v161, v164, vcc
	v_pk_mul_f32 v[126:127], v[126:127], v[164:165] op_sel_hi:[1,0]
	v_pk_mul_f32 v[124:125], v[124:125], v[164:165] op_sel_hi:[1,0]
	v_pk_mul_f32 v[122:123], v[122:123], v[164:165] op_sel_hi:[1,0]
	v_pk_mul_f32 v[120:121], v[120:121], v[164:165] op_sel_hi:[1,0]
	v_pk_mul_f32 v[118:119], v[118:119], v[164:165] op_sel_hi:[1,0]
	v_pk_mul_f32 v[116:117], v[116:117], v[164:165] op_sel_hi:[1,0]
	v_pk_mul_f32 v[166:167], v[114:115], v[164:165] op_sel_hi:[1,0]
	v_pk_mul_f32 v[164:165], v[112:113], v[164:165] op_sel_hi:[1,0]
	v_cvt_pk_bf16_f32 v112, v124, v125
	v_cvt_pk_bf16_f32 v113, v126, v127
	v_cvt_pk_bf16_f32 v114, v120, v121
	v_cvt_pk_bf16_f32 v115, v122, v123
	v_cvt_pk_bf16_f32 v116, v116, v117
	v_cvt_pk_bf16_f32 v117, v118, v119
	s_nop 0
	v_cvt_pk_bf16_f32 v118, v164, v165
	v_cvt_pk_bf16_f32 v119, v166, v167
	global_store_dwordx4 v[138:139], v[112:115], off
	global_store_dwordx4 v[162:163], v[116:119], off
	s_nop 1
	v_mov_b32_e32 v112, v226
	s_nop 0
	v_mov_b32_e32 v114, v227
	v_mov_b32_e32 v113, v228
	v_mov_b32_e32 v115, v229
	v_add_u32_e32 v116, 16, v160
	v_ashrrev_i32_e32 v117, 31, v116
	v_lshl_add_u64 v[118:119], v[116:117], 0, s[4:5]
	v_lshl_add_u64 v[116:117], v[116:117], 0, s[34:35]
	v_lshlrev_b64 v[118:119], 8, v[118:119]
	v_pk_add_f32 v[112:113], v[112:113], v[114:115]
	s_nop 0
	v_add_f32_e32 v112, v112, v113
	v_fmamk_f32 v112, v112, 0x3a800000, v182
	v_mul_f32_e32 v113, 0x4b800000, v112
	v_cmp_gt_f32_e32 vcc, s54, v112
	v_lshlrev_b64 v[114:115], 8, v[116:117]
	v_lshl_add_u64 v[114:115], v[136:137], 0, v[114:115]
	v_cndmask_b32_e32 v112, v112, v113, vcc
	v_rsq_f32_e32 v120, v112
	v_lshl_add_u64 v[112:113], v[136:137], 0, v[118:119]
	v_mul_f32_e32 v116, 0x45800000, v120
	v_cndmask_b32_e32 v116, v120, v116, vcc
	v_pk_mul_f32 v[110:111], v[110:111], v[116:117] op_sel_hi:[1,0]
	v_pk_mul_f32 v[108:109], v[108:109], v[116:117] op_sel_hi:[1,0]
	v_pk_mul_f32 v[106:107], v[106:107], v[116:117] op_sel_hi:[1,0]
	v_pk_mul_f32 v[104:105], v[104:105], v[116:117] op_sel_hi:[1,0]
	v_pk_mul_f32 v[102:103], v[102:103], v[116:117] op_sel_hi:[1,0]
	v_pk_mul_f32 v[100:101], v[100:101], v[116:117] op_sel_hi:[1,0]
	v_pk_mul_f32 v[118:119], v[98:99], v[116:117] op_sel_hi:[1,0]
	v_pk_mul_f32 v[116:117], v[96:97], v[116:117] op_sel_hi:[1,0]
	v_cvt_pk_bf16_f32 v96, v108, v109
	v_cvt_pk_bf16_f32 v97, v110, v111
	v_cvt_pk_bf16_f32 v98, v104, v105
	v_cvt_pk_bf16_f32 v99, v106, v107
	v_cvt_pk_bf16_f32 v100, v100, v101
	v_cvt_pk_bf16_f32 v101, v102, v103
	s_nop 0
	v_cvt_pk_bf16_f32 v102, v116, v117
	v_cvt_pk_bf16_f32 v103, v118, v119
	global_store_dwordx4 v[112:113], v[96:99], off
	global_store_dwordx4 v[114:115], v[100:103], off
	s_nop 1
	v_mov_b32_e32 v96, v230
	s_nop 0
	v_mov_b32_e32 v98, v231
	v_mov_b32_e32 v97, v232
	v_mov_b32_e32 v99, v233
	v_add_u32_e32 v100, 32, v160
	v_ashrrev_i32_e32 v101, 31, v100
	v_lshl_add_u64 v[102:103], v[100:101], 0, s[4:5]
	v_lshl_add_u64 v[100:101], v[100:101], 0, s[34:35]
	v_lshlrev_b64 v[102:103], 8, v[102:103]
	v_pk_add_f32 v[96:97], v[96:97], v[98:99]
	s_nop 0
	v_add_f32_e32 v96, v96, v97
	v_fmamk_f32 v96, v96, 0x3a800000, v182
	v_mul_f32_e32 v97, 0x4b800000, v96
	v_cmp_gt_f32_e32 vcc, s54, v96
	v_lshlrev_b64 v[98:99], 8, v[100:101]
	v_lshl_add_u64 v[98:99], v[136:137], 0, v[98:99]
	v_cndmask_b32_e32 v96, v96, v97, vcc
	v_rsq_f32_e32 v104, v96
	v_lshl_add_u64 v[96:97], v[136:137], 0, v[102:103]
	v_mul_f32_e32 v100, 0x45800000, v104
	v_cndmask_b32_e32 v100, v104, v100, vcc
	v_pk_mul_f32 v[94:95], v[94:95], v[100:101] op_sel_hi:[1,0]
	v_pk_mul_f32 v[92:93], v[92:93], v[100:101] op_sel_hi:[1,0]
	v_pk_mul_f32 v[90:91], v[90:91], v[100:101] op_sel_hi:[1,0]
	v_pk_mul_f32 v[88:89], v[88:89], v[100:101] op_sel_hi:[1,0]
	v_pk_mul_f32 v[86:87], v[86:87], v[100:101] op_sel_hi:[1,0]
	v_pk_mul_f32 v[84:85], v[84:85], v[100:101] op_sel_hi:[1,0]
	v_pk_mul_f32 v[102:103], v[82:83], v[100:101] op_sel_hi:[1,0]
	v_pk_mul_f32 v[100:101], v[80:81], v[100:101] op_sel_hi:[1,0]
	v_cvt_pk_bf16_f32 v80, v92, v93
	v_cvt_pk_bf16_f32 v81, v94, v95
	v_cvt_pk_bf16_f32 v82, v88, v89
	v_cvt_pk_bf16_f32 v83, v90, v91
	v_cvt_pk_bf16_f32 v84, v84, v85
	v_cvt_pk_bf16_f32 v85, v86, v87
	s_nop 0
	v_cvt_pk_bf16_f32 v86, v100, v101
	v_cvt_pk_bf16_f32 v87, v102, v103
	global_store_dwordx4 v[96:97], v[80:83], off
	global_store_dwordx4 v[98:99], v[84:87], off
	s_nop 1
	v_mov_b32_e32 v80, v234
	s_nop 0
	v_mov_b32_e32 v82, v235
	v_mov_b32_e32 v81, v236
	v_mov_b32_e32 v83, v237
	v_add_u32_e32 v84, 48, v160
	v_ashrrev_i32_e32 v85, 31, v84
	v_lshl_add_u64 v[86:87], v[84:85], 0, s[4:5]
	v_lshl_add_u64 v[84:85], v[84:85], 0, s[34:35]
	v_lshlrev_b64 v[86:87], 8, v[86:87]
	v_pk_add_f32 v[80:81], v[80:81], v[82:83]
	s_nop 0
	v_add_f32_e32 v80, v80, v81
	v_fmamk_f32 v80, v80, 0x3a800000, v182
	v_mul_f32_e32 v81, 0x4b800000, v80
	v_cmp_gt_f32_e32 vcc, s54, v80
	v_lshlrev_b64 v[82:83], 8, v[84:85]
	v_lshl_add_u64 v[82:83], v[136:137], 0, v[82:83]
	v_cndmask_b32_e32 v80, v80, v81, vcc
	v_rsq_f32_e32 v88, v80
	v_lshl_add_u64 v[80:81], v[136:137], 0, v[86:87]
	v_mul_f32_e32 v84, 0x45800000, v88
	v_cndmask_b32_e32 v84, v88, v84, vcc
	v_pk_mul_f32 v[78:79], v[78:79], v[84:85] op_sel_hi:[1,0]
	v_pk_mul_f32 v[76:77], v[76:77], v[84:85] op_sel_hi:[1,0]
	v_pk_mul_f32 v[74:75], v[74:75], v[84:85] op_sel_hi:[1,0]
	v_pk_mul_f32 v[72:73], v[72:73], v[84:85] op_sel_hi:[1,0]
	v_pk_mul_f32 v[70:71], v[70:71], v[84:85] op_sel_hi:[1,0]
	v_pk_mul_f32 v[68:69], v[68:69], v[84:85] op_sel_hi:[1,0]
	v_pk_mul_f32 v[86:87], v[66:67], v[84:85] op_sel_hi:[1,0]
	v_pk_mul_f32 v[84:85], v[64:65], v[84:85] op_sel_hi:[1,0]
	v_cvt_pk_bf16_f32 v64, v76, v77
	v_cvt_pk_bf16_f32 v65, v78, v79
	v_cvt_pk_bf16_f32 v66, v72, v73
	v_cvt_pk_bf16_f32 v67, v74, v75
	v_cvt_pk_bf16_f32 v68, v68, v69
	v_cvt_pk_bf16_f32 v69, v70, v71
	s_nop 0
	v_cvt_pk_bf16_f32 v70, v84, v85
	v_cvt_pk_bf16_f32 v71, v86, v87
	global_store_dwordx4 v[80:81], v[64:67], off
	global_store_dwordx4 v[82:83], v[68:71], off
	s_nop 1
	v_mov_b32_e32 v64, v238
	s_nop 0
	v_mov_b32_e32 v66, v239
	v_mov_b32_e32 v65, v240
	v_mov_b32_e32 v67, v241
	v_add_u32_e32 v68, 0x80, v160
	v_ashrrev_i32_e32 v69, 31, v68
	v_lshl_add_u64 v[70:71], v[68:69], 0, s[4:5]
	v_lshl_add_u64 v[68:69], v[68:69], 0, s[34:35]
	v_lshlrev_b64 v[70:71], 8, v[70:71]
	v_pk_add_f32 v[64:65], v[64:65], v[66:67]
	s_nop 0
	v_add_f32_e32 v64, v64, v65
	v_fmamk_f32 v64, v64, 0x3a800000, v182
	v_mul_f32_e32 v65, 0x4b800000, v64
	v_cmp_gt_f32_e32 vcc, s54, v64
	v_lshlrev_b64 v[66:67], 8, v[68:69]
	v_lshl_add_u64 v[66:67], v[136:137], 0, v[66:67]
	v_cndmask_b32_e32 v64, v64, v65, vcc
	v_rsq_f32_e32 v72, v64
	v_lshl_add_u64 v[64:65], v[136:137], 0, v[70:71]
	v_mul_f32_e32 v68, 0x45800000, v72
	v_cndmask_b32_e32 v68, v72, v68, vcc
	v_pk_mul_f32 v[62:63], v[62:63], v[68:69] op_sel_hi:[1,0]
	v_pk_mul_f32 v[60:61], v[60:61], v[68:69] op_sel_hi:[1,0]
	v_pk_mul_f32 v[58:59], v[58:59], v[68:69] op_sel_hi:[1,0]
	v_pk_mul_f32 v[56:57], v[56:57], v[68:69] op_sel_hi:[1,0]
	v_pk_mul_f32 v[54:55], v[54:55], v[68:69] op_sel_hi:[1,0]
	v_pk_mul_f32 v[52:53], v[52:53], v[68:69] op_sel_hi:[1,0]
	v_pk_mul_f32 v[70:71], v[50:51], v[68:69] op_sel_hi:[1,0]
	v_pk_mul_f32 v[68:69], v[48:49], v[68:69] op_sel_hi:[1,0]
	v_cvt_pk_bf16_f32 v48, v60, v61
	v_cvt_pk_bf16_f32 v49, v62, v63
	v_cvt_pk_bf16_f32 v50, v56, v57
	v_cvt_pk_bf16_f32 v51, v58, v59
	v_cvt_pk_bf16_f32 v52, v52, v53
	v_cvt_pk_bf16_f32 v53, v54, v55
	s_nop 0
	v_cvt_pk_bf16_f32 v54, v68, v69
	v_cvt_pk_bf16_f32 v55, v70, v71
	global_store_dwordx4 v[64:65], v[48:51], off
	global_store_dwordx4 v[66:67], v[52:55], off
	s_nop 1
	v_mov_b32_e32 v48, v242
	s_nop 0
	v_mov_b32_e32 v50, v243
	v_mov_b32_e32 v49, v244
	v_mov_b32_e32 v51, v245
	v_add_u32_e32 v52, 0x90, v160
	v_ashrrev_i32_e32 v53, 31, v52
	v_lshl_add_u64 v[54:55], v[52:53], 0, s[4:5]
	v_lshl_add_u64 v[52:53], v[52:53], 0, s[34:35]
	v_lshlrev_b64 v[54:55], 8, v[54:55]
	v_pk_add_f32 v[48:49], v[48:49], v[50:51]
	s_nop 0
	v_add_f32_e32 v48, v48, v49
	v_fmamk_f32 v48, v48, 0x3a800000, v182
	v_mul_f32_e32 v49, 0x4b800000, v48
	v_cmp_gt_f32_e32 vcc, s54, v48
	v_lshlrev_b64 v[50:51], 8, v[52:53]
	v_lshl_add_u64 v[50:51], v[136:137], 0, v[50:51]
	v_cndmask_b32_e32 v48, v48, v49, vcc
	v_rsq_f32_e32 v56, v48
	v_lshl_add_u64 v[48:49], v[136:137], 0, v[54:55]
	v_mul_f32_e32 v52, 0x45800000, v56
	v_cndmask_b32_e32 v52, v56, v52, vcc
	v_pk_mul_f32 v[46:47], v[46:47], v[52:53] op_sel_hi:[1,0]
	v_pk_mul_f32 v[44:45], v[44:45], v[52:53] op_sel_hi:[1,0]
	v_pk_mul_f32 v[42:43], v[42:43], v[52:53] op_sel_hi:[1,0]
	v_pk_mul_f32 v[40:41], v[40:41], v[52:53] op_sel_hi:[1,0]
	v_pk_mul_f32 v[38:39], v[38:39], v[52:53] op_sel_hi:[1,0]
	v_pk_mul_f32 v[36:37], v[36:37], v[52:53] op_sel_hi:[1,0]
	v_pk_mul_f32 v[54:55], v[34:35], v[52:53] op_sel_hi:[1,0]
	v_pk_mul_f32 v[52:53], v[32:33], v[52:53] op_sel_hi:[1,0]
	v_cvt_pk_bf16_f32 v32, v44, v45
	v_cvt_pk_bf16_f32 v33, v46, v47
	v_cvt_pk_bf16_f32 v34, v40, v41
	v_cvt_pk_bf16_f32 v35, v42, v43
	v_cvt_pk_bf16_f32 v36, v36, v37
	v_cvt_pk_bf16_f32 v37, v38, v39
	s_nop 0
	v_cvt_pk_bf16_f32 v38, v52, v53
	v_cvt_pk_bf16_f32 v39, v54, v55
	global_store_dwordx4 v[48:49], v[32:35], off
	global_store_dwordx4 v[50:51], v[36:39], off
	s_nop 1
	v_mov_b32_e32 v32, v246
	s_nop 0
	v_mov_b32_e32 v34, v247
	v_mov_b32_e32 v33, v248
	v_mov_b32_e32 v35, v249
	v_add_u32_e32 v36, 0xa0, v160
	v_ashrrev_i32_e32 v37, 31, v36
	v_lshl_add_u64 v[38:39], v[36:37], 0, s[4:5]
	v_lshl_add_u64 v[36:37], v[36:37], 0, s[34:35]
	v_lshlrev_b64 v[38:39], 8, v[38:39]
	v_pk_add_f32 v[32:33], v[32:33], v[34:35]
	s_nop 0
	v_add_f32_e32 v32, v32, v33
	v_fmamk_f32 v32, v32, 0x3a800000, v182
	v_mul_f32_e32 v33, 0x4b800000, v32
	v_cmp_gt_f32_e32 vcc, s54, v32
	v_lshlrev_b64 v[34:35], 8, v[36:37]
	v_lshl_add_u64 v[34:35], v[136:137], 0, v[34:35]
	v_cndmask_b32_e32 v32, v32, v33, vcc
	v_rsq_f32_e32 v40, v32
	v_lshl_add_u64 v[32:33], v[136:137], 0, v[38:39]
	v_mul_f32_e32 v36, 0x45800000, v40
	v_cndmask_b32_e32 v36, v40, v36, vcc
	v_pk_mul_f32 v[30:31], v[30:31], v[36:37] op_sel_hi:[1,0]
	v_pk_mul_f32 v[28:29], v[28:29], v[36:37] op_sel_hi:[1,0]
	v_pk_mul_f32 v[26:27], v[26:27], v[36:37] op_sel_hi:[1,0]
	v_pk_mul_f32 v[24:25], v[24:25], v[36:37] op_sel_hi:[1,0]
	v_pk_mul_f32 v[22:23], v[22:23], v[36:37] op_sel_hi:[1,0]
	v_pk_mul_f32 v[20:21], v[20:21], v[36:37] op_sel_hi:[1,0]
	v_pk_mul_f32 v[38:39], v[18:19], v[36:37] op_sel_hi:[1,0]
	v_pk_mul_f32 v[36:37], v[16:17], v[36:37] op_sel_hi:[1,0]
	v_cvt_pk_bf16_f32 v16, v28, v29
	v_cvt_pk_bf16_f32 v17, v30, v31
	v_cvt_pk_bf16_f32 v18, v24, v25
	v_cvt_pk_bf16_f32 v19, v26, v27
	v_cvt_pk_bf16_f32 v20, v20, v21
	v_cvt_pk_bf16_f32 v21, v22, v23
	s_nop 0
	v_cvt_pk_bf16_f32 v22, v36, v37
	v_cvt_pk_bf16_f32 v23, v38, v39
	global_store_dwordx4 v[32:33], v[16:19], off
	global_store_dwordx4 v[34:35], v[20:23], off
	s_nop 1
	v_mov_b32_e32 v16, v250
	s_nop 0
	v_mov_b32_e32 v18, v251
	v_mov_b32_e32 v17, v252
	v_mov_b32_e32 v19, v253
	v_add_u32_e32 v20, 0xb0, v160
	v_ashrrev_i32_e32 v21, 31, v20
	v_lshl_add_u64 v[22:23], v[20:21], 0, s[4:5]
	v_lshl_add_u64 v[20:21], v[20:21], 0, s[34:35]
	v_lshlrev_b64 v[22:23], 8, v[22:23]
	v_pk_add_f32 v[16:17], v[16:17], v[18:19]
	s_nop 0
	v_add_f32_e32 v16, v16, v17
	v_fmamk_f32 v16, v16, 0x3a800000, v182
	v_mul_f32_e32 v17, 0x4b800000, v16
	v_cmp_gt_f32_e32 vcc, s54, v16
	v_lshlrev_b64 v[18:19], 8, v[20:21]
	v_lshl_add_u64 v[18:19], v[136:137], 0, v[18:19]
	v_cndmask_b32_e32 v16, v16, v17, vcc
	v_rsq_f32_e32 v24, v16
	v_lshl_add_u64 v[16:17], v[136:137], 0, v[22:23]
	v_mul_f32_e32 v20, 0x45800000, v24
	v_cndmask_b32_e32 v20, v24, v20, vcc
	v_pk_mul_f32 v[14:15], v[14:15], v[20:21] op_sel_hi:[1,0]
	v_pk_mul_f32 v[12:13], v[12:13], v[20:21] op_sel_hi:[1,0]
	v_pk_mul_f32 v[10:11], v[10:11], v[20:21] op_sel_hi:[1,0]
	v_pk_mul_f32 v[8:9], v[8:9], v[20:21] op_sel_hi:[1,0]
	v_pk_mul_f32 v[6:7], v[6:7], v[20:21] op_sel_hi:[1,0]
	v_pk_mul_f32 v[4:5], v[4:5], v[20:21] op_sel_hi:[1,0]
	v_pk_mul_f32 v[22:23], v[2:3], v[20:21] op_sel_hi:[1,0]
	v_pk_mul_f32 v[20:21], v[0:1], v[20:21] op_sel_hi:[1,0]
	v_cvt_pk_bf16_f32 v0, v12, v13
	v_cvt_pk_bf16_f32 v1, v14, v15
	v_cvt_pk_bf16_f32 v2, v8, v9
	v_cvt_pk_bf16_f32 v3, v10, v11
	v_cvt_pk_bf16_f32 v4, v4, v5
	v_cvt_pk_bf16_f32 v5, v6, v7
	s_nop 0
	v_cvt_pk_bf16_f32 v6, v20, v21
	v_cvt_pk_bf16_f32 v7, v22, v23
	global_store_dwordx4 v[16:17], v[0:3], off
	global_store_dwordx4 v[18:19], v[4:7], off
	s_branch .LBB0_97

.LBB0_441:
	s_add_u32 s22, s42, 0xfffc0080
	s_addc_u32 s23, s43, -1
	s_add_i32 s79, 0, 0x10000
	v_add_u32_e32 v156, s79, v161
	ds_read_b128 v[144:147], v156
	ds_read_b128 v[148:151], v156 offset:1024
	ds_read_b128 v[152:155], v156 offset:2048
	ds_read_b128 v[164:167], v156 offset:3072
	s_cmp_eq_u32 s60, 12
	s_cselect_b32 s47, s5, s23
	s_cselect_b32 s46, s4, s22
	s_cselect_b32 s45, s7, s19
	s_cselect_b32 s44, s6, s18
	v_lshl_add_u64 v[156:157], s[42:43], 0, v[140:141]
	s_add_i32 m0, s52, 0xc000
	ds_read_b128 v[168:171], v163
	ds_read_b128 v[172:175], v163 offset:1024
	ds_read_b128 v[176:179], v163 offset:2048
	ds_read_b128 v[180:183], v163 offset:3072
	ds_read_b128 v[184:187], v163 offset:4096
	ds_read_b128 v[188:191], v163 offset:5120
	ds_read_b128 v[192:195], v163 offset:6144
	ds_read_b128 v[200:203], v163 offset:7168
	global_load_lds_dwordx4 v[156:157], off
	v_lshl_add_u64 v[156:157], s[42:43], 0, v[142:143]
	s_add_i32 m0, s52, 0xe000
	s_nop 0
	global_load_lds_dwordx4 v[156:157], off
	s_waitcnt lgkmcnt(8)
	s_barrier
	s_waitcnt lgkmcnt(0)
	s_setprio 1
	s_waitcnt lgkmcnt(0)
	v_mfma_f32_16x16x32_bf16 v[124:127], v[144:147], v[168:171], v[124:127]
	v_mfma_f32_16x16x32_bf16 v[120:123], v[152:155], v[168:171], v[120:123]
	v_mfma_f32_16x16x32_bf16 v[108:111], v[144:147], v[176:179], v[108:111]
	v_mfma_f32_16x16x32_bf16 v[104:107], v[152:155], v[176:179], v[104:107]
	v_mfma_f32_16x16x32_bf16 v[92:95], v[144:147], v[184:187], v[92:95]
	v_mfma_f32_16x16x32_bf16 v[88:91], v[152:155], v[184:187], v[88:91]
	v_mfma_f32_16x16x32_bf16 v[76:79], v[144:147], v[192:195], v[76:79]
	v_mfma_f32_16x16x32_bf16 v[72:75], v[152:155], v[192:195], v[72:75]
	v_mfma_f32_16x16x32_bf16 v[124:127], v[148:151], v[172:175], v[124:127]
	v_mfma_f32_16x16x32_bf16 v[120:123], v[164:167], v[172:175], v[120:123]
	v_mfma_f32_16x16x32_bf16 v[108:111], v[148:151], v[180:183], v[108:111]
	v_mfma_f32_16x16x32_bf16 v[104:107], v[164:167], v[180:183], v[104:107]
	v_mfma_f32_16x16x32_bf16 v[92:95], v[148:151], v[188:191], v[92:95]
	v_mfma_f32_16x16x32_bf16 v[88:91], v[164:167], v[188:191], v[88:91]
	v_mfma_f32_16x16x32_bf16 v[76:79], v[148:151], v[200:203], v[76:79]
	v_mfma_f32_16x16x32_bf16 v[72:75], v[164:167], v[200:203], v[72:75]
	s_setprio 0
	s_barrier
	s_add_i32 s80, 0, 0x14000
	v_add_u32_e32 v156, s80, v161
	s_add_i32 s22, s79, s51
	ds_read_b128 v[204:207], v156
	ds_read_b128 v[208:211], v156 offset:1024
	ds_read_b128 v[212:215], v156 offset:2048
	ds_read_b128 v[216:219], v156 offset:3072
	v_lshl_add_u64 v[156:157], s[44:45], 0, v[128:129]
	s_mov_b32 m0, s22
	v_lshl_add_u64 v[220:221], s[44:45], 0, v[134:135]
	global_load_lds_dwordx4 v[156:157], off
	s_add_i32 m0, s22, 0x2000
	s_nop 0
	global_load_lds_dwordx4 v[220:221], off
	s_barrier
	s_waitcnt lgkmcnt(0)
	s_setprio 1
	s_waitcnt lgkmcnt(0)
	v_mfma_f32_16x16x32_bf16 v[116:119], v[204:207], v[168:171], v[116:119]
	v_mfma_f32_16x16x32_bf16 v[112:115], v[212:215], v[168:171], v[112:115]
	v_mfma_f32_16x16x32_bf16 v[100:103], v[204:207], v[176:179], v[100:103]
	v_mfma_f32_16x16x32_bf16 v[96:99], v[212:215], v[176:179], v[96:99]
	v_mfma_f32_16x16x32_bf16 v[84:87], v[204:207], v[184:187], v[84:87]
	v_mfma_f32_16x16x32_bf16 v[80:83], v[212:215], v[184:187], v[80:83]
	v_mfma_f32_16x16x32_bf16 v[68:71], v[204:207], v[192:195], v[68:71]
	v_mfma_f32_16x16x32_bf16 v[64:67], v[212:215], v[192:195], v[64:67]
	v_mfma_f32_16x16x32_bf16 v[116:119], v[208:211], v[172:175], v[116:119]
	v_mfma_f32_16x16x32_bf16 v[112:115], v[216:219], v[172:175], v[112:115]
	v_mfma_f32_16x16x32_bf16 v[100:103], v[208:211], v[180:183], v[100:103]
	v_mfma_f32_16x16x32_bf16 v[96:99], v[216:219], v[180:183], v[96:99]
	v_mfma_f32_16x16x32_bf16 v[84:87], v[208:211], v[188:191], v[84:87]
	v_mfma_f32_16x16x32_bf16 v[80:83], v[216:219], v[188:191], v[80:83]
	v_mfma_f32_16x16x32_bf16 v[68:71], v[208:211], v[200:203], v[68:71]
	v_mfma_f32_16x16x32_bf16 v[64:67], v[216:219], v[200:203], v[64:67]
	s_setprio 0
	s_mov_b32 m0, s52
	v_lshl_add_u64 v[222:223], s[46:47], 0, v[138:139]
	s_barrier
	ds_read_b128 v[168:171], v163 offset:16384
	ds_read_b128 v[172:175], v163 offset:17408
	ds_read_b128 v[176:179], v163 offset:18432
	ds_read_b128 v[180:183], v163 offset:19456
	ds_read_b128 v[184:187], v163 offset:20480
	ds_read_b128 v[188:191], v163 offset:21504
	ds_read_b128 v[192:195], v163 offset:22528
	ds_read_b128 v[200:203], v163 offset:23552
	global_load_lds_dwordx4 v[222:223], off
	v_lshl_add_u64 v[224:225], s[46:47], 0, v[136:137]
	s_mov_b32 m0, s53
	s_nop 0
	global_load_lds_dwordx4 v[224:225], off
	s_barrier
	s_waitcnt lgkmcnt(0)
	s_setprio 1
	s_waitcnt lgkmcnt(0)
	v_mfma_f32_16x16x32_bf16 v[60:63], v[144:147], v[168:171], v[60:63]
	v_mfma_f32_16x16x32_bf16 v[56:59], v[152:155], v[168:171], v[56:59]
	v_mfma_f32_16x16x32_bf16 v[44:47], v[144:147], v[176:179], v[44:47]
	v_mfma_f32_16x16x32_bf16 v[40:43], v[152:155], v[176:179], v[40:43]
	v_mfma_f32_16x16x32_bf16 v[28:31], v[144:147], v[184:187], v[28:31]
	v_mfma_f32_16x16x32_bf16 v[24:27], v[152:155], v[184:187], v[24:27]
	v_mfma_f32_16x16x32_bf16 v[12:15], v[144:147], v[192:195], v[12:15]
	v_mfma_f32_16x16x32_bf16 v[8:11], v[152:155], v[192:195], v[8:11]
	v_mfma_f32_16x16x32_bf16 v[60:63], v[148:151], v[172:175], v[60:63]
	v_mfma_f32_16x16x32_bf16 v[56:59], v[164:167], v[172:175], v[56:59]
	v_mfma_f32_16x16x32_bf16 v[44:47], v[148:151], v[180:183], v[44:47]
	v_mfma_f32_16x16x32_bf16 v[40:43], v[164:167], v[180:183], v[40:43]
	v_mfma_f32_16x16x32_bf16 v[28:31], v[148:151], v[188:191], v[28:31]
	v_mfma_f32_16x16x32_bf16 v[24:27], v[164:167], v[188:191], v[24:27]
	v_mfma_f32_16x16x32_bf16 v[12:15], v[148:151], v[200:203], v[12:15]
	v_mfma_f32_16x16x32_bf16 v[8:11], v[164:167], v[200:203], v[8:11]
	s_setprio 0
	s_barrier
	s_add_u32 s22, s44, 0x40000
	s_addc_u32 s23, s45, 0
	s_add_i32 s79, s80, s51
	v_lshl_add_u64 v[144:145], s[22:23], 0, v[128:129]
	s_mov_b32 m0, s79
	s_nop 0
	global_load_lds_dwordx4 v[144:145], off
	v_lshl_add_u64 v[144:145], s[22:23], 0, v[134:135]
	s_add_i32 m0, s79, 0x2000
	s_nop 0
	global_load_lds_dwordx4 v[144:145], off
	s_waitcnt vmcnt(6)
	s_barrier
	s_setprio 1
	v_mfma_f32_16x16x32_bf16 v[52:55], v[204:207], v[168:171], v[52:55]
	v_mfma_f32_16x16x32_bf16 v[48:51], v[212:215], v[168:171], v[48:51]
	v_mfma_f32_16x16x32_bf16 v[36:39], v[204:207], v[176:179], v[36:39]
	v_mfma_f32_16x16x32_bf16 v[32:35], v[212:215], v[176:179], v[32:35]
	v_mfma_f32_16x16x32_bf16 v[20:23], v[204:207], v[184:187], v[20:23]
	v_mfma_f32_16x16x32_bf16 v[16:19], v[212:215], v[184:187], v[16:19]
	v_mfma_f32_16x16x32_bf16 v[4:7], v[204:207], v[192:195], v[4:7]
	v_mfma_f32_16x16x32_bf16 v[0:3], v[212:215], v[192:195], v[0:3]
	v_mfma_f32_16x16x32_bf16 v[52:55], v[208:211], v[172:175], v[52:55]
	v_mfma_f32_16x16x32_bf16 v[48:51], v[216:219], v[172:175], v[48:51]
	v_mfma_f32_16x16x32_bf16 v[36:39], v[208:211], v[180:183], v[36:39]
	v_mfma_f32_16x16x32_bf16 v[32:35], v[216:219], v[180:183], v[32:35]
	v_mfma_f32_16x16x32_bf16 v[20:23], v[208:211], v[188:191], v[20:23]
	v_mfma_f32_16x16x32_bf16 v[16:19], v[216:219], v[188:191], v[16:19]
	v_mfma_f32_16x16x32_bf16 v[4:7], v[208:211], v[200:203], v[4:7]
	v_mfma_f32_16x16x32_bf16 v[0:3], v[216:219], v[200:203], v[0:3]
	s_setprio 0
	s_add_i32 s79, 0, 0x18000
	v_add_u32_e32 v164, s79, v161
	s_barrier
	ds_read_b128 v[144:147], v164
	ds_read_b128 v[148:151], v164 offset:1024
	ds_read_b128 v[152:155], v164 offset:2048
	ds_read_b128 v[164:167], v164 offset:3072
	s_add_u32 s22, s46, 0x40000
	s_addc_u32 s23, s47, 0
	s_mov_b32 m0, s70
	v_lshl_add_u64 v[204:205], s[22:23], 0, v[138:139]
	ds_read_b128 v[168:171], v163 offset:32768
	ds_read_b128 v[172:175], v163 offset:33792
	ds_read_b128 v[176:179], v163 offset:34816
	ds_read_b128 v[180:183], v163 offset:35840
	ds_read_b128 v[184:187], v163 offset:36864
	ds_read_b128 v[188:191], v163 offset:37888
	ds_read_b128 v[192:195], v163 offset:38912
	ds_read_b128 v[200:203], v163 offset:39936
	global_load_lds_dwordx4 v[204:205], off
	v_lshl_add_u64 v[204:205], s[22:23], 0, v[136:137]
	s_mov_b32 m0, s71
	s_nop 0
	global_load_lds_dwordx4 v[204:205], off
	s_waitcnt lgkmcnt(8)
	s_barrier
	s_waitcnt lgkmcnt(0)
	s_setprio 1
	s_waitcnt lgkmcnt(0)
	v_mfma_f32_16x16x32_bf16 v[124:127], v[144:147], v[168:171], v[124:127]
	v_mfma_f32_16x16x32_bf16 v[120:123], v[152:155], v[168:171], v[120:123]
	v_mfma_f32_16x16x32_bf16 v[108:111], v[144:147], v[176:179], v[108:111]
	v_mfma_f32_16x16x32_bf16 v[104:107], v[152:155], v[176:179], v[104:107]
	v_mfma_f32_16x16x32_bf16 v[92:95], v[144:147], v[184:187], v[92:95]
	v_mfma_f32_16x16x32_bf16 v[88:91], v[152:155], v[184:187], v[88:91]
	v_mfma_f32_16x16x32_bf16 v[76:79], v[144:147], v[192:195], v[76:79]
	v_mfma_f32_16x16x32_bf16 v[72:75], v[152:155], v[192:195], v[72:75]
	v_mfma_f32_16x16x32_bf16 v[124:127], v[148:151], v[172:175], v[124:127]
	v_mfma_f32_16x16x32_bf16 v[120:123], v[164:167], v[172:175], v[120:123]
	v_mfma_f32_16x16x32_bf16 v[108:111], v[148:151], v[180:183], v[108:111]
	v_mfma_f32_16x16x32_bf16 v[104:107], v[164:167], v[180:183], v[104:107]
	v_mfma_f32_16x16x32_bf16 v[92:95], v[148:151], v[188:191], v[92:95]
	v_mfma_f32_16x16x32_bf16 v[88:91], v[164:167], v[188:191], v[88:91]
	v_mfma_f32_16x16x32_bf16 v[76:79], v[148:151], v[200:203], v[76:79]
	v_mfma_f32_16x16x32_bf16 v[72:75], v[164:167], v[200:203], v[72:75]
	s_setprio 0
	s_barrier
	s_add_i32 s46, 0, 0x1c000
	s_add_i32 s22, s79, s51
	v_add_u32_e32 v216, s46, v161
	v_lshl_add_u64 v[156:157], v[156:157], 0, s[40:41]
	s_mov_b32 m0, s22
	ds_read_b128 v[204:207], v216
	ds_read_b128 v[208:211], v216 offset:1024
	ds_read_b128 v[212:215], v216 offset:2048
	ds_read_b128 v[216:219], v216 offset:3072
	global_load_lds_dwordx4 v[156:157], off
	v_lshl_add_u64 v[156:157], v[220:221], 0, s[40:41]
	s_add_i32 m0, s22, 0x2000
	s_nop 0
	global_load_lds_dwordx4 v[156:157], off
	s_barrier
	s_waitcnt lgkmcnt(0)
	s_setprio 1
	s_waitcnt lgkmcnt(0)
	v_mfma_f32_16x16x32_bf16 v[116:119], v[204:207], v[168:171], v[116:119]
	v_mfma_f32_16x16x32_bf16 v[112:115], v[212:215], v[168:171], v[112:115]
	v_mfma_f32_16x16x32_bf16 v[100:103], v[204:207], v[176:179], v[100:103]
	v_mfma_f32_16x16x32_bf16 v[96:99], v[212:215], v[176:179], v[96:99]
	v_mfma_f32_16x16x32_bf16 v[84:87], v[204:207], v[184:187], v[84:87]
	v_mfma_f32_16x16x32_bf16 v[80:83], v[212:215], v[184:187], v[80:83]
	v_mfma_f32_16x16x32_bf16 v[68:71], v[204:207], v[192:195], v[68:71]
	v_mfma_f32_16x16x32_bf16 v[64:67], v[212:215], v[192:195], v[64:67]
	v_mfma_f32_16x16x32_bf16 v[116:119], v[208:211], v[172:175], v[116:119]
	v_mfma_f32_16x16x32_bf16 v[112:115], v[216:219], v[172:175], v[112:115]
	v_mfma_f32_16x16x32_bf16 v[100:103], v[208:211], v[180:183], v[100:103]
	v_mfma_f32_16x16x32_bf16 v[96:99], v[216:219], v[180:183], v[96:99]
	v_mfma_f32_16x16x32_bf16 v[84:87], v[208:211], v[188:191], v[84:87]
	v_mfma_f32_16x16x32_bf16 v[80:83], v[216:219], v[188:191], v[80:83]
	v_mfma_f32_16x16x32_bf16 v[68:71], v[208:211], v[200:203], v[68:71]
	v_mfma_f32_16x16x32_bf16 v[64:67], v[216:219], v[200:203], v[64:67]
	s_setprio 0
	s_mov_b32 m0, s72
	v_lshl_add_u64 v[156:157], v[222:223], 0, s[40:41]
	s_barrier
	ds_read_b128 v[168:171], v163 offset:49152
	ds_read_b128 v[172:175], v163 offset:50176
	ds_read_b128 v[176:179], v163 offset:51200
	ds_read_b128 v[180:183], v163 offset:52224
	ds_read_b128 v[184:187], v163 offset:53248
	ds_read_b128 v[188:191], v163 offset:54272
	ds_read_b128 v[192:195], v163 offset:55296
	ds_read_b128 v[200:203], v163 offset:56320
	global_load_lds_dwordx4 v[156:157], off
	v_lshl_add_u64 v[156:157], v[224:225], 0, s[40:41]
	s_mov_b32 m0, s73
	s_nop 0
	global_load_lds_dwordx4 v[156:157], off
	s_barrier
	s_waitcnt lgkmcnt(0)
	s_setprio 1
	s_waitcnt lgkmcnt(0)
	v_mfma_f32_16x16x32_bf16 v[60:63], v[144:147], v[168:171], v[60:63]
	v_mfma_f32_16x16x32_bf16 v[56:59], v[152:155], v[168:171], v[56:59]
	v_mfma_f32_16x16x32_bf16 v[44:47], v[144:147], v[176:179], v[44:47]
	v_mfma_f32_16x16x32_bf16 v[40:43], v[152:155], v[176:179], v[40:43]
	v_mfma_f32_16x16x32_bf16 v[28:31], v[144:147], v[184:187], v[28:31]
	v_mfma_f32_16x16x32_bf16 v[24:27], v[152:155], v[184:187], v[24:27]
	v_mfma_f32_16x16x32_bf16 v[12:15], v[144:147], v[192:195], v[12:15]
	v_mfma_f32_16x16x32_bf16 v[8:11], v[152:155], v[192:195], v[8:11]
	v_mfma_f32_16x16x32_bf16 v[60:63], v[148:151], v[172:175], v[60:63]
	v_mfma_f32_16x16x32_bf16 v[56:59], v[164:167], v[172:175], v[56:59]
	v_mfma_f32_16x16x32_bf16 v[44:47], v[148:151], v[180:183], v[44:47]
	v_mfma_f32_16x16x32_bf16 v[40:43], v[164:167], v[180:183], v[40:43]
	v_mfma_f32_16x16x32_bf16 v[28:31], v[148:151], v[188:191], v[28:31]
	v_mfma_f32_16x16x32_bf16 v[24:27], v[164:167], v[188:191], v[24:27]
	v_mfma_f32_16x16x32_bf16 v[12:15], v[148:151], v[200:203], v[12:15]
	v_mfma_f32_16x16x32_bf16 v[8:11], v[164:167], v[200:203], v[8:11]
	s_setprio 0
	s_barrier
	s_add_u32 s22, s44, 0x40080
	s_addc_u32 s23, s45, 0
	s_add_i32 s44, s46, s51
	v_lshl_add_u64 v[144:145], s[22:23], 0, v[128:129]
	s_mov_b32 m0, s44
	s_nop 0
	global_load_lds_dwordx4 v[144:145], off
	v_lshl_add_u64 v[144:145], s[22:23], 0, v[134:135]
	s_add_i32 m0, s44, 0x2000
	s_nop 0
	global_load_lds_dwordx4 v[144:145], off
	s_waitcnt vmcnt(6)
	s_barrier
	s_setprio 1
	v_mfma_f32_16x16x32_bf16 v[52:55], v[204:207], v[168:171], v[52:55]
	v_mfma_f32_16x16x32_bf16 v[48:51], v[212:215], v[168:171], v[48:51]
	v_mfma_f32_16x16x32_bf16 v[36:39], v[204:207], v[176:179], v[36:39]
	v_mfma_f32_16x16x32_bf16 v[32:35], v[212:215], v[176:179], v[32:35]
	v_mfma_f32_16x16x32_bf16 v[20:23], v[204:207], v[184:187], v[20:23]
	v_mfma_f32_16x16x32_bf16 v[16:19], v[212:215], v[184:187], v[16:19]
	v_mfma_f32_16x16x32_bf16 v[4:7], v[204:207], v[192:195], v[4:7]
	v_mfma_f32_16x16x32_bf16 v[0:3], v[212:215], v[192:195], v[0:3]
	v_mfma_f32_16x16x32_bf16 v[52:55], v[208:211], v[172:175], v[52:55]
	v_mfma_f32_16x16x32_bf16 v[48:51], v[216:219], v[172:175], v[48:51]
	v_mfma_f32_16x16x32_bf16 v[36:39], v[208:211], v[180:183], v[36:39]
	v_mfma_f32_16x16x32_bf16 v[32:35], v[216:219], v[180:183], v[32:35]
	v_mfma_f32_16x16x32_bf16 v[20:23], v[208:211], v[188:191], v[20:23]
	v_mfma_f32_16x16x32_bf16 v[16:19], v[216:219], v[188:191], v[16:19]
	v_mfma_f32_16x16x32_bf16 v[4:7], v[208:211], v[200:203], v[4:7]
	v_mfma_f32_16x16x32_bf16 v[0:3], v[216:219], v[200:203], v[0:3]
	s_setprio 0
	s_add_i32 s60, s60, 2
	s_add_u32 s42, s42, 0x100
	s_addc_u32 s43, s43, 0
	s_add_u32 s18, s18, 0x100
	s_addc_u32 s19, s19, 0
	s_cmp_gt_u32 s60, 13
	s_barrier
	s_cbranch_scc0 .LBB0_441
	v_add_u32_e32 v152, s33, v160
	v_ashrrev_i32_e32 v153, 31, v152
	v_lshl_add_u64 v[144:145], v[152:153], 2, s[8:9]
	v_add_co_u32_e32 v146, vcc, 0x40000, v144
	global_load_dword v156, v[144:145], off
	s_nop 0
	v_addc_co_u32_e32 v147, vcc, 0, v145, vcc
	v_add_co_u32_e32 v148, vcc, 0x80000, v144
	global_load_dword v164, v[146:147], off
	s_nop 0
	v_addc_co_u32_e32 v149, vcc, 0, v145, vcc
	v_add_co_u32_e32 v150, vcc, 0xc0000, v144
	global_load_dword v157, v[148:149], off
	s_nop 0
	v_addc_co_u32_e32 v151, vcc, 0, v145, vcc
	global_load_dword v165, v[150:151], off
	global_load_dword v226, v[144:145], off offset:64
	global_load_dword v227, v[146:147], off offset:64
	global_load_dword v228, v[148:149], off offset:64
	global_load_dword v229, v[150:151], off offset:64
	global_load_dword v230, v[144:145], off offset:128
	global_load_dword v231, v[146:147], off offset:128
	global_load_dword v232, v[148:149], off offset:128
	global_load_dword v233, v[150:151], off offset:128
	global_load_dword v234, v[144:145], off offset:192
	global_load_dword v235, v[146:147], off offset:192
	global_load_dword v236, v[148:149], off offset:192
	global_load_dword v237, v[150:151], off offset:192
	global_load_dword v238, v[144:145], off offset:512
	global_load_dword v239, v[146:147], off offset:512
	global_load_dword v240, v[148:149], off offset:512
	global_load_dword v241, v[150:151], off offset:512
	global_load_dword v242, v[144:145], off offset:576
	global_load_dword v243, v[146:147], off offset:576
	global_load_dword v244, v[148:149], off offset:576
	global_load_dword v245, v[150:151], off offset:576
	global_load_dword v246, v[144:145], off offset:640
	global_load_dword v247, v[146:147], off offset:640
	global_load_dword v248, v[148:149], off offset:640
	global_load_dword v249, v[150:151], off offset:640
	global_load_dword v250, v[144:145], off offset:704
	global_load_dword v251, v[146:147], off offset:704
	global_load_dword v252, v[148:149], off offset:704
	global_load_dword v253, v[150:151], off offset:704
	v_subrev_u32_e32 v152, s74, v152
	v_add_u32_e32 v154, s78, v162
	v_ashrrev_i32_e32 v155, 31, v154
	v_lshlrev_b64 v[154:155], 1, v[154:155]
	s_mov_b32 s78, s76
	s_mov_b32 s33, s77
	s_mov_b64 s[44:45], s[6:7]
	s_mov_b64 s[42:43], s[4:5]
	s_waitcnt vmcnt(0)
	v_pk_add_f32 v[156:157], v[156:157], v[164:165]
	s_nop 0
	v_add_f32_e32 v153, v156, v157
	v_fmamk_f32 v153, v153, 0x3a800000, v158
	v_cmp_gt_f32_e32 vcc, s67, v153
	v_mul_f32_e32 v156, 0x4b800000, v153
	s_nop 0
	v_cndmask_b32_e32 v153, v153, v156, vcc
	v_rsq_f32_e32 v153, v153
	s_nop 0
	v_mul_f32_e32 v156, 0x45800000, v153
	v_cndmask_b32_e32 v164, v153, v156, vcc
	v_pk_mul_f32 v[120:121], v[120:121], v[164:165] op_sel_hi:[1,0]
	v_ashrrev_i32_e32 v153, 31, v152
	v_pk_mul_f32 v[124:125], v[124:125], v[164:165] op_sel_hi:[1,0]
	v_pk_mul_f32 v[122:123], v[122:123], v[164:165] op_sel_hi:[1,0]
	v_max_f32_e32 v120, 0, v120
	v_lshlrev_b64 v[156:157], 13, v[152:153]
	v_pk_mul_f32 v[126:127], v[126:127], v[164:165] op_sel_hi:[1,0]
	v_mul_f32_e32 v153, v120, v120
	v_max_f32_e32 v120, 0, v125
	v_max_f32_e32 v121, 0, v121
	v_max_f32_e32 v122, 0, v122
	v_lshl_add_u64 v[156:157], s[92:93], 0, v[156:157]
	v_max_f32_e32 v124, 0, v124
	v_mul_f32_e32 v120, v120, v120
	v_mul_f32_e32 v125, v121, v121
	v_max_f32_e32 v121, 0, v126
	v_mul_f32_e32 v126, v122, v122
	v_max_f32_e32 v122, 0, v127
	v_max_f32_e32 v123, 0, v123
	v_pk_mul_f32 v[114:115], v[114:115], v[164:165] op_sel_hi:[1,0]
	v_pk_mul_f32 v[112:113], v[112:113], v[164:165] op_sel_hi:[1,0]
	v_lshl_add_u64 v[156:157], v[156:157], 0, v[154:155]
	v_mul_f32_e32 v124, v124, v124
	v_mul_f32_e32 v121, v121, v121
	v_mul_f32_e32 v122, v122, v122
	v_mul_f32_e32 v123, v123, v123
	v_cvt_pk_bf16_f32 v120, v124, v120
	v_pk_mul_f32 v[118:119], v[118:119], v[164:165] op_sel_hi:[1,0]
	v_pk_mul_f32 v[116:117], v[116:117], v[164:165] op_sel_hi:[1,0]
	v_max_f32_e32 v112, 0, v112
	v_max_f32_e32 v113, 0, v113
	v_max_f32_e32 v114, 0, v114
	v_cvt_pk_bf16_f32 v121, v121, v122
	v_cvt_pk_bf16_f32 v122, v153, v125
	v_cvt_pk_bf16_f32 v123, v126, v123
	global_store_dwordx4 v[156:157], v[120:123], off
	v_max_f32_e32 v115, 0, v115
	v_max_f32_e32 v116, 0, v116
	v_mul_f32_e32 v120, v112, v112
	v_max_f32_e32 v112, 0, v117
	v_mul_f32_e32 v117, v113, v113
	v_max_f32_e32 v113, 0, v118
	v_mul_f32_e32 v118, v114, v114
	v_max_f32_e32 v114, 0, v119
	v_mul_f32_e32 v112, v112, v112
	v_mul_f32_e32 v113, v113, v113
	v_mul_f32_e32 v114, v114, v114
	v_mul_f32_e32 v115, v115, v115
	v_mul_f32_e32 v116, v116, v116
	v_cvt_pk_bf16_f32 v112, v116, v112
	v_cvt_pk_bf16_f32 v113, v113, v114
	v_cvt_pk_bf16_f32 v114, v120, v117
	v_cvt_pk_bf16_f32 v115, v118, v115
	global_store_dwordx4 v[156:157], v[112:115], off offset:256
	s_nop 1
	v_mov_b32_e32 v112, v226
	s_nop 0
	v_mov_b32_e32 v114, v227
	v_mov_b32_e32 v113, v228
	v_mov_b32_e32 v115, v229
	v_pk_add_f32 v[112:113], v[112:113], v[114:115]
	s_nop 0
	v_add_f32_e32 v112, v112, v113
	v_fmamk_f32 v112, v112, 0x3a800000, v158
	v_cmp_gt_f32_e32 vcc, s67, v112
	v_mul_f32_e32 v113, 0x4b800000, v112
	s_nop 0
	v_cndmask_b32_e32 v112, v112, v113, vcc
	v_rsq_f32_e32 v112, v112
	s_nop 0
	v_mul_f32_e32 v113, 0x45800000, v112
	v_cndmask_b32_e32 v114, v112, v113, vcc
	v_add_u32_e32 v112, 16, v152
	v_pk_mul_f32 v[104:105], v[104:105], v[114:115] op_sel_hi:[1,0]
	v_ashrrev_i32_e32 v113, 31, v112
	v_pk_mul_f32 v[108:109], v[108:109], v[114:115] op_sel_hi:[1,0]
	v_pk_mul_f32 v[106:107], v[106:107], v[114:115] op_sel_hi:[1,0]
	v_max_f32_e32 v104, 0, v104
	v_lshlrev_b64 v[112:113], 13, v[112:113]
	v_pk_mul_f32 v[110:111], v[110:111], v[114:115] op_sel_hi:[1,0]
	v_mul_f32_e32 v115, v104, v104
	v_max_f32_e32 v104, 0, v109
	v_max_f32_e32 v105, 0, v105
	v_max_f32_e32 v106, 0, v106
	v_lshl_add_u64 v[112:113], s[92:93], 0, v[112:113]
	v_max_f32_e32 v108, 0, v108
	v_mul_f32_e32 v104, v104, v104
	v_mul_f32_e32 v109, v105, v105
	v_max_f32_e32 v105, 0, v110
	v_mul_f32_e32 v110, v106, v106
	v_max_f32_e32 v106, 0, v111
	v_max_f32_e32 v107, 0, v107
	v_pk_mul_f32 v[98:99], v[98:99], v[114:115] op_sel_hi:[1,0]
	v_pk_mul_f32 v[96:97], v[96:97], v[114:115] op_sel_hi:[1,0]
	v_lshl_add_u64 v[112:113], v[112:113], 0, v[154:155]
	v_mul_f32_e32 v108, v108, v108
	v_mul_f32_e32 v105, v105, v105
	v_mul_f32_e32 v106, v106, v106
	v_mul_f32_e32 v107, v107, v107
	v_cvt_pk_bf16_f32 v104, v108, v104
	v_pk_mul_f32 v[102:103], v[102:103], v[114:115] op_sel_hi:[1,0]
	v_pk_mul_f32 v[100:101], v[100:101], v[114:115] op_sel_hi:[1,0]
	v_max_f32_e32 v96, 0, v96
	v_max_f32_e32 v97, 0, v97
	v_max_f32_e32 v98, 0, v98
	v_cvt_pk_bf16_f32 v105, v105, v106
	v_cvt_pk_bf16_f32 v106, v115, v109
	v_cvt_pk_bf16_f32 v107, v110, v107
	global_store_dwordx4 v[112:113], v[104:107], off
	v_max_f32_e32 v99, 0, v99
	v_max_f32_e32 v100, 0, v100
	v_mul_f32_e32 v104, v96, v96
	v_max_f32_e32 v96, 0, v101
	v_mul_f32_e32 v101, v97, v97
	v_max_f32_e32 v97, 0, v102
	v_mul_f32_e32 v102, v98, v98
	v_max_f32_e32 v98, 0, v103
	v_mul_f32_e32 v96, v96, v96
	v_mul_f32_e32 v97, v97, v97
	v_mul_f32_e32 v98, v98, v98
	v_mul_f32_e32 v99, v99, v99
	v_mul_f32_e32 v100, v100, v100
	v_cvt_pk_bf16_f32 v96, v100, v96
	v_cvt_pk_bf16_f32 v97, v97, v98
	v_cvt_pk_bf16_f32 v98, v104, v101
	v_cvt_pk_bf16_f32 v99, v102, v99
	global_store_dwordx4 v[112:113], v[96:99], off offset:256
	s_nop 1
	v_mov_b32_e32 v96, v230
	s_nop 0
	v_mov_b32_e32 v98, v231
	v_mov_b32_e32 v97, v232
	v_mov_b32_e32 v99, v233
	v_pk_add_f32 v[96:97], v[96:97], v[98:99]
	s_nop 0
	v_add_f32_e32 v96, v96, v97
	v_fmamk_f32 v96, v96, 0x3a800000, v158
	v_cmp_gt_f32_e32 vcc, s67, v96
	v_mul_f32_e32 v97, 0x4b800000, v96
	s_nop 0
	v_cndmask_b32_e32 v96, v96, v97, vcc
	v_rsq_f32_e32 v96, v96
	s_nop 0
	v_mul_f32_e32 v97, 0x45800000, v96
	v_cndmask_b32_e32 v98, v96, v97, vcc
	v_add_u32_e32 v96, 32, v152
	v_pk_mul_f32 v[88:89], v[88:89], v[98:99] op_sel_hi:[1,0]
	v_ashrrev_i32_e32 v97, 31, v96
	v_pk_mul_f32 v[92:93], v[92:93], v[98:99] op_sel_hi:[1,0]
	v_pk_mul_f32 v[90:91], v[90:91], v[98:99] op_sel_hi:[1,0]
	v_max_f32_e32 v88, 0, v88
	v_lshlrev_b64 v[96:97], 13, v[96:97]
	v_pk_mul_f32 v[94:95], v[94:95], v[98:99] op_sel_hi:[1,0]
	v_mul_f32_e32 v99, v88, v88
	v_max_f32_e32 v88, 0, v93
	v_max_f32_e32 v89, 0, v89
	v_max_f32_e32 v90, 0, v90
	v_lshl_add_u64 v[96:97], s[92:93], 0, v[96:97]
	v_max_f32_e32 v92, 0, v92
	v_mul_f32_e32 v88, v88, v88
	v_mul_f32_e32 v93, v89, v89
	v_max_f32_e32 v89, 0, v94
	v_mul_f32_e32 v94, v90, v90
	v_max_f32_e32 v90, 0, v95
	v_max_f32_e32 v91, 0, v91
	v_pk_mul_f32 v[82:83], v[82:83], v[98:99] op_sel_hi:[1,0]
	v_pk_mul_f32 v[80:81], v[80:81], v[98:99] op_sel_hi:[1,0]
	v_lshl_add_u64 v[96:97], v[96:97], 0, v[154:155]
	v_mul_f32_e32 v92, v92, v92
	v_mul_f32_e32 v89, v89, v89
	v_mul_f32_e32 v90, v90, v90
	v_mul_f32_e32 v91, v91, v91
	v_cvt_pk_bf16_f32 v88, v92, v88
	v_pk_mul_f32 v[86:87], v[86:87], v[98:99] op_sel_hi:[1,0]
	v_pk_mul_f32 v[84:85], v[84:85], v[98:99] op_sel_hi:[1,0]
	v_max_f32_e32 v80, 0, v80
	v_max_f32_e32 v81, 0, v81
	v_max_f32_e32 v82, 0, v82
	v_cvt_pk_bf16_f32 v89, v89, v90
	v_cvt_pk_bf16_f32 v90, v99, v93
	v_cvt_pk_bf16_f32 v91, v94, v91
	global_store_dwordx4 v[96:97], v[88:91], off
	v_max_f32_e32 v83, 0, v83
	v_max_f32_e32 v84, 0, v84
	v_mul_f32_e32 v88, v80, v80
	v_max_f32_e32 v80, 0, v85
	v_mul_f32_e32 v85, v81, v81
	v_max_f32_e32 v81, 0, v86
	v_mul_f32_e32 v86, v82, v82
	v_max_f32_e32 v82, 0, v87
	v_mul_f32_e32 v80, v80, v80
	v_mul_f32_e32 v81, v81, v81
	v_mul_f32_e32 v82, v82, v82
	v_mul_f32_e32 v83, v83, v83
	v_mul_f32_e32 v84, v84, v84
	v_cvt_pk_bf16_f32 v80, v84, v80
	v_cvt_pk_bf16_f32 v81, v81, v82
	v_cvt_pk_bf16_f32 v82, v88, v85
	v_cvt_pk_bf16_f32 v83, v86, v83
	global_store_dwordx4 v[96:97], v[80:83], off offset:256
	s_nop 1
	v_mov_b32_e32 v80, v234
	s_nop 0
	v_mov_b32_e32 v82, v235
	v_mov_b32_e32 v81, v236
	v_mov_b32_e32 v83, v237
	v_pk_add_f32 v[80:81], v[80:81], v[82:83]
	s_nop 0
	v_add_f32_e32 v80, v80, v81
	v_fmamk_f32 v80, v80, 0x3a800000, v158
	v_cmp_gt_f32_e32 vcc, s67, v80
	v_mul_f32_e32 v81, 0x4b800000, v80
	s_nop 0
	v_cndmask_b32_e32 v80, v80, v81, vcc
	v_rsq_f32_e32 v80, v80
	s_nop 0
	v_mul_f32_e32 v81, 0x45800000, v80
	v_cndmask_b32_e32 v82, v80, v81, vcc
	v_add_u32_e32 v80, 48, v152
	v_pk_mul_f32 v[72:73], v[72:73], v[82:83] op_sel_hi:[1,0]
	v_ashrrev_i32_e32 v81, 31, v80
	v_pk_mul_f32 v[76:77], v[76:77], v[82:83] op_sel_hi:[1,0]
	v_pk_mul_f32 v[74:75], v[74:75], v[82:83] op_sel_hi:[1,0]
	v_max_f32_e32 v72, 0, v72
	v_lshlrev_b64 v[80:81], 13, v[80:81]
	v_pk_mul_f32 v[78:79], v[78:79], v[82:83] op_sel_hi:[1,0]
	v_mul_f32_e32 v83, v72, v72
	v_max_f32_e32 v72, 0, v77
	v_max_f32_e32 v73, 0, v73
	v_max_f32_e32 v74, 0, v74
	v_lshl_add_u64 v[80:81], s[92:93], 0, v[80:81]
	v_max_f32_e32 v76, 0, v76
	v_mul_f32_e32 v72, v72, v72
	v_mul_f32_e32 v77, v73, v73
	v_max_f32_e32 v73, 0, v78
	v_mul_f32_e32 v78, v74, v74
	v_max_f32_e32 v74, 0, v79
	v_max_f32_e32 v75, 0, v75
	v_pk_mul_f32 v[66:67], v[66:67], v[82:83] op_sel_hi:[1,0]
	v_pk_mul_f32 v[64:65], v[64:65], v[82:83] op_sel_hi:[1,0]
	v_lshl_add_u64 v[80:81], v[80:81], 0, v[154:155]
	v_mul_f32_e32 v76, v76, v76
	v_mul_f32_e32 v73, v73, v73
	v_mul_f32_e32 v74, v74, v74
	v_mul_f32_e32 v75, v75, v75
	v_cvt_pk_bf16_f32 v72, v76, v72
	v_pk_mul_f32 v[70:71], v[70:71], v[82:83] op_sel_hi:[1,0]
	v_pk_mul_f32 v[68:69], v[68:69], v[82:83] op_sel_hi:[1,0]
	v_max_f32_e32 v64, 0, v64
	v_max_f32_e32 v65, 0, v65
	v_max_f32_e32 v66, 0, v66
	v_cvt_pk_bf16_f32 v73, v73, v74
	v_cvt_pk_bf16_f32 v74, v83, v77
	v_cvt_pk_bf16_f32 v75, v78, v75
	global_store_dwordx4 v[80:81], v[72:75], off
	v_max_f32_e32 v67, 0, v67
	v_max_f32_e32 v68, 0, v68
	v_mul_f32_e32 v72, v64, v64
	v_max_f32_e32 v64, 0, v69
	v_mul_f32_e32 v69, v65, v65
	v_max_f32_e32 v65, 0, v70
	v_mul_f32_e32 v70, v66, v66
	v_max_f32_e32 v66, 0, v71
	v_mul_f32_e32 v64, v64, v64
	v_mul_f32_e32 v65, v65, v65
	v_mul_f32_e32 v66, v66, v66
	v_mul_f32_e32 v67, v67, v67
	v_mul_f32_e32 v68, v68, v68
	v_cvt_pk_bf16_f32 v64, v68, v64
	v_cvt_pk_bf16_f32 v65, v65, v66
	v_cvt_pk_bf16_f32 v66, v72, v69
	v_cvt_pk_bf16_f32 v67, v70, v67
	global_store_dwordx4 v[80:81], v[64:67], off offset:256
	s_nop 1
	v_mov_b32_e32 v64, v238
	s_nop 0
	v_mov_b32_e32 v66, v239
	v_mov_b32_e32 v65, v240
	v_mov_b32_e32 v67, v241
	v_pk_add_f32 v[64:65], v[64:65], v[66:67]
	s_nop 0
	v_add_f32_e32 v64, v64, v65
	v_fmamk_f32 v64, v64, 0x3a800000, v158
	v_cmp_gt_f32_e32 vcc, s67, v64
	v_mul_f32_e32 v65, 0x4b800000, v64
	s_nop 0
	v_cndmask_b32_e32 v64, v64, v65, vcc
	v_rsq_f32_e32 v64, v64
	s_nop 0
	v_mul_f32_e32 v65, 0x45800000, v64
	v_cndmask_b32_e32 v66, v64, v65, vcc
	v_add_u32_e32 v64, 0x80, v152
	v_pk_mul_f32 v[56:57], v[56:57], v[66:67] op_sel_hi:[1,0]
	v_ashrrev_i32_e32 v65, 31, v64
	v_pk_mul_f32 v[60:61], v[60:61], v[66:67] op_sel_hi:[1,0]
	v_pk_mul_f32 v[58:59], v[58:59], v[66:67] op_sel_hi:[1,0]
	v_max_f32_e32 v56, 0, v56
	v_lshlrev_b64 v[64:65], 13, v[64:65]
	v_pk_mul_f32 v[62:63], v[62:63], v[66:67] op_sel_hi:[1,0]
	v_mul_f32_e32 v67, v56, v56
	v_max_f32_e32 v56, 0, v61
	v_max_f32_e32 v57, 0, v57
	v_max_f32_e32 v58, 0, v58
	v_lshl_add_u64 v[64:65], s[92:93], 0, v[64:65]
	v_max_f32_e32 v60, 0, v60
	v_mul_f32_e32 v56, v56, v56
	v_mul_f32_e32 v61, v57, v57
	v_max_f32_e32 v57, 0, v62
	v_mul_f32_e32 v62, v58, v58
	v_max_f32_e32 v58, 0, v63
	v_max_f32_e32 v59, 0, v59
	v_pk_mul_f32 v[50:51], v[50:51], v[66:67] op_sel_hi:[1,0]
	v_pk_mul_f32 v[48:49], v[48:49], v[66:67] op_sel_hi:[1,0]
	v_lshl_add_u64 v[64:65], v[64:65], 0, v[154:155]
	v_mul_f32_e32 v60, v60, v60
	v_mul_f32_e32 v57, v57, v57
	v_mul_f32_e32 v58, v58, v58
	v_mul_f32_e32 v59, v59, v59
	v_cvt_pk_bf16_f32 v56, v60, v56
	v_pk_mul_f32 v[54:55], v[54:55], v[66:67] op_sel_hi:[1,0]
	v_pk_mul_f32 v[52:53], v[52:53], v[66:67] op_sel_hi:[1,0]
	v_max_f32_e32 v48, 0, v48
	v_max_f32_e32 v49, 0, v49
	v_max_f32_e32 v50, 0, v50
	v_cvt_pk_bf16_f32 v57, v57, v58
	v_cvt_pk_bf16_f32 v58, v67, v61
	v_cvt_pk_bf16_f32 v59, v62, v59
	global_store_dwordx4 v[64:65], v[56:59], off
	v_max_f32_e32 v51, 0, v51
	v_max_f32_e32 v52, 0, v52
	v_mul_f32_e32 v56, v48, v48
	v_max_f32_e32 v48, 0, v53
	v_mul_f32_e32 v53, v49, v49
	v_max_f32_e32 v49, 0, v54
	v_mul_f32_e32 v54, v50, v50
	v_max_f32_e32 v50, 0, v55
	v_mul_f32_e32 v48, v48, v48
	v_mul_f32_e32 v49, v49, v49
	v_mul_f32_e32 v50, v50, v50
	v_mul_f32_e32 v51, v51, v51
	v_mul_f32_e32 v52, v52, v52
	v_cvt_pk_bf16_f32 v48, v52, v48
	v_cvt_pk_bf16_f32 v49, v49, v50
	v_cvt_pk_bf16_f32 v50, v56, v53
	v_cvt_pk_bf16_f32 v51, v54, v51
	global_store_dwordx4 v[64:65], v[48:51], off offset:256
	s_nop 1
	v_mov_b32_e32 v48, v242
	s_nop 0
	v_mov_b32_e32 v50, v243
	v_mov_b32_e32 v49, v244
	v_mov_b32_e32 v51, v245
	v_pk_add_f32 v[48:49], v[48:49], v[50:51]
	s_nop 0
	v_add_f32_e32 v48, v48, v49
	v_fmamk_f32 v48, v48, 0x3a800000, v158
	v_cmp_gt_f32_e32 vcc, s67, v48
	v_mul_f32_e32 v49, 0x4b800000, v48
	s_nop 0
	v_cndmask_b32_e32 v48, v48, v49, vcc
	v_rsq_f32_e32 v48, v48
	s_nop 0
	v_mul_f32_e32 v49, 0x45800000, v48
	v_cndmask_b32_e32 v50, v48, v49, vcc
	v_add_u32_e32 v48, 0x90, v152
	v_pk_mul_f32 v[40:41], v[40:41], v[50:51] op_sel_hi:[1,0]
	v_ashrrev_i32_e32 v49, 31, v48
	v_pk_mul_f32 v[44:45], v[44:45], v[50:51] op_sel_hi:[1,0]
	v_pk_mul_f32 v[42:43], v[42:43], v[50:51] op_sel_hi:[1,0]
	v_max_f32_e32 v40, 0, v40
	v_lshlrev_b64 v[48:49], 13, v[48:49]
	v_pk_mul_f32 v[46:47], v[46:47], v[50:51] op_sel_hi:[1,0]
	v_mul_f32_e32 v51, v40, v40
	v_max_f32_e32 v40, 0, v45
	v_max_f32_e32 v41, 0, v41
	v_max_f32_e32 v42, 0, v42
	v_lshl_add_u64 v[48:49], s[92:93], 0, v[48:49]
	v_max_f32_e32 v44, 0, v44
	v_mul_f32_e32 v40, v40, v40
	v_mul_f32_e32 v45, v41, v41
	v_max_f32_e32 v41, 0, v46
	v_mul_f32_e32 v46, v42, v42
	v_max_f32_e32 v42, 0, v47
	v_max_f32_e32 v43, 0, v43
	v_pk_mul_f32 v[34:35], v[34:35], v[50:51] op_sel_hi:[1,0]
	v_pk_mul_f32 v[32:33], v[32:33], v[50:51] op_sel_hi:[1,0]
	v_lshl_add_u64 v[48:49], v[48:49], 0, v[154:155]
	v_mul_f32_e32 v44, v44, v44
	v_mul_f32_e32 v41, v41, v41
	v_mul_f32_e32 v42, v42, v42
	v_mul_f32_e32 v43, v43, v43
	v_cvt_pk_bf16_f32 v40, v44, v40
	v_pk_mul_f32 v[38:39], v[38:39], v[50:51] op_sel_hi:[1,0]
	v_pk_mul_f32 v[36:37], v[36:37], v[50:51] op_sel_hi:[1,0]
	v_max_f32_e32 v32, 0, v32
	v_max_f32_e32 v33, 0, v33
	v_max_f32_e32 v34, 0, v34
	v_cvt_pk_bf16_f32 v41, v41, v42
	v_cvt_pk_bf16_f32 v42, v51, v45
	v_cvt_pk_bf16_f32 v43, v46, v43
	global_store_dwordx4 v[48:49], v[40:43], off
	v_max_f32_e32 v35, 0, v35
	v_max_f32_e32 v36, 0, v36
	v_mul_f32_e32 v40, v32, v32
	v_max_f32_e32 v32, 0, v37
	v_mul_f32_e32 v37, v33, v33
	v_max_f32_e32 v33, 0, v38
	v_mul_f32_e32 v38, v34, v34
	v_max_f32_e32 v34, 0, v39
	v_mul_f32_e32 v32, v32, v32
	v_mul_f32_e32 v33, v33, v33
	v_mul_f32_e32 v34, v34, v34
	v_mul_f32_e32 v35, v35, v35
	v_mul_f32_e32 v36, v36, v36
	v_cvt_pk_bf16_f32 v32, v36, v32
	v_cvt_pk_bf16_f32 v33, v33, v34
	v_cvt_pk_bf16_f32 v34, v40, v37
	v_cvt_pk_bf16_f32 v35, v38, v35
	global_store_dwordx4 v[48:49], v[32:35], off offset:256
	s_nop 1
	v_mov_b32_e32 v32, v246
	s_nop 0
	v_mov_b32_e32 v34, v247
	v_mov_b32_e32 v33, v248
	v_mov_b32_e32 v35, v249
	v_pk_add_f32 v[32:33], v[32:33], v[34:35]
	s_nop 0
	v_add_f32_e32 v32, v32, v33
	v_fmamk_f32 v32, v32, 0x3a800000, v158
	v_cmp_gt_f32_e32 vcc, s67, v32
	v_mul_f32_e32 v33, 0x4b800000, v32
	s_nop 0
	v_cndmask_b32_e32 v32, v32, v33, vcc
	v_rsq_f32_e32 v32, v32
	s_nop 0
	v_mul_f32_e32 v33, 0x45800000, v32
	v_cndmask_b32_e32 v34, v32, v33, vcc
	v_add_u32_e32 v32, 0xa0, v152
	v_pk_mul_f32 v[24:25], v[24:25], v[34:35] op_sel_hi:[1,0]
	v_ashrrev_i32_e32 v33, 31, v32
	v_pk_mul_f32 v[28:29], v[28:29], v[34:35] op_sel_hi:[1,0]
	v_pk_mul_f32 v[26:27], v[26:27], v[34:35] op_sel_hi:[1,0]
	v_max_f32_e32 v24, 0, v24
	v_lshlrev_b64 v[32:33], 13, v[32:33]
	v_pk_mul_f32 v[30:31], v[30:31], v[34:35] op_sel_hi:[1,0]
	v_mul_f32_e32 v35, v24, v24
	v_max_f32_e32 v24, 0, v29
	v_max_f32_e32 v25, 0, v25
	v_max_f32_e32 v26, 0, v26
	v_lshl_add_u64 v[32:33], s[92:93], 0, v[32:33]
	v_max_f32_e32 v28, 0, v28
	v_mul_f32_e32 v24, v24, v24
	v_mul_f32_e32 v29, v25, v25
	v_max_f32_e32 v25, 0, v30
	v_mul_f32_e32 v30, v26, v26
	v_max_f32_e32 v26, 0, v31
	v_max_f32_e32 v27, 0, v27
	v_pk_mul_f32 v[18:19], v[18:19], v[34:35] op_sel_hi:[1,0]
	v_pk_mul_f32 v[16:17], v[16:17], v[34:35] op_sel_hi:[1,0]
	v_lshl_add_u64 v[32:33], v[32:33], 0, v[154:155]
	v_mul_f32_e32 v28, v28, v28
	v_mul_f32_e32 v25, v25, v25
	v_mul_f32_e32 v26, v26, v26
	v_mul_f32_e32 v27, v27, v27
	v_cvt_pk_bf16_f32 v24, v28, v24
	v_pk_mul_f32 v[22:23], v[22:23], v[34:35] op_sel_hi:[1,0]
	v_pk_mul_f32 v[20:21], v[20:21], v[34:35] op_sel_hi:[1,0]
	v_max_f32_e32 v16, 0, v16
	v_max_f32_e32 v17, 0, v17
	v_max_f32_e32 v18, 0, v18
	v_cvt_pk_bf16_f32 v25, v25, v26
	v_cvt_pk_bf16_f32 v26, v35, v29
	v_cvt_pk_bf16_f32 v27, v30, v27
	global_store_dwordx4 v[32:33], v[24:27], off
	v_max_f32_e32 v19, 0, v19
	v_max_f32_e32 v20, 0, v20
	v_mul_f32_e32 v24, v16, v16
	v_max_f32_e32 v16, 0, v21
	v_mul_f32_e32 v21, v17, v17
	v_max_f32_e32 v17, 0, v22
	v_mul_f32_e32 v22, v18, v18
	v_max_f32_e32 v18, 0, v23
	v_mul_f32_e32 v16, v16, v16
	v_mul_f32_e32 v17, v17, v17
	v_mul_f32_e32 v18, v18, v18
	v_mul_f32_e32 v19, v19, v19
	v_mul_f32_e32 v20, v20, v20
	v_cvt_pk_bf16_f32 v16, v20, v16
	v_cvt_pk_bf16_f32 v17, v17, v18
	v_cvt_pk_bf16_f32 v18, v24, v21
	v_cvt_pk_bf16_f32 v19, v22, v19
	global_store_dwordx4 v[32:33], v[16:19], off offset:256
	s_nop 1
	v_mov_b32_e32 v16, v250
	s_nop 0
	v_mov_b32_e32 v18, v251
	v_mov_b32_e32 v17, v252
	v_mov_b32_e32 v19, v253
	v_pk_add_f32 v[16:17], v[16:17], v[18:19]
	s_nop 0
	v_add_f32_e32 v16, v16, v17
	v_fmamk_f32 v16, v16, 0x3a800000, v158
	v_cmp_gt_f32_e32 vcc, s67, v16
	v_mul_f32_e32 v17, 0x4b800000, v16
	v_add_u32_e32 v18, 0xb0, v152
	v_cndmask_b32_e32 v16, v16, v17, vcc
	v_rsq_f32_e32 v16, v16
	v_ashrrev_i32_e32 v19, 31, v18
	v_lshlrev_b64 v[18:19], 13, v[18:19]
	v_lshl_add_u64 v[18:19], s[92:93], 0, v[18:19]
	v_mul_f32_e32 v17, 0x45800000, v16
	v_cndmask_b32_e32 v16, v16, v17, vcc
	v_pk_mul_f32 v[8:9], v[8:9], v[16:17] op_sel_hi:[1,0]
	v_pk_mul_f32 v[12:13], v[12:13], v[16:17] op_sel_hi:[1,0]
	v_pk_mul_f32 v[10:11], v[10:11], v[16:17] op_sel_hi:[1,0]
	v_max_f32_e32 v8, 0, v8
	v_pk_mul_f32 v[14:15], v[14:15], v[16:17] op_sel_hi:[1,0]
	v_mul_f32_e32 v17, v8, v8
	v_max_f32_e32 v8, 0, v13
	v_max_f32_e32 v9, 0, v9
	v_max_f32_e32 v10, 0, v10
	v_max_f32_e32 v12, 0, v12
	v_mul_f32_e32 v8, v8, v8
	v_mul_f32_e32 v13, v9, v9
	v_max_f32_e32 v9, 0, v14
	v_mul_f32_e32 v14, v10, v10
	v_max_f32_e32 v10, 0, v15
	v_max_f32_e32 v11, 0, v11
	v_pk_mul_f32 v[2:3], v[2:3], v[16:17] op_sel_hi:[1,0]
	v_pk_mul_f32 v[0:1], v[0:1], v[16:17] op_sel_hi:[1,0]
	v_lshl_add_u64 v[18:19], v[18:19], 0, v[154:155]
	v_mul_f32_e32 v12, v12, v12
	v_mul_f32_e32 v9, v9, v9
	v_mul_f32_e32 v10, v10, v10
	v_mul_f32_e32 v11, v11, v11
	v_cvt_pk_bf16_f32 v8, v12, v8
	v_pk_mul_f32 v[6:7], v[6:7], v[16:17] op_sel_hi:[1,0]
	v_pk_mul_f32 v[4:5], v[4:5], v[16:17] op_sel_hi:[1,0]
	v_max_f32_e32 v0, 0, v0
	v_max_f32_e32 v1, 0, v1
	v_max_f32_e32 v2, 0, v2
	v_cvt_pk_bf16_f32 v9, v9, v10
	v_cvt_pk_bf16_f32 v10, v17, v13
	v_cvt_pk_bf16_f32 v11, v14, v11
	global_store_dwordx4 v[18:19], v[8:11], off
	v_max_f32_e32 v3, 0, v3
	v_max_f32_e32 v4, 0, v4
	v_mul_f32_e32 v8, v0, v0
	v_max_f32_e32 v0, 0, v5
	v_mul_f32_e32 v5, v1, v1
	v_max_f32_e32 v1, 0, v6
	v_mul_f32_e32 v6, v2, v2
	v_max_f32_e32 v2, 0, v7
	v_mul_f32_e32 v0, v0, v0
	v_mul_f32_e32 v1, v1, v1
	v_mul_f32_e32 v2, v2, v2
	v_mul_f32_e32 v3, v3, v3
	s_and_b64 vcc, exec, s[0:1]
	v_mul_f32_e32 v4, v4, v4
	v_cvt_pk_bf16_f32 v0, v4, v0
	v_cvt_pk_bf16_f32 v1, v1, v2
	v_cvt_pk_bf16_f32 v2, v8, v5
	v_cvt_pk_bf16_f32 v3, v6, v3
	global_store_dwordx4 v[18:19], v[0:3], off offset:256
	s_cbranch_vccz .LBB0_434
	s_waitcnt vmcnt(0)
	s_cmpk_gt_u32 s49, 0xff
	s_cbranch_scc1 .LBB0_445
	s_barrier

.LBB0_495:
	ds_read_b128 v[144:147], v156
	ds_read_b128 v[148:151], v156 offset:1024
	ds_read_b128 v[160:163], v156 offset:2048
	ds_read_b128 v[164:167], v156 offset:3072
	s_add_u32 s22, s38, 0xfffc0080
	s_addc_u32 s23, s39, -1
	s_cmp_eq_u32 s44, 12
	s_cselect_b32 s43, s35, s23
	s_cselect_b32 s42, s34, s22
	s_cselect_b32 s41, s37, s19
	s_cselect_b32 s40, s36, s18
	v_lshl_add_u64 v[152:153], s[38:39], 0, v[138:139]
	s_add_i32 m0, s50, 0xc000
	ds_read_b128 v[168:171], v157
	ds_read_b128 v[172:175], v157 offset:1024
	ds_read_b128 v[176:179], v157 offset:2048
	ds_read_b128 v[180:183], v157 offset:3072
	ds_read_b128 v[184:187], v157 offset:4096
	ds_read_b128 v[188:191], v157 offset:5120
	ds_read_b128 v[192:195], v157 offset:6144
	ds_read_b128 v[200:203], v157 offset:7168
	global_load_lds_dwordx4 v[152:153], off
	v_lshl_add_u64 v[152:153], s[38:39], 0, v[140:141]
	s_add_i32 m0, s50, 0xe000
	s_nop 0
	global_load_lds_dwordx4 v[152:153], off
	s_waitcnt lgkmcnt(8)
	s_barrier
	s_waitcnt lgkmcnt(0)
	s_setprio 1
	s_waitcnt lgkmcnt(0)
	v_mfma_f32_16x16x32_bf16 v[124:127], v[144:147], v[168:171], v[124:127]
	v_mfma_f32_16x16x32_bf16 v[120:123], v[160:163], v[168:171], v[120:123]
	v_mfma_f32_16x16x32_bf16 v[108:111], v[144:147], v[176:179], v[108:111]
	v_mfma_f32_16x16x32_bf16 v[104:107], v[160:163], v[176:179], v[104:107]
	v_mfma_f32_16x16x32_bf16 v[92:95], v[144:147], v[184:187], v[92:95]
	v_mfma_f32_16x16x32_bf16 v[88:91], v[160:163], v[184:187], v[88:91]
	v_mfma_f32_16x16x32_bf16 v[76:79], v[144:147], v[192:195], v[76:79]
	v_mfma_f32_16x16x32_bf16 v[72:75], v[160:163], v[192:195], v[72:75]
	v_mfma_f32_16x16x32_bf16 v[124:127], v[148:151], v[172:175], v[124:127]
	v_mfma_f32_16x16x32_bf16 v[120:123], v[164:167], v[172:175], v[120:123]
	v_mfma_f32_16x16x32_bf16 v[108:111], v[148:151], v[180:183], v[108:111]
	v_mfma_f32_16x16x32_bf16 v[104:107], v[164:167], v[180:183], v[104:107]
	v_mfma_f32_16x16x32_bf16 v[92:95], v[148:151], v[188:191], v[92:95]
	v_mfma_f32_16x16x32_bf16 v[88:91], v[164:167], v[188:191], v[88:91]
	v_mfma_f32_16x16x32_bf16 v[76:79], v[148:151], v[200:203], v[76:79]
	v_mfma_f32_16x16x32_bf16 v[72:75], v[164:167], v[200:203], v[72:75]
	s_setprio 0
	s_barrier
	s_add_i32 s22, s64, s48
	v_lshl_add_u64 v[152:153], s[40:41], 0, v[132:133]
	s_mov_b32 m0, s22
	ds_read_b128 v[204:207], v158
	ds_read_b128 v[208:211], v158 offset:1024
	ds_read_b128 v[212:215], v158 offset:2048
	ds_read_b128 v[216:219], v158 offset:3072
	global_load_lds_dwordx4 v[152:153], off
	v_lshl_add_u64 v[220:221], s[40:41], 0, v[128:129]
	s_add_i32 m0, s22, 0x2000
	s_nop 0
	global_load_lds_dwordx4 v[220:221], off
	s_barrier
	s_waitcnt lgkmcnt(0)
	s_setprio 1
	s_waitcnt lgkmcnt(0)
	v_mfma_f32_16x16x32_bf16 v[116:119], v[204:207], v[168:171], v[116:119]
	v_mfma_f32_16x16x32_bf16 v[112:115], v[212:215], v[168:171], v[112:115]
	v_mfma_f32_16x16x32_bf16 v[100:103], v[204:207], v[176:179], v[100:103]
	v_mfma_f32_16x16x32_bf16 v[96:99], v[212:215], v[176:179], v[96:99]
	v_mfma_f32_16x16x32_bf16 v[84:87], v[204:207], v[184:187], v[84:87]
	v_mfma_f32_16x16x32_bf16 v[80:83], v[212:215], v[184:187], v[80:83]
	v_mfma_f32_16x16x32_bf16 v[68:71], v[204:207], v[192:195], v[68:71]
	v_mfma_f32_16x16x32_bf16 v[64:67], v[212:215], v[192:195], v[64:67]
	v_mfma_f32_16x16x32_bf16 v[116:119], v[208:211], v[172:175], v[116:119]
	v_mfma_f32_16x16x32_bf16 v[112:115], v[216:219], v[172:175], v[112:115]
	v_mfma_f32_16x16x32_bf16 v[100:103], v[208:211], v[180:183], v[100:103]
	v_mfma_f32_16x16x32_bf16 v[96:99], v[216:219], v[180:183], v[96:99]
	v_mfma_f32_16x16x32_bf16 v[84:87], v[208:211], v[188:191], v[84:87]
	v_mfma_f32_16x16x32_bf16 v[80:83], v[216:219], v[188:191], v[80:83]
	v_mfma_f32_16x16x32_bf16 v[68:71], v[208:211], v[200:203], v[68:71]
	v_mfma_f32_16x16x32_bf16 v[64:67], v[216:219], v[200:203], v[64:67]
	s_setprio 0
	s_mov_b32 m0, s50
	v_lshl_add_u64 v[222:223], s[42:43], 0, v[134:135]
	s_barrier
	ds_read_b128 v[168:171], v157 offset:16384
	ds_read_b128 v[172:175], v157 offset:17408
	ds_read_b128 v[176:179], v157 offset:18432
	ds_read_b128 v[180:183], v157 offset:19456
	ds_read_b128 v[184:187], v157 offset:20480
	ds_read_b128 v[188:191], v157 offset:21504
	ds_read_b128 v[192:195], v157 offset:22528
	ds_read_b128 v[200:203], v157 offset:23552
	global_load_lds_dwordx4 v[222:223], off
	v_lshl_add_u64 v[224:225], s[42:43], 0, v[130:131]
	s_mov_b32 m0, s51
	s_nop 0
	global_load_lds_dwordx4 v[224:225], off
	s_barrier
	s_waitcnt lgkmcnt(0)
	s_setprio 1
	s_waitcnt lgkmcnt(0)
	v_mfma_f32_16x16x32_bf16 v[60:63], v[144:147], v[168:171], v[60:63]
	v_mfma_f32_16x16x32_bf16 v[56:59], v[160:163], v[168:171], v[56:59]
	v_mfma_f32_16x16x32_bf16 v[44:47], v[144:147], v[176:179], v[44:47]
	v_mfma_f32_16x16x32_bf16 v[40:43], v[160:163], v[176:179], v[40:43]
	v_mfma_f32_16x16x32_bf16 v[28:31], v[144:147], v[184:187], v[28:31]
	v_mfma_f32_16x16x32_bf16 v[24:27], v[160:163], v[184:187], v[24:27]
	v_mfma_f32_16x16x32_bf16 v[12:15], v[144:147], v[192:195], v[12:15]
	v_mfma_f32_16x16x32_bf16 v[8:11], v[160:163], v[192:195], v[8:11]
	v_mfma_f32_16x16x32_bf16 v[60:63], v[148:151], v[172:175], v[60:63]
	v_mfma_f32_16x16x32_bf16 v[56:59], v[164:167], v[172:175], v[56:59]
	v_mfma_f32_16x16x32_bf16 v[44:47], v[148:151], v[180:183], v[44:47]
	v_mfma_f32_16x16x32_bf16 v[40:43], v[164:167], v[180:183], v[40:43]
	v_mfma_f32_16x16x32_bf16 v[28:31], v[148:151], v[188:191], v[28:31]
	v_mfma_f32_16x16x32_bf16 v[24:27], v[164:167], v[188:191], v[24:27]
	v_mfma_f32_16x16x32_bf16 v[12:15], v[148:151], v[200:203], v[12:15]
	v_mfma_f32_16x16x32_bf16 v[8:11], v[164:167], v[200:203], v[8:11]
	s_setprio 0
	s_barrier
	s_add_u32 s22, s40, 0x40000
	s_addc_u32 s23, s41, 0
	s_add_i32 s45, s65, s48
	v_lshl_add_u64 v[144:145], s[22:23], 0, v[132:133]
	s_mov_b32 m0, s45
	s_nop 0
	global_load_lds_dwordx4 v[144:145], off
	v_lshl_add_u64 v[144:145], s[22:23], 0, v[128:129]
	s_add_i32 m0, s45, 0x2000
	s_nop 0
	global_load_lds_dwordx4 v[144:145], off
	s_waitcnt vmcnt(6)
	s_barrier
	s_setprio 1
	v_mfma_f32_16x16x32_bf16 v[52:55], v[204:207], v[168:171], v[52:55]
	v_mfma_f32_16x16x32_bf16 v[48:51], v[212:215], v[168:171], v[48:51]
	v_mfma_f32_16x16x32_bf16 v[36:39], v[204:207], v[176:179], v[36:39]
	v_mfma_f32_16x16x32_bf16 v[32:35], v[212:215], v[176:179], v[32:35]
	v_mfma_f32_16x16x32_bf16 v[20:23], v[204:207], v[184:187], v[20:23]
	v_mfma_f32_16x16x32_bf16 v[16:19], v[212:215], v[184:187], v[16:19]
	v_mfma_f32_16x16x32_bf16 v[4:7], v[204:207], v[192:195], v[4:7]
	v_mfma_f32_16x16x32_bf16 v[0:3], v[212:215], v[192:195], v[0:3]
	v_mfma_f32_16x16x32_bf16 v[52:55], v[208:211], v[172:175], v[52:55]
	v_mfma_f32_16x16x32_bf16 v[48:51], v[216:219], v[172:175], v[48:51]
	v_mfma_f32_16x16x32_bf16 v[36:39], v[208:211], v[180:183], v[36:39]
	v_mfma_f32_16x16x32_bf16 v[32:35], v[216:219], v[180:183], v[32:35]
	v_mfma_f32_16x16x32_bf16 v[20:23], v[208:211], v[188:191], v[20:23]
	v_mfma_f32_16x16x32_bf16 v[16:19], v[216:219], v[188:191], v[16:19]
	v_mfma_f32_16x16x32_bf16 v[4:7], v[208:211], v[200:203], v[4:7]
	v_mfma_f32_16x16x32_bf16 v[0:3], v[216:219], v[200:203], v[0:3]
	s_setprio 0
	s_add_i32 s45, 0, 0x18000
	v_add_u32_e32 v164, s45, v155
	s_barrier
	ds_read_b128 v[144:147], v164
	ds_read_b128 v[148:151], v164 offset:1024
	ds_read_b128 v[160:163], v164 offset:2048
	ds_read_b128 v[164:167], v164 offset:3072
	s_add_u32 s22, s42, 0x40000
	s_addc_u32 s23, s43, 0
	s_mov_b32 m0, s52
	v_lshl_add_u64 v[204:205], s[22:23], 0, v[134:135]
	ds_read_b128 v[168:171], v157 offset:32768
	ds_read_b128 v[172:175], v157 offset:33792
	ds_read_b128 v[176:179], v157 offset:34816
	ds_read_b128 v[180:183], v157 offset:35840
	ds_read_b128 v[184:187], v157 offset:36864
	ds_read_b128 v[188:191], v157 offset:37888
	ds_read_b128 v[192:195], v157 offset:38912
	ds_read_b128 v[200:203], v157 offset:39936
	global_load_lds_dwordx4 v[204:205], off
	v_lshl_add_u64 v[204:205], s[22:23], 0, v[130:131]
	s_mov_b32 m0, s53
	s_nop 0
	global_load_lds_dwordx4 v[204:205], off
	s_waitcnt lgkmcnt(8)
	s_barrier
	s_waitcnt lgkmcnt(0)
	s_setprio 1
	s_waitcnt lgkmcnt(0)
	v_mfma_f32_16x16x32_bf16 v[124:127], v[144:147], v[168:171], v[124:127]
	v_mfma_f32_16x16x32_bf16 v[120:123], v[160:163], v[168:171], v[120:123]
	v_mfma_f32_16x16x32_bf16 v[108:111], v[144:147], v[176:179], v[108:111]
	v_mfma_f32_16x16x32_bf16 v[104:107], v[160:163], v[176:179], v[104:107]
	v_mfma_f32_16x16x32_bf16 v[92:95], v[144:147], v[184:187], v[92:95]
	v_mfma_f32_16x16x32_bf16 v[88:91], v[160:163], v[184:187], v[88:91]
	v_mfma_f32_16x16x32_bf16 v[76:79], v[144:147], v[192:195], v[76:79]
	v_mfma_f32_16x16x32_bf16 v[72:75], v[160:163], v[192:195], v[72:75]
	v_mfma_f32_16x16x32_bf16 v[124:127], v[148:151], v[172:175], v[124:127]
	v_mfma_f32_16x16x32_bf16 v[120:123], v[164:167], v[172:175], v[120:123]
	v_mfma_f32_16x16x32_bf16 v[108:111], v[148:151], v[180:183], v[108:111]
	v_mfma_f32_16x16x32_bf16 v[104:107], v[164:167], v[180:183], v[104:107]
	v_mfma_f32_16x16x32_bf16 v[92:95], v[148:151], v[188:191], v[92:95]
	v_mfma_f32_16x16x32_bf16 v[88:91], v[164:167], v[188:191], v[88:91]
	v_mfma_f32_16x16x32_bf16 v[76:79], v[148:151], v[200:203], v[76:79]
	v_mfma_f32_16x16x32_bf16 v[72:75], v[164:167], v[200:203], v[72:75]
	s_setprio 0
	s_barrier
	s_add_i32 s42, 0, 0x1c000
	s_add_i32 s22, s45, s48
	v_add_u32_e32 v216, s42, v155
	v_lshl_add_u64 v[152:153], v[152:153], 0, s[6:7]
	s_mov_b32 m0, s22
	ds_read_b128 v[204:207], v216
	ds_read_b128 v[208:211], v216 offset:1024
	ds_read_b128 v[212:215], v216 offset:2048
	ds_read_b128 v[216:219], v216 offset:3072
	global_load_lds_dwordx4 v[152:153], off
	v_lshl_add_u64 v[152:153], v[220:221], 0, s[6:7]
	s_add_i32 m0, s22, 0x2000
	s_nop 0
	global_load_lds_dwordx4 v[152:153], off
	s_barrier
	s_waitcnt lgkmcnt(0)
	s_setprio 1
	s_waitcnt lgkmcnt(0)
	v_mfma_f32_16x16x32_bf16 v[116:119], v[204:207], v[168:171], v[116:119]
	v_mfma_f32_16x16x32_bf16 v[112:115], v[212:215], v[168:171], v[112:115]
	v_mfma_f32_16x16x32_bf16 v[100:103], v[204:207], v[176:179], v[100:103]
	v_mfma_f32_16x16x32_bf16 v[96:99], v[212:215], v[176:179], v[96:99]
	v_mfma_f32_16x16x32_bf16 v[84:87], v[204:207], v[184:187], v[84:87]
	v_mfma_f32_16x16x32_bf16 v[80:83], v[212:215], v[184:187], v[80:83]
	v_mfma_f32_16x16x32_bf16 v[68:71], v[204:207], v[192:195], v[68:71]
	v_mfma_f32_16x16x32_bf16 v[64:67], v[212:215], v[192:195], v[64:67]
	v_mfma_f32_16x16x32_bf16 v[116:119], v[208:211], v[172:175], v[116:119]
	v_mfma_f32_16x16x32_bf16 v[112:115], v[216:219], v[172:175], v[112:115]
	v_mfma_f32_16x16x32_bf16 v[100:103], v[208:211], v[180:183], v[100:103]
	v_mfma_f32_16x16x32_bf16 v[96:99], v[216:219], v[180:183], v[96:99]
	v_mfma_f32_16x16x32_bf16 v[84:87], v[208:211], v[188:191], v[84:87]
	v_mfma_f32_16x16x32_bf16 v[80:83], v[216:219], v[188:191], v[80:83]
	v_mfma_f32_16x16x32_bf16 v[68:71], v[208:211], v[200:203], v[68:71]
	v_mfma_f32_16x16x32_bf16 v[64:67], v[216:219], v[200:203], v[64:67]
	s_setprio 0
	s_mov_b32 m0, s62
	v_lshl_add_u64 v[152:153], v[222:223], 0, s[6:7]
	s_barrier
	ds_read_b128 v[168:171], v157 offset:49152
	ds_read_b128 v[172:175], v157 offset:50176
	ds_read_b128 v[176:179], v157 offset:51200
	ds_read_b128 v[180:183], v157 offset:52224
	ds_read_b128 v[184:187], v157 offset:53248
	ds_read_b128 v[188:191], v157 offset:54272
	ds_read_b128 v[192:195], v157 offset:55296
	ds_read_b128 v[200:203], v157 offset:56320
	global_load_lds_dwordx4 v[152:153], off
	v_lshl_add_u64 v[152:153], v[224:225], 0, s[6:7]
	s_mov_b32 m0, s63
	s_nop 0
	global_load_lds_dwordx4 v[152:153], off
	s_barrier
	s_waitcnt lgkmcnt(0)
	s_setprio 1
	s_waitcnt lgkmcnt(0)
	v_mfma_f32_16x16x32_bf16 v[60:63], v[144:147], v[168:171], v[60:63]
	v_mfma_f32_16x16x32_bf16 v[56:59], v[160:163], v[168:171], v[56:59]
	v_mfma_f32_16x16x32_bf16 v[44:47], v[144:147], v[176:179], v[44:47]
	v_mfma_f32_16x16x32_bf16 v[40:43], v[160:163], v[176:179], v[40:43]
	v_mfma_f32_16x16x32_bf16 v[28:31], v[144:147], v[184:187], v[28:31]
	v_mfma_f32_16x16x32_bf16 v[24:27], v[160:163], v[184:187], v[24:27]
	v_mfma_f32_16x16x32_bf16 v[12:15], v[144:147], v[192:195], v[12:15]
	v_mfma_f32_16x16x32_bf16 v[8:11], v[160:163], v[192:195], v[8:11]
	v_mfma_f32_16x16x32_bf16 v[60:63], v[148:151], v[172:175], v[60:63]
	v_mfma_f32_16x16x32_bf16 v[56:59], v[164:167], v[172:175], v[56:59]
	v_mfma_f32_16x16x32_bf16 v[44:47], v[148:151], v[180:183], v[44:47]
	v_mfma_f32_16x16x32_bf16 v[40:43], v[164:167], v[180:183], v[40:43]
	v_mfma_f32_16x16x32_bf16 v[28:31], v[148:151], v[188:191], v[28:31]
	v_mfma_f32_16x16x32_bf16 v[24:27], v[164:167], v[188:191], v[24:27]
	v_mfma_f32_16x16x32_bf16 v[12:15], v[148:151], v[200:203], v[12:15]
	v_mfma_f32_16x16x32_bf16 v[8:11], v[164:167], v[200:203], v[8:11]
	s_setprio 0
	s_barrier
	s_add_u32 s22, s40, 0x40080
	s_addc_u32 s23, s41, 0
	s_add_i32 s40, s42, s48
	v_lshl_add_u64 v[144:145], s[22:23], 0, v[132:133]
	s_mov_b32 m0, s40
	s_nop 0
	global_load_lds_dwordx4 v[144:145], off
	v_lshl_add_u64 v[144:145], s[22:23], 0, v[128:129]
	s_add_i32 m0, s40, 0x2000
	s_nop 0
	global_load_lds_dwordx4 v[144:145], off
	s_waitcnt vmcnt(6)
	s_barrier
	s_setprio 1
	v_mfma_f32_16x16x32_bf16 v[52:55], v[204:207], v[168:171], v[52:55]
	v_mfma_f32_16x16x32_bf16 v[48:51], v[212:215], v[168:171], v[48:51]
	v_mfma_f32_16x16x32_bf16 v[36:39], v[204:207], v[176:179], v[36:39]
	v_mfma_f32_16x16x32_bf16 v[32:35], v[212:215], v[176:179], v[32:35]
	v_mfma_f32_16x16x32_bf16 v[20:23], v[204:207], v[184:187], v[20:23]
	v_mfma_f32_16x16x32_bf16 v[16:19], v[212:215], v[184:187], v[16:19]
	v_mfma_f32_16x16x32_bf16 v[4:7], v[204:207], v[192:195], v[4:7]
	v_mfma_f32_16x16x32_bf16 v[0:3], v[212:215], v[192:195], v[0:3]
	v_mfma_f32_16x16x32_bf16 v[52:55], v[208:211], v[172:175], v[52:55]
	v_mfma_f32_16x16x32_bf16 v[48:51], v[216:219], v[172:175], v[48:51]
	v_mfma_f32_16x16x32_bf16 v[36:39], v[208:211], v[180:183], v[36:39]
	v_mfma_f32_16x16x32_bf16 v[32:35], v[216:219], v[180:183], v[32:35]
	v_mfma_f32_16x16x32_bf16 v[20:23], v[208:211], v[188:191], v[20:23]
	v_mfma_f32_16x16x32_bf16 v[16:19], v[216:219], v[188:191], v[16:19]
	v_mfma_f32_16x16x32_bf16 v[4:7], v[208:211], v[200:203], v[4:7]
	v_mfma_f32_16x16x32_bf16 v[0:3], v[216:219], v[200:203], v[0:3]
	s_setprio 0
	s_add_i32 s44, s44, 2
	s_add_u32 s38, s38, 0x100
	s_addc_u32 s39, s39, 0
	s_add_u32 s18, s18, 0x100
	s_addc_u32 s19, s19, 0
	s_cmp_gt_u32 s44, 13
	s_barrier
	s_cbranch_scc0 .LBB0_495
	v_add_u32_e32 v144, s71, v154
	v_ashrrev_i32_e32 v145, 31, v144
	v_lshl_add_u64 v[146:147], v[144:145], 2, s[94:95]
	v_add_co_u32_e32 v148, vcc, 0x40000, v146
	s_ashr_i32 s18, s70, 7
	s_nop 0
	v_addc_co_u32_e32 v149, vcc, 0, v147, vcc
	v_add_co_u32_e32 v150, vcc, 0x80000, v146
	s_ashr_i32 s19, s18, 31
	s_nop 0
	v_addc_co_u32_e32 v151, vcc, 0, v147, vcc
	v_add_co_u32_e32 v152, vcc, 0xc0000, v146
	s_lshl_b64 s[18:19], s[18:19], 23
	s_nop 0
	v_addc_co_u32_e32 v153, vcc, 0, v147, vcc
	global_load_dword v160, v[146:147], off
	global_load_dword v162, v[148:149], off
	global_load_dword v161, v[150:151], off
	global_load_dword v163, v[152:153], off
	global_load_dword v226, v[146:147], off offset:64
	global_load_dword v227, v[148:149], off offset:64
	global_load_dword v228, v[150:151], off offset:64
	global_load_dword v229, v[152:153], off offset:64
	global_load_dword v230, v[146:147], off offset:128
	global_load_dword v231, v[148:149], off offset:128
	global_load_dword v232, v[150:151], off offset:128
	global_load_dword v233, v[152:153], off offset:128
	global_load_dword v234, v[146:147], off offset:192
	global_load_dword v235, v[148:149], off offset:192
	global_load_dword v236, v[150:151], off offset:192
	global_load_dword v237, v[152:153], off offset:192
	global_load_dword v238, v[146:147], off offset:512
	global_load_dword v239, v[148:149], off offset:512
	global_load_dword v240, v[150:151], off offset:512
	global_load_dword v241, v[152:153], off offset:512
	global_load_dword v242, v[146:147], off offset:576
	global_load_dword v243, v[148:149], off offset:576
	global_load_dword v244, v[150:151], off offset:576
	global_load_dword v245, v[152:153], off offset:576
	global_load_dword v246, v[146:147], off offset:640
	global_load_dword v247, v[148:149], off offset:640
	global_load_dword v248, v[150:151], off offset:640
	global_load_dword v249, v[152:153], off offset:640
	global_load_dword v250, v[146:147], off offset:704
	global_load_dword v251, v[148:149], off offset:704
	global_load_dword v252, v[150:151], off offset:704
	global_load_dword v253, v[152:153], off offset:704
	s_add_u32 s38, s92, s18
	s_addc_u32 s39, s93, s19
	v_lshlrev_b64 v[144:145], 8, v[144:145]
	s_add_u32 s40, s38, 0x800000
	v_lshl_add_u64 v[164:165], s[38:39], 0, v[144:145]
	s_addc_u32 s41, s39, 0
	v_lshl_add_u64 v[164:165], v[164:165], 0, s[8:9]
	v_lshl_add_u64 v[164:165], v[164:165], 0, v[136:137]
	s_mov_b64 s[18:19], 0x1000
	s_mov_b32 s70, s68
	s_mov_b32 s71, s69
	s_mov_b64 s[44:45], s[36:37]
	s_mov_b64 s[42:43], s[34:35]
	s_waitcnt vmcnt(0)
	v_pk_add_f32 v[160:161], v[160:161], v[162:163]
	s_nop 0
	v_add_f32_e32 v160, v160, v161
	v_fmamk_f32 v160, v160, 0x3a800000, v159
	v_mul_f32_e32 v161, 0x4b800000, v160
	v_cmp_gt_f32_e32 vcc, s66, v160
	s_nop 1
	v_cndmask_b32_e32 v160, v160, v161, vcc
	v_rsq_f32_e32 v162, v160
	v_lshl_add_u64 v[160:161], s[40:41], 0, v[144:145]
	v_lshl_add_u64 v[160:161], v[160:161], 0, s[8:9]
	v_lshl_add_u64 v[160:161], v[160:161], 0, v[136:137]
	v_mul_f32_e32 v163, 0x45800000, v162
	v_cndmask_b32_e32 v162, v162, v163, vcc
	v_pk_mul_f32 v[126:127], v[126:127], v[162:163] op_sel_hi:[1,0]
	v_pk_mul_f32 v[124:125], v[124:125], v[162:163] op_sel_hi:[1,0]
	v_pk_mul_f32 v[122:123], v[122:123], v[162:163] op_sel_hi:[1,0]
	v_pk_mul_f32 v[120:121], v[120:121], v[162:163] op_sel_hi:[1,0]
	v_pk_mul_f32 v[118:119], v[118:119], v[162:163] op_sel_hi:[1,0]
	v_pk_mul_f32 v[116:117], v[116:117], v[162:163] op_sel_hi:[1,0]
	v_pk_mul_f32 v[166:167], v[114:115], v[162:163] op_sel_hi:[1,0]
	v_pk_mul_f32 v[162:163], v[112:113], v[162:163] op_sel_hi:[1,0]
	v_cvt_pk_bf16_f32 v112, v124, v125
	v_cvt_pk_bf16_f32 v113, v126, v127
	v_cvt_pk_bf16_f32 v114, v120, v121
	v_cvt_pk_bf16_f32 v115, v122, v123
	v_cvt_pk_bf16_f32 v116, v116, v117
	v_cvt_pk_bf16_f32 v117, v118, v119
	s_nop 0
	v_cvt_pk_bf16_f32 v118, v162, v163
	v_cvt_pk_bf16_f32 v119, v166, v167
	global_store_dwordx4 v[164:165], v[112:115], off
	global_store_dwordx4 v[160:161], v[116:119], off
	s_nop 1
	v_mov_b32_e32 v112, v226
	s_nop 0
	v_mov_b32_e32 v114, v227
	v_mov_b32_e32 v113, v228
	v_mov_b32_e32 v115, v229
	v_lshl_add_u64 v[116:117], v[144:145], 0, s[18:19]
	v_lshl_add_u64 v[118:119], s[38:39], 0, v[116:117]
	v_lshl_add_u64 v[118:119], v[118:119], 0, s[8:9]
	v_lshl_add_u64 v[118:119], v[118:119], 0, v[136:137]
	s_mov_b64 s[18:19], 0x2000
	v_pk_add_f32 v[112:113], v[112:113], v[114:115]
	s_nop 0
	v_add_f32_e32 v112, v112, v113
	v_fmamk_f32 v112, v112, 0x3a800000, v159
	v_mul_f32_e32 v113, 0x4b800000, v112
	v_cmp_gt_f32_e32 vcc, s66, v112
	s_nop 1
	v_cndmask_b32_e32 v112, v112, v113, vcc
	v_rsq_f32_e32 v114, v112
	v_lshl_add_u64 v[112:113], s[40:41], 0, v[116:117]
	v_lshl_add_u64 v[112:113], v[112:113], 0, s[8:9]
	v_lshl_add_u64 v[112:113], v[112:113], 0, v[136:137]
	v_mul_f32_e32 v115, 0x45800000, v114
	v_cndmask_b32_e32 v114, v114, v115, vcc
	v_pk_mul_f32 v[110:111], v[110:111], v[114:115] op_sel_hi:[1,0]
	v_pk_mul_f32 v[108:109], v[108:109], v[114:115] op_sel_hi:[1,0]
	v_pk_mul_f32 v[106:107], v[106:107], v[114:115] op_sel_hi:[1,0]
	v_pk_mul_f32 v[104:105], v[104:105], v[114:115] op_sel_hi:[1,0]
	v_pk_mul_f32 v[102:103], v[102:103], v[114:115] op_sel_hi:[1,0]
	v_pk_mul_f32 v[100:101], v[100:101], v[114:115] op_sel_hi:[1,0]
	v_pk_mul_f32 v[116:117], v[98:99], v[114:115] op_sel_hi:[1,0]
	v_pk_mul_f32 v[114:115], v[96:97], v[114:115] op_sel_hi:[1,0]
	v_cvt_pk_bf16_f32 v96, v108, v109
	v_cvt_pk_bf16_f32 v97, v110, v111
	v_cvt_pk_bf16_f32 v98, v104, v105
	v_cvt_pk_bf16_f32 v99, v106, v107
	v_cvt_pk_bf16_f32 v100, v100, v101
	v_cvt_pk_bf16_f32 v101, v102, v103
	s_nop 0
	v_cvt_pk_bf16_f32 v102, v114, v115
	v_cvt_pk_bf16_f32 v103, v116, v117
	global_store_dwordx4 v[118:119], v[96:99], off
	global_store_dwordx4 v[112:113], v[100:103], off
	s_nop 1
	v_mov_b32_e32 v96, v230
	s_nop 0
	v_mov_b32_e32 v98, v231
	v_mov_b32_e32 v97, v232
	v_mov_b32_e32 v99, v233
	v_lshl_add_u64 v[100:101], v[144:145], 0, s[18:19]
	v_lshl_add_u64 v[102:103], s[38:39], 0, v[100:101]
	v_lshl_add_u64 v[102:103], v[102:103], 0, s[8:9]
	v_lshl_add_u64 v[102:103], v[102:103], 0, v[136:137]
	v_pk_add_f32 v[96:97], v[96:97], v[98:99]
	s_nop 0
	v_add_f32_e32 v96, v96, v97
	v_fmamk_f32 v96, v96, 0x3a800000, v159
	v_mul_f32_e32 v97, 0x4b800000, v96
	v_cmp_gt_f32_e32 vcc, s66, v96
	s_nop 1
	v_cndmask_b32_e32 v96, v96, v97, vcc
	v_rsq_f32_e32 v98, v96
	v_lshl_add_u64 v[96:97], s[40:41], 0, v[100:101]
	v_lshl_add_u64 v[96:97], v[96:97], 0, s[8:9]
	v_lshl_add_u64 v[96:97], v[96:97], 0, v[136:137]
	v_mul_f32_e32 v99, 0x45800000, v98
	v_cndmask_b32_e32 v98, v98, v99, vcc
	v_pk_mul_f32 v[94:95], v[94:95], v[98:99] op_sel_hi:[1,0]
	v_pk_mul_f32 v[92:93], v[92:93], v[98:99] op_sel_hi:[1,0]
	v_pk_mul_f32 v[90:91], v[90:91], v[98:99] op_sel_hi:[1,0]
	v_pk_mul_f32 v[88:89], v[88:89], v[98:99] op_sel_hi:[1,0]
	v_pk_mul_f32 v[86:87], v[86:87], v[98:99] op_sel_hi:[1,0]
	v_pk_mul_f32 v[84:85], v[84:85], v[98:99] op_sel_hi:[1,0]
	v_pk_mul_f32 v[100:101], v[82:83], v[98:99] op_sel_hi:[1,0]
	v_pk_mul_f32 v[98:99], v[80:81], v[98:99] op_sel_hi:[1,0]
	v_cvt_pk_bf16_f32 v80, v92, v93
	v_cvt_pk_bf16_f32 v81, v94, v95
	v_cvt_pk_bf16_f32 v82, v88, v89
	v_cvt_pk_bf16_f32 v83, v90, v91
	v_cvt_pk_bf16_f32 v84, v84, v85
	v_cvt_pk_bf16_f32 v85, v86, v87
	s_nop 0
	v_cvt_pk_bf16_f32 v86, v98, v99
	v_cvt_pk_bf16_f32 v87, v100, v101
	global_store_dwordx4 v[102:103], v[80:83], off
	global_store_dwordx4 v[96:97], v[84:87], off
	s_nop 1
	v_mov_b32_e32 v80, v234
	s_nop 0
	v_mov_b32_e32 v82, v235
	v_mov_b32_e32 v81, v236
	v_mov_b32_e32 v83, v237
	v_lshl_add_u64 v[84:85], v[144:145], 0, s[10:11]
	v_lshl_add_u64 v[86:87], s[38:39], 0, v[84:85]
	v_lshl_add_u64 v[86:87], v[86:87], 0, s[8:9]
	v_lshl_add_u64 v[86:87], v[86:87], 0, v[136:137]
	v_pk_add_f32 v[80:81], v[80:81], v[82:83]
	s_nop 0
	v_add_f32_e32 v80, v80, v81
	v_fmamk_f32 v80, v80, 0x3a800000, v159
	v_mul_f32_e32 v81, 0x4b800000, v80
	v_cmp_gt_f32_e32 vcc, s66, v80
	s_nop 1
	v_cndmask_b32_e32 v80, v80, v81, vcc
	v_rsq_f32_e32 v82, v80
	v_lshl_add_u64 v[80:81], s[40:41], 0, v[84:85]
	v_lshl_add_u64 v[80:81], v[80:81], 0, s[8:9]
	v_lshl_add_u64 v[80:81], v[80:81], 0, v[136:137]
	v_mul_f32_e32 v83, 0x45800000, v82
	v_cndmask_b32_e32 v82, v82, v83, vcc
	v_pk_mul_f32 v[78:79], v[78:79], v[82:83] op_sel_hi:[1,0]
	v_pk_mul_f32 v[76:77], v[76:77], v[82:83] op_sel_hi:[1,0]
	v_pk_mul_f32 v[74:75], v[74:75], v[82:83] op_sel_hi:[1,0]
	v_pk_mul_f32 v[72:73], v[72:73], v[82:83] op_sel_hi:[1,0]
	v_pk_mul_f32 v[70:71], v[70:71], v[82:83] op_sel_hi:[1,0]
	v_pk_mul_f32 v[68:69], v[68:69], v[82:83] op_sel_hi:[1,0]
	v_pk_mul_f32 v[84:85], v[66:67], v[82:83] op_sel_hi:[1,0]
	v_pk_mul_f32 v[82:83], v[64:65], v[82:83] op_sel_hi:[1,0]
	v_cvt_pk_bf16_f32 v64, v76, v77
	v_cvt_pk_bf16_f32 v65, v78, v79
	v_cvt_pk_bf16_f32 v66, v72, v73
	v_cvt_pk_bf16_f32 v67, v74, v75
	v_cvt_pk_bf16_f32 v68, v68, v69
	v_cvt_pk_bf16_f32 v69, v70, v71
	s_nop 0
	v_cvt_pk_bf16_f32 v70, v82, v83
	v_cvt_pk_bf16_f32 v71, v84, v85
	global_store_dwordx4 v[86:87], v[64:67], off
	global_store_dwordx4 v[80:81], v[68:71], off
	s_nop 1
	v_mov_b32_e32 v64, v238
	s_nop 0
	v_mov_b32_e32 v66, v239
	v_mov_b32_e32 v65, v240
	v_mov_b32_e32 v67, v241
	v_lshl_add_u64 v[68:69], v[144:145], 0, s[24:25]
	v_lshl_add_u64 v[70:71], s[38:39], 0, v[68:69]
	v_lshl_add_u64 v[70:71], v[70:71], 0, s[8:9]
	v_lshl_add_u64 v[70:71], v[70:71], 0, v[136:137]
	v_pk_add_f32 v[64:65], v[64:65], v[66:67]
	s_nop 0
	v_add_f32_e32 v64, v64, v65
	v_fmamk_f32 v64, v64, 0x3a800000, v159
	v_mul_f32_e32 v65, 0x4b800000, v64
	v_cmp_gt_f32_e32 vcc, s66, v64
	s_nop 1
	v_cndmask_b32_e32 v64, v64, v65, vcc
	v_rsq_f32_e32 v66, v64
	v_lshl_add_u64 v[64:65], s[40:41], 0, v[68:69]
	v_lshl_add_u64 v[64:65], v[64:65], 0, s[8:9]
	v_lshl_add_u64 v[64:65], v[64:65], 0, v[136:137]
	v_mul_f32_e32 v67, 0x45800000, v66
	v_cndmask_b32_e32 v66, v66, v67, vcc
	v_pk_mul_f32 v[62:63], v[62:63], v[66:67] op_sel_hi:[1,0]
	v_pk_mul_f32 v[60:61], v[60:61], v[66:67] op_sel_hi:[1,0]
	v_pk_mul_f32 v[58:59], v[58:59], v[66:67] op_sel_hi:[1,0]
	v_pk_mul_f32 v[56:57], v[56:57], v[66:67] op_sel_hi:[1,0]
	v_pk_mul_f32 v[54:55], v[54:55], v[66:67] op_sel_hi:[1,0]
	v_pk_mul_f32 v[52:53], v[52:53], v[66:67] op_sel_hi:[1,0]
	v_pk_mul_f32 v[68:69], v[50:51], v[66:67] op_sel_hi:[1,0]
	v_pk_mul_f32 v[66:67], v[48:49], v[66:67] op_sel_hi:[1,0]
	v_cvt_pk_bf16_f32 v48, v60, v61
	v_cvt_pk_bf16_f32 v49, v62, v63
	v_cvt_pk_bf16_f32 v50, v56, v57
	v_cvt_pk_bf16_f32 v51, v58, v59
	v_cvt_pk_bf16_f32 v52, v52, v53
	v_cvt_pk_bf16_f32 v53, v54, v55
	s_nop 0
	v_cvt_pk_bf16_f32 v54, v66, v67
	v_cvt_pk_bf16_f32 v55, v68, v69
	global_store_dwordx4 v[70:71], v[48:51], off
	global_store_dwordx4 v[64:65], v[52:55], off
	s_nop 1
	v_mov_b32_e32 v48, v242
	s_nop 0
	v_mov_b32_e32 v50, v243
	v_mov_b32_e32 v49, v244
	v_mov_b32_e32 v51, v245
	v_lshl_add_u64 v[52:53], v[144:145], 0, s[26:27]
	v_lshl_add_u64 v[54:55], s[38:39], 0, v[52:53]
	v_lshl_add_u64 v[54:55], v[54:55], 0, s[8:9]
	v_lshl_add_u64 v[54:55], v[54:55], 0, v[136:137]
	v_pk_add_f32 v[48:49], v[48:49], v[50:51]
	s_nop 0
	v_add_f32_e32 v48, v48, v49
	v_fmamk_f32 v48, v48, 0x3a800000, v159
	v_mul_f32_e32 v49, 0x4b800000, v48
	v_cmp_gt_f32_e32 vcc, s66, v48
	s_nop 1
	v_cndmask_b32_e32 v48, v48, v49, vcc
	v_rsq_f32_e32 v50, v48
	v_lshl_add_u64 v[48:49], s[40:41], 0, v[52:53]
	v_lshl_add_u64 v[48:49], v[48:49], 0, s[8:9]
	v_lshl_add_u64 v[48:49], v[48:49], 0, v[136:137]
	v_mul_f32_e32 v51, 0x45800000, v50
	v_cndmask_b32_e32 v50, v50, v51, vcc
	v_pk_mul_f32 v[46:47], v[46:47], v[50:51] op_sel_hi:[1,0]
	v_pk_mul_f32 v[44:45], v[44:45], v[50:51] op_sel_hi:[1,0]
	v_pk_mul_f32 v[42:43], v[42:43], v[50:51] op_sel_hi:[1,0]
	v_pk_mul_f32 v[40:41], v[40:41], v[50:51] op_sel_hi:[1,0]
	v_pk_mul_f32 v[38:39], v[38:39], v[50:51] op_sel_hi:[1,0]
	v_pk_mul_f32 v[36:37], v[36:37], v[50:51] op_sel_hi:[1,0]
	v_pk_mul_f32 v[52:53], v[34:35], v[50:51] op_sel_hi:[1,0]
	v_pk_mul_f32 v[50:51], v[32:33], v[50:51] op_sel_hi:[1,0]
	v_cvt_pk_bf16_f32 v32, v44, v45
	v_cvt_pk_bf16_f32 v33, v46, v47
	v_cvt_pk_bf16_f32 v34, v40, v41
	v_cvt_pk_bf16_f32 v35, v42, v43
	v_cvt_pk_bf16_f32 v36, v36, v37
	v_cvt_pk_bf16_f32 v37, v38, v39
	s_nop 0
	v_cvt_pk_bf16_f32 v38, v50, v51
	v_cvt_pk_bf16_f32 v39, v52, v53
	global_store_dwordx4 v[54:55], v[32:35], off
	global_store_dwordx4 v[48:49], v[36:39], off
	s_nop 1
	v_mov_b32_e32 v32, v246
	s_nop 0
	v_mov_b32_e32 v34, v247
	v_mov_b32_e32 v33, v248
	v_mov_b32_e32 v35, v249
	v_lshl_add_u64 v[36:37], v[144:145], 0, s[28:29]
	v_lshl_add_u64 v[38:39], s[38:39], 0, v[36:37]
	v_lshl_add_u64 v[38:39], v[38:39], 0, s[8:9]
	v_lshl_add_u64 v[38:39], v[38:39], 0, v[136:137]
	v_pk_add_f32 v[32:33], v[32:33], v[34:35]
	s_nop 0
	v_add_f32_e32 v32, v32, v33
	v_fmamk_f32 v32, v32, 0x3a800000, v159
	v_mul_f32_e32 v33, 0x4b800000, v32
	v_cmp_gt_f32_e32 vcc, s66, v32
	s_nop 1
	v_cndmask_b32_e32 v32, v32, v33, vcc
	v_rsq_f32_e32 v34, v32
	v_lshl_add_u64 v[32:33], s[40:41], 0, v[36:37]
	v_lshl_add_u64 v[32:33], v[32:33], 0, s[8:9]
	v_lshl_add_u64 v[32:33], v[32:33], 0, v[136:137]
	v_mul_f32_e32 v35, 0x45800000, v34
	v_cndmask_b32_e32 v34, v34, v35, vcc
	v_pk_mul_f32 v[30:31], v[30:31], v[34:35] op_sel_hi:[1,0]
	v_pk_mul_f32 v[28:29], v[28:29], v[34:35] op_sel_hi:[1,0]
	v_pk_mul_f32 v[26:27], v[26:27], v[34:35] op_sel_hi:[1,0]
	v_pk_mul_f32 v[24:25], v[24:25], v[34:35] op_sel_hi:[1,0]
	v_pk_mul_f32 v[22:23], v[22:23], v[34:35] op_sel_hi:[1,0]
	v_pk_mul_f32 v[20:21], v[20:21], v[34:35] op_sel_hi:[1,0]
	v_pk_mul_f32 v[36:37], v[18:19], v[34:35] op_sel_hi:[1,0]
	v_pk_mul_f32 v[34:35], v[16:17], v[34:35] op_sel_hi:[1,0]
	v_cvt_pk_bf16_f32 v16, v28, v29
	v_cvt_pk_bf16_f32 v17, v30, v31
	v_cvt_pk_bf16_f32 v18, v24, v25
	v_cvt_pk_bf16_f32 v19, v26, v27
	v_cvt_pk_bf16_f32 v20, v20, v21
	v_cvt_pk_bf16_f32 v21, v22, v23
	s_nop 0
	v_cvt_pk_bf16_f32 v22, v34, v35
	v_cvt_pk_bf16_f32 v23, v36, v37
	global_store_dwordx4 v[38:39], v[16:19], off
	global_store_dwordx4 v[32:33], v[20:23], off
	s_nop 1
	v_mov_b32_e32 v16, v250
	s_nop 0
	v_mov_b32_e32 v18, v251
	v_mov_b32_e32 v17, v252
	v_mov_b32_e32 v19, v253
	s_and_b64 vcc, exec, s[2:3]
	v_lshl_add_u64 v[20:21], v[144:145], 0, s[30:31]
	v_lshl_add_u64 v[22:23], s[38:39], 0, v[20:21]
	v_lshl_add_u64 v[22:23], v[22:23], 0, s[8:9]
	v_lshl_add_u64 v[22:23], v[22:23], 0, v[136:137]
	v_pk_add_f32 v[16:17], v[16:17], v[18:19]
	s_nop 0
	v_add_f32_e32 v16, v16, v17
	v_fmamk_f32 v16, v16, 0x3a800000, v159
	v_mul_f32_e32 v17, 0x4b800000, v16
	v_cmp_gt_f32_e64 s[2:3], s66, v16
	s_nop 1
	v_cndmask_b32_e64 v16, v16, v17, s[2:3]
	v_rsq_f32_e32 v18, v16
	v_lshl_add_u64 v[16:17], s[40:41], 0, v[20:21]
	v_lshl_add_u64 v[16:17], v[16:17], 0, s[8:9]
	v_lshl_add_u64 v[16:17], v[16:17], 0, v[136:137]
	v_mul_f32_e32 v19, 0x45800000, v18
	v_cndmask_b32_e64 v18, v18, v19, s[2:3]
	v_pk_mul_f32 v[14:15], v[14:15], v[18:19] op_sel_hi:[1,0]
	v_pk_mul_f32 v[12:13], v[12:13], v[18:19] op_sel_hi:[1,0]
	v_pk_mul_f32 v[10:11], v[10:11], v[18:19] op_sel_hi:[1,0]
	v_pk_mul_f32 v[8:9], v[8:9], v[18:19] op_sel_hi:[1,0]
	v_pk_mul_f32 v[6:7], v[6:7], v[18:19] op_sel_hi:[1,0]
	v_pk_mul_f32 v[4:5], v[4:5], v[18:19] op_sel_hi:[1,0]
	v_pk_mul_f32 v[20:21], v[2:3], v[18:19] op_sel_hi:[1,0]
	v_pk_mul_f32 v[18:19], v[0:1], v[18:19] op_sel_hi:[1,0]
	v_cvt_pk_bf16_f32 v0, v12, v13
	v_cvt_pk_bf16_f32 v1, v14, v15
	v_cvt_pk_bf16_f32 v2, v8, v9
	v_cvt_pk_bf16_f32 v3, v10, v11
	v_cvt_pk_bf16_f32 v4, v4, v5
	v_cvt_pk_bf16_f32 v5, v6, v7
	s_nop 0
	v_cvt_pk_bf16_f32 v6, v18, v19
	v_cvt_pk_bf16_f32 v7, v20, v21
	global_store_dwordx4 v[22:23], v[0:3], off
	global_store_dwordx4 v[16:17], v[4:7], off
	s_cbranch_vccz .LBB0_492
	s_waitcnt vmcnt(0)
	s_cmpk_gt_u32 s33, 0xff
	s_cbranch_scc1 .LBB0_499
	s_barrier

.LBB0_667:
	ds_read_b128 v[144:147], v156
	ds_read_b128 v[148:151], v156 offset:1024
	ds_read_b128 v[160:163], v156 offset:2048
	ds_read_b128 v[164:167], v156 offset:3072
	s_add_u32 s42, s40, 0xfffc0080
	s_addc_u32 s43, s41, -1
	s_cmp_eq_u32 s46, 12
	s_cselect_b32 s45, s37, s43
	s_cselect_b32 s44, s36, s42
	s_cselect_b32 s43, s39, s19
	s_cselect_b32 s42, s38, s18
	v_lshl_add_u64 v[152:153], s[40:41], 0, v[138:139]
	s_add_i32 m0, s53, 0xc000
	ds_read_b128 v[168:171], v157
	ds_read_b128 v[172:175], v157 offset:1024
	ds_read_b128 v[176:179], v157 offset:2048
	ds_read_b128 v[180:183], v157 offset:3072
	ds_read_b128 v[184:187], v157 offset:4096
	ds_read_b128 v[188:191], v157 offset:5120
	ds_read_b128 v[192:195], v157 offset:6144
	ds_read_b128 v[200:203], v157 offset:7168
	global_load_lds_dwordx4 v[152:153], off
	v_lshl_add_u64 v[152:153], s[40:41], 0, v[140:141]
	s_add_i32 m0, s53, 0xe000
	s_nop 0
	global_load_lds_dwordx4 v[152:153], off
	s_waitcnt lgkmcnt(8)
	s_barrier
	s_waitcnt lgkmcnt(0)
	s_setprio 1
	s_waitcnt lgkmcnt(0)
	v_mfma_f32_16x16x32_bf16 v[124:127], v[144:147], v[168:171], v[124:127]
	v_mfma_f32_16x16x32_bf16 v[120:123], v[160:163], v[168:171], v[120:123]
	v_mfma_f32_16x16x32_bf16 v[108:111], v[144:147], v[176:179], v[108:111]
	v_mfma_f32_16x16x32_bf16 v[104:107], v[160:163], v[176:179], v[104:107]
	v_mfma_f32_16x16x32_bf16 v[92:95], v[144:147], v[184:187], v[92:95]
	v_mfma_f32_16x16x32_bf16 v[88:91], v[160:163], v[184:187], v[88:91]
	v_mfma_f32_16x16x32_bf16 v[76:79], v[144:147], v[192:195], v[76:79]
	v_mfma_f32_16x16x32_bf16 v[72:75], v[160:163], v[192:195], v[72:75]
	v_mfma_f32_16x16x32_bf16 v[124:127], v[148:151], v[172:175], v[124:127]
	v_mfma_f32_16x16x32_bf16 v[120:123], v[164:167], v[172:175], v[120:123]
	v_mfma_f32_16x16x32_bf16 v[108:111], v[148:151], v[180:183], v[108:111]
	v_mfma_f32_16x16x32_bf16 v[104:107], v[164:167], v[180:183], v[104:107]
	v_mfma_f32_16x16x32_bf16 v[92:95], v[148:151], v[188:191], v[92:95]
	v_mfma_f32_16x16x32_bf16 v[88:91], v[164:167], v[188:191], v[88:91]
	v_mfma_f32_16x16x32_bf16 v[76:79], v[148:151], v[200:203], v[76:79]
	v_mfma_f32_16x16x32_bf16 v[72:75], v[164:167], v[200:203], v[72:75]
	s_setprio 0
	s_barrier
	s_add_i32 s47, s67, s50
	v_lshl_add_u64 v[152:153], s[42:43], 0, v[132:133]
	s_mov_b32 m0, s47
	ds_read_b128 v[204:207], v158
	ds_read_b128 v[208:211], v158 offset:1024
	ds_read_b128 v[212:215], v158 offset:2048
	ds_read_b128 v[216:219], v158 offset:3072
	global_load_lds_dwordx4 v[152:153], off
	v_lshl_add_u64 v[220:221], s[42:43], 0, v[128:129]
	s_add_i32 m0, s47, 0x2000
	s_nop 0
	global_load_lds_dwordx4 v[220:221], off
	s_barrier
	s_waitcnt lgkmcnt(0)
	s_setprio 1
	s_waitcnt lgkmcnt(0)
	v_mfma_f32_16x16x32_bf16 v[116:119], v[204:207], v[168:171], v[116:119]
	v_mfma_f32_16x16x32_bf16 v[112:115], v[212:215], v[168:171], v[112:115]
	v_mfma_f32_16x16x32_bf16 v[100:103], v[204:207], v[176:179], v[100:103]
	v_mfma_f32_16x16x32_bf16 v[96:99], v[212:215], v[176:179], v[96:99]
	v_mfma_f32_16x16x32_bf16 v[84:87], v[204:207], v[184:187], v[84:87]
	v_mfma_f32_16x16x32_bf16 v[80:83], v[212:215], v[184:187], v[80:83]
	v_mfma_f32_16x16x32_bf16 v[68:71], v[204:207], v[192:195], v[68:71]
	v_mfma_f32_16x16x32_bf16 v[64:67], v[212:215], v[192:195], v[64:67]
	v_mfma_f32_16x16x32_bf16 v[116:119], v[208:211], v[172:175], v[116:119]
	v_mfma_f32_16x16x32_bf16 v[112:115], v[216:219], v[172:175], v[112:115]
	v_mfma_f32_16x16x32_bf16 v[100:103], v[208:211], v[180:183], v[100:103]
	v_mfma_f32_16x16x32_bf16 v[96:99], v[216:219], v[180:183], v[96:99]
	v_mfma_f32_16x16x32_bf16 v[84:87], v[208:211], v[188:191], v[84:87]
	v_mfma_f32_16x16x32_bf16 v[80:83], v[216:219], v[188:191], v[80:83]
	v_mfma_f32_16x16x32_bf16 v[68:71], v[208:211], v[200:203], v[68:71]
	v_mfma_f32_16x16x32_bf16 v[64:67], v[216:219], v[200:203], v[64:67]
	s_setprio 0
	s_mov_b32 m0, s53
	v_lshl_add_u64 v[222:223], s[44:45], 0, v[134:135]
	s_barrier
	ds_read_b128 v[168:171], v157 offset:16384
	ds_read_b128 v[172:175], v157 offset:17408
	ds_read_b128 v[176:179], v157 offset:18432
	ds_read_b128 v[180:183], v157 offset:19456
	ds_read_b128 v[184:187], v157 offset:20480
	ds_read_b128 v[188:191], v157 offset:21504
	ds_read_b128 v[192:195], v157 offset:22528
	ds_read_b128 v[200:203], v157 offset:23552
	global_load_lds_dwordx4 v[222:223], off
	v_lshl_add_u64 v[224:225], s[44:45], 0, v[130:131]
	s_mov_b32 m0, s62
	s_nop 0
	global_load_lds_dwordx4 v[224:225], off
	s_barrier
	s_waitcnt lgkmcnt(0)
	s_setprio 1
	s_waitcnt lgkmcnt(0)
	v_mfma_f32_16x16x32_bf16 v[60:63], v[144:147], v[168:171], v[60:63]
	v_mfma_f32_16x16x32_bf16 v[56:59], v[160:163], v[168:171], v[56:59]
	v_mfma_f32_16x16x32_bf16 v[44:47], v[144:147], v[176:179], v[44:47]
	v_mfma_f32_16x16x32_bf16 v[40:43], v[160:163], v[176:179], v[40:43]
	v_mfma_f32_16x16x32_bf16 v[28:31], v[144:147], v[184:187], v[28:31]
	v_mfma_f32_16x16x32_bf16 v[24:27], v[160:163], v[184:187], v[24:27]
	v_mfma_f32_16x16x32_bf16 v[12:15], v[144:147], v[192:195], v[12:15]
	v_mfma_f32_16x16x32_bf16 v[8:11], v[160:163], v[192:195], v[8:11]
	v_mfma_f32_16x16x32_bf16 v[60:63], v[148:151], v[172:175], v[60:63]
	v_mfma_f32_16x16x32_bf16 v[56:59], v[164:167], v[172:175], v[56:59]
	v_mfma_f32_16x16x32_bf16 v[44:47], v[148:151], v[180:183], v[44:47]
	v_mfma_f32_16x16x32_bf16 v[40:43], v[164:167], v[180:183], v[40:43]
	v_mfma_f32_16x16x32_bf16 v[28:31], v[148:151], v[188:191], v[28:31]
	v_mfma_f32_16x16x32_bf16 v[24:27], v[164:167], v[188:191], v[24:27]
	v_mfma_f32_16x16x32_bf16 v[12:15], v[148:151], v[200:203], v[12:15]
	v_mfma_f32_16x16x32_bf16 v[8:11], v[164:167], v[200:203], v[8:11]
	s_setprio 0
	s_barrier
	s_add_u32 s76, s42, 0x40000
	s_addc_u32 s77, s43, 0
	s_add_i32 s47, s68, s50
	v_lshl_add_u64 v[144:145], s[76:77], 0, v[132:133]
	s_mov_b32 m0, s47
	s_nop 0
	global_load_lds_dwordx4 v[144:145], off
	v_lshl_add_u64 v[144:145], s[76:77], 0, v[128:129]
	s_add_i32 m0, s47, 0x2000
	s_nop 0
	global_load_lds_dwordx4 v[144:145], off
	s_waitcnt vmcnt(6)
	s_barrier
	s_setprio 1
	v_mfma_f32_16x16x32_bf16 v[52:55], v[204:207], v[168:171], v[52:55]
	v_mfma_f32_16x16x32_bf16 v[48:51], v[212:215], v[168:171], v[48:51]
	v_mfma_f32_16x16x32_bf16 v[36:39], v[204:207], v[176:179], v[36:39]
	v_mfma_f32_16x16x32_bf16 v[32:35], v[212:215], v[176:179], v[32:35]
	v_mfma_f32_16x16x32_bf16 v[20:23], v[204:207], v[184:187], v[20:23]
	v_mfma_f32_16x16x32_bf16 v[16:19], v[212:215], v[184:187], v[16:19]
	v_mfma_f32_16x16x32_bf16 v[4:7], v[204:207], v[192:195], v[4:7]
	v_mfma_f32_16x16x32_bf16 v[0:3], v[212:215], v[192:195], v[0:3]
	v_mfma_f32_16x16x32_bf16 v[52:55], v[208:211], v[172:175], v[52:55]
	v_mfma_f32_16x16x32_bf16 v[48:51], v[216:219], v[172:175], v[48:51]
	v_mfma_f32_16x16x32_bf16 v[36:39], v[208:211], v[180:183], v[36:39]
	v_mfma_f32_16x16x32_bf16 v[32:35], v[216:219], v[180:183], v[32:35]
	v_mfma_f32_16x16x32_bf16 v[20:23], v[208:211], v[188:191], v[20:23]
	v_mfma_f32_16x16x32_bf16 v[16:19], v[216:219], v[188:191], v[16:19]
	v_mfma_f32_16x16x32_bf16 v[4:7], v[208:211], v[200:203], v[4:7]
	v_mfma_f32_16x16x32_bf16 v[0:3], v[216:219], v[200:203], v[0:3]
	s_setprio 0
	s_add_i32 s47, 0, 0x18000
	v_add_u32_e32 v164, s47, v155
	s_barrier
	ds_read_b128 v[144:147], v164
	ds_read_b128 v[148:151], v164 offset:1024
	ds_read_b128 v[160:163], v164 offset:2048
	ds_read_b128 v[164:167], v164 offset:3072
	s_add_u32 s44, s44, 0x40000
	s_addc_u32 s45, s45, 0
	s_mov_b32 m0, s63
	v_lshl_add_u64 v[204:205], s[44:45], 0, v[134:135]
	ds_read_b128 v[168:171], v157 offset:32768
	ds_read_b128 v[172:175], v157 offset:33792
	ds_read_b128 v[176:179], v157 offset:34816
	ds_read_b128 v[180:183], v157 offset:35840
	ds_read_b128 v[184:187], v157 offset:36864
	ds_read_b128 v[188:191], v157 offset:37888
	ds_read_b128 v[192:195], v157 offset:38912
	ds_read_b128 v[200:203], v157 offset:39936
	global_load_lds_dwordx4 v[204:205], off
	v_lshl_add_u64 v[204:205], s[44:45], 0, v[130:131]
	s_mov_b32 m0, s64
	s_nop 0
	global_load_lds_dwordx4 v[204:205], off
	s_waitcnt lgkmcnt(8)
	s_barrier
	s_waitcnt lgkmcnt(0)
	s_setprio 1
	s_waitcnt lgkmcnt(0)
	v_mfma_f32_16x16x32_bf16 v[124:127], v[144:147], v[168:171], v[124:127]
	v_mfma_f32_16x16x32_bf16 v[120:123], v[160:163], v[168:171], v[120:123]
	v_mfma_f32_16x16x32_bf16 v[108:111], v[144:147], v[176:179], v[108:111]
	v_mfma_f32_16x16x32_bf16 v[104:107], v[160:163], v[176:179], v[104:107]
	v_mfma_f32_16x16x32_bf16 v[92:95], v[144:147], v[184:187], v[92:95]
	v_mfma_f32_16x16x32_bf16 v[88:91], v[160:163], v[184:187], v[88:91]
	v_mfma_f32_16x16x32_bf16 v[76:79], v[144:147], v[192:195], v[76:79]
	v_mfma_f32_16x16x32_bf16 v[72:75], v[160:163], v[192:195], v[72:75]
	v_mfma_f32_16x16x32_bf16 v[124:127], v[148:151], v[172:175], v[124:127]
	v_mfma_f32_16x16x32_bf16 v[120:123], v[164:167], v[172:175], v[120:123]
	v_mfma_f32_16x16x32_bf16 v[108:111], v[148:151], v[180:183], v[108:111]
	v_mfma_f32_16x16x32_bf16 v[104:107], v[164:167], v[180:183], v[104:107]
	v_mfma_f32_16x16x32_bf16 v[92:95], v[148:151], v[188:191], v[92:95]
	v_mfma_f32_16x16x32_bf16 v[88:91], v[164:167], v[188:191], v[88:91]
	v_mfma_f32_16x16x32_bf16 v[76:79], v[148:151], v[200:203], v[76:79]
	v_mfma_f32_16x16x32_bf16 v[72:75], v[164:167], v[200:203], v[72:75]
	s_setprio 0
	s_barrier
	s_add_i32 s44, 0, 0x1c000
	s_add_i32 s45, s47, s50
	v_add_u32_e32 v216, s44, v155
	v_lshl_add_u64 v[152:153], v[152:153], 0, s[8:9]
	s_mov_b32 m0, s45
	ds_read_b128 v[204:207], v216
	ds_read_b128 v[208:211], v216 offset:1024
	ds_read_b128 v[212:215], v216 offset:2048
	ds_read_b128 v[216:219], v216 offset:3072
	global_load_lds_dwordx4 v[152:153], off
	v_lshl_add_u64 v[152:153], v[220:221], 0, s[8:9]
	s_add_i32 m0, s45, 0x2000
	s_nop 0
	global_load_lds_dwordx4 v[152:153], off
	s_barrier
	s_waitcnt lgkmcnt(0)
	s_setprio 1
	s_waitcnt lgkmcnt(0)
	v_mfma_f32_16x16x32_bf16 v[116:119], v[204:207], v[168:171], v[116:119]
	v_mfma_f32_16x16x32_bf16 v[112:115], v[212:215], v[168:171], v[112:115]
	v_mfma_f32_16x16x32_bf16 v[100:103], v[204:207], v[176:179], v[100:103]
	v_mfma_f32_16x16x32_bf16 v[96:99], v[212:215], v[176:179], v[96:99]
	v_mfma_f32_16x16x32_bf16 v[84:87], v[204:207], v[184:187], v[84:87]
	v_mfma_f32_16x16x32_bf16 v[80:83], v[212:215], v[184:187], v[80:83]
	v_mfma_f32_16x16x32_bf16 v[68:71], v[204:207], v[192:195], v[68:71]
	v_mfma_f32_16x16x32_bf16 v[64:67], v[212:215], v[192:195], v[64:67]
	v_mfma_f32_16x16x32_bf16 v[116:119], v[208:211], v[172:175], v[116:119]
	v_mfma_f32_16x16x32_bf16 v[112:115], v[216:219], v[172:175], v[112:115]
	v_mfma_f32_16x16x32_bf16 v[100:103], v[208:211], v[180:183], v[100:103]
	v_mfma_f32_16x16x32_bf16 v[96:99], v[216:219], v[180:183], v[96:99]
	v_mfma_f32_16x16x32_bf16 v[84:87], v[208:211], v[188:191], v[84:87]
	v_mfma_f32_16x16x32_bf16 v[80:83], v[216:219], v[188:191], v[80:83]
	v_mfma_f32_16x16x32_bf16 v[68:71], v[208:211], v[200:203], v[68:71]
	v_mfma_f32_16x16x32_bf16 v[64:67], v[216:219], v[200:203], v[64:67]
	s_setprio 0
	s_mov_b32 m0, s65
	v_lshl_add_u64 v[152:153], v[222:223], 0, s[8:9]
	s_barrier
	ds_read_b128 v[168:171], v157 offset:49152
	ds_read_b128 v[172:175], v157 offset:50176
	ds_read_b128 v[176:179], v157 offset:51200
	ds_read_b128 v[180:183], v157 offset:52224
	ds_read_b128 v[184:187], v157 offset:53248
	ds_read_b128 v[188:191], v157 offset:54272
	ds_read_b128 v[192:195], v157 offset:55296
	ds_read_b128 v[200:203], v157 offset:56320
	global_load_lds_dwordx4 v[152:153], off
	v_lshl_add_u64 v[152:153], v[224:225], 0, s[8:9]
	s_mov_b32 m0, s66
	s_nop 0
	global_load_lds_dwordx4 v[152:153], off
	s_barrier
	s_waitcnt lgkmcnt(0)
	s_setprio 1
	s_waitcnt lgkmcnt(0)
	v_mfma_f32_16x16x32_bf16 v[60:63], v[144:147], v[168:171], v[60:63]
	v_mfma_f32_16x16x32_bf16 v[56:59], v[160:163], v[168:171], v[56:59]
	v_mfma_f32_16x16x32_bf16 v[44:47], v[144:147], v[176:179], v[44:47]
	v_mfma_f32_16x16x32_bf16 v[40:43], v[160:163], v[176:179], v[40:43]
	v_mfma_f32_16x16x32_bf16 v[28:31], v[144:147], v[184:187], v[28:31]
	v_mfma_f32_16x16x32_bf16 v[24:27], v[160:163], v[184:187], v[24:27]
	v_mfma_f32_16x16x32_bf16 v[12:15], v[144:147], v[192:195], v[12:15]
	v_mfma_f32_16x16x32_bf16 v[8:11], v[160:163], v[192:195], v[8:11]
	v_mfma_f32_16x16x32_bf16 v[60:63], v[148:151], v[172:175], v[60:63]
	v_mfma_f32_16x16x32_bf16 v[56:59], v[164:167], v[172:175], v[56:59]
	v_mfma_f32_16x16x32_bf16 v[44:47], v[148:151], v[180:183], v[44:47]
	v_mfma_f32_16x16x32_bf16 v[40:43], v[164:167], v[180:183], v[40:43]
	v_mfma_f32_16x16x32_bf16 v[28:31], v[148:151], v[188:191], v[28:31]
	v_mfma_f32_16x16x32_bf16 v[24:27], v[164:167], v[188:191], v[24:27]
	v_mfma_f32_16x16x32_bf16 v[12:15], v[148:151], v[200:203], v[12:15]
	v_mfma_f32_16x16x32_bf16 v[8:11], v[164:167], v[200:203], v[8:11]
	s_setprio 0
	s_barrier
	s_add_u32 s42, s42, 0x40080
	s_addc_u32 s43, s43, 0
	s_add_i32 s44, s44, s50
	v_lshl_add_u64 v[144:145], s[42:43], 0, v[132:133]
	s_mov_b32 m0, s44
	s_nop 0
	global_load_lds_dwordx4 v[144:145], off
	v_lshl_add_u64 v[144:145], s[42:43], 0, v[128:129]
	s_add_i32 m0, s44, 0x2000
	s_nop 0
	global_load_lds_dwordx4 v[144:145], off
	s_waitcnt vmcnt(6)
	s_barrier
	s_setprio 1
	v_mfma_f32_16x16x32_bf16 v[52:55], v[204:207], v[168:171], v[52:55]
	v_mfma_f32_16x16x32_bf16 v[48:51], v[212:215], v[168:171], v[48:51]
	v_mfma_f32_16x16x32_bf16 v[36:39], v[204:207], v[176:179], v[36:39]
	v_mfma_f32_16x16x32_bf16 v[32:35], v[212:215], v[176:179], v[32:35]
	v_mfma_f32_16x16x32_bf16 v[20:23], v[204:207], v[184:187], v[20:23]
	v_mfma_f32_16x16x32_bf16 v[16:19], v[212:215], v[184:187], v[16:19]
	v_mfma_f32_16x16x32_bf16 v[4:7], v[204:207], v[192:195], v[4:7]
	v_mfma_f32_16x16x32_bf16 v[0:3], v[212:215], v[192:195], v[0:3]
	v_mfma_f32_16x16x32_bf16 v[52:55], v[208:211], v[172:175], v[52:55]
	v_mfma_f32_16x16x32_bf16 v[48:51], v[216:219], v[172:175], v[48:51]
	v_mfma_f32_16x16x32_bf16 v[36:39], v[208:211], v[180:183], v[36:39]
	v_mfma_f32_16x16x32_bf16 v[32:35], v[216:219], v[180:183], v[32:35]
	v_mfma_f32_16x16x32_bf16 v[20:23], v[208:211], v[188:191], v[20:23]
	v_mfma_f32_16x16x32_bf16 v[16:19], v[216:219], v[188:191], v[16:19]
	v_mfma_f32_16x16x32_bf16 v[4:7], v[208:211], v[200:203], v[4:7]
	v_mfma_f32_16x16x32_bf16 v[0:3], v[216:219], v[200:203], v[0:3]
	s_setprio 0
	s_add_i32 s46, s46, 2
	s_add_u32 s40, s40, 0x100
	s_addc_u32 s41, s41, 0
	s_add_u32 s18, s18, 0x100
	s_addc_u32 s19, s19, 0
	s_cmp_gt_u32 s46, 13
	s_barrier
	s_cbranch_scc0 .LBB0_667
	v_add_u32_e32 v144, s74, v154
	v_ashrrev_i32_e32 v145, 31, v144
	v_lshl_add_u64 v[146:147], v[144:145], 2, s[94:95]
	v_add_co_u32_e32 v148, vcc, 0x40000, v146
	s_ashr_i32 s18, s73, 7
	s_nop 0
	v_addc_co_u32_e32 v149, vcc, 0, v147, vcc
	v_add_co_u32_e32 v150, vcc, 0x80000, v146
	s_mov_b32 s40, 0xff800000
	s_nop 0
	v_addc_co_u32_e32 v151, vcc, 0, v147, vcc
	v_add_co_u32_e32 v152, vcc, 0xc0000, v146
	s_ashr_i32 s19, s18, 31
	s_nop 0
	v_addc_co_u32_e32 v153, vcc, 0, v147, vcc
	global_load_dword v160, v[146:147], off
	global_load_dword v162, v[148:149], off
	global_load_dword v161, v[150:151], off
	global_load_dword v163, v[152:153], off
	global_load_dword v226, v[146:147], off offset:64
	global_load_dword v227, v[148:149], off offset:64
	global_load_dword v228, v[150:151], off offset:64
	global_load_dword v229, v[152:153], off offset:64
	global_load_dword v230, v[146:147], off offset:128
	global_load_dword v231, v[148:149], off offset:128
	global_load_dword v232, v[150:151], off offset:128
	global_load_dword v233, v[152:153], off offset:128
	global_load_dword v234, v[146:147], off offset:192
	global_load_dword v235, v[148:149], off offset:192
	global_load_dword v236, v[150:151], off offset:192
	global_load_dword v237, v[152:153], off offset:192
	global_load_dword v238, v[146:147], off offset:512
	global_load_dword v239, v[148:149], off offset:512
	global_load_dword v240, v[150:151], off offset:512
	global_load_dword v241, v[152:153], off offset:512
	global_load_dword v242, v[146:147], off offset:576
	global_load_dword v243, v[148:149], off offset:576
	global_load_dword v244, v[150:151], off offset:576
	global_load_dword v245, v[152:153], off offset:576
	global_load_dword v246, v[146:147], off offset:640
	global_load_dword v247, v[148:149], off offset:640
	global_load_dword v248, v[150:151], off offset:640
	global_load_dword v249, v[152:153], off offset:640
	global_load_dword v250, v[146:147], off offset:704
	global_load_dword v251, v[148:149], off offset:704
	global_load_dword v252, v[150:151], off offset:704
	global_load_dword v253, v[152:153], off offset:704
	s_mov_b32 s41, -1
	v_lshlrev_b64 v[144:145], 8, v[144:145]
	s_lshl_b64 s[18:19], s[18:19], 23
	v_lshl_add_u64 v[164:165], v[144:145], 0, s[40:41]
	s_add_u32 s40, s92, s18
	s_addc_u32 s41, s93, s19
	s_add_u32 s42, s40, 0x800000
	v_lshl_add_u64 v[166:167], s[40:41], 0, v[164:165]
	s_addc_u32 s43, s41, 0
	v_lshl_add_u64 v[166:167], v[166:167], 0, s[10:11]
	v_lshl_add_u64 v[166:167], v[166:167], 0, v[136:137]
	s_mov_b32 s18, 0xff801000
	s_mov_b32 s19, -1
	s_mov_b32 s73, s71
	s_mov_b32 s74, s72
	s_mov_b64 s[46:47], s[38:39]
	s_mov_b64 s[44:45], s[36:37]
	s_waitcnt vmcnt(0)
	v_pk_add_f32 v[160:161], v[160:161], v[162:163]
	s_nop 0
	v_add_f32_e32 v160, v160, v161
	v_fmamk_f32 v160, v160, 0x3a800000, v159
	v_mul_f32_e32 v161, 0x4b800000, v160
	v_cmp_gt_f32_e32 vcc, s69, v160
	s_nop 1
	v_cndmask_b32_e32 v160, v160, v161, vcc
	v_rsq_f32_e32 v162, v160
	v_lshl_add_u64 v[160:161], s[42:43], 0, v[164:165]
	v_lshl_add_u64 v[160:161], v[160:161], 0, s[10:11]
	v_lshl_add_u64 v[160:161], v[160:161], 0, v[136:137]
	v_mul_f32_e32 v163, 0x45800000, v162
	v_cndmask_b32_e32 v162, v162, v163, vcc
	v_pk_mul_f32 v[126:127], v[126:127], v[162:163] op_sel_hi:[1,0]
	v_pk_mul_f32 v[124:125], v[124:125], v[162:163] op_sel_hi:[1,0]
	v_pk_mul_f32 v[122:123], v[122:123], v[162:163] op_sel_hi:[1,0]
	v_pk_mul_f32 v[120:121], v[120:121], v[162:163] op_sel_hi:[1,0]
	v_pk_mul_f32 v[118:119], v[118:119], v[162:163] op_sel_hi:[1,0]
	v_pk_mul_f32 v[116:117], v[116:117], v[162:163] op_sel_hi:[1,0]
	v_pk_mul_f32 v[164:165], v[114:115], v[162:163] op_sel_hi:[1,0]
	v_pk_mul_f32 v[162:163], v[112:113], v[162:163] op_sel_hi:[1,0]
	v_cvt_pk_bf16_f32 v112, v124, v125
	v_cvt_pk_bf16_f32 v113, v126, v127
	v_cvt_pk_bf16_f32 v114, v120, v121
	v_cvt_pk_bf16_f32 v115, v122, v123
	v_cvt_pk_bf16_f32 v116, v116, v117
	v_cvt_pk_bf16_f32 v117, v118, v119
	s_nop 0
	v_cvt_pk_bf16_f32 v118, v162, v163
	v_cvt_pk_bf16_f32 v119, v164, v165
	global_store_dwordx4 v[166:167], v[112:115], off
	global_store_dwordx4 v[160:161], v[116:119], off
	s_nop 1
	v_mov_b32_e32 v112, v226
	s_nop 0
	v_mov_b32_e32 v114, v227
	v_mov_b32_e32 v113, v228
	v_mov_b32_e32 v115, v229
	v_lshl_add_u64 v[116:117], v[144:145], 0, s[18:19]
	v_lshl_add_u64 v[118:119], s[40:41], 0, v[116:117]
	v_lshl_add_u64 v[118:119], v[118:119], 0, s[10:11]
	v_lshl_add_u64 v[118:119], v[118:119], 0, v[136:137]
	v_pk_add_f32 v[112:113], v[112:113], v[114:115]
	s_nop 0
	v_add_f32_e32 v112, v112, v113
	v_fmamk_f32 v112, v112, 0x3a800000, v159
	v_mul_f32_e32 v113, 0x4b800000, v112
	v_cmp_gt_f32_e32 vcc, s69, v112
	s_nop 1
	v_cndmask_b32_e32 v112, v112, v113, vcc
	v_rsq_f32_e32 v114, v112
	v_lshl_add_u64 v[112:113], s[42:43], 0, v[116:117]
	v_lshl_add_u64 v[112:113], v[112:113], 0, s[10:11]
	v_lshl_add_u64 v[112:113], v[112:113], 0, v[136:137]
	v_mul_f32_e32 v115, 0x45800000, v114
	v_cndmask_b32_e32 v114, v114, v115, vcc
	v_pk_mul_f32 v[110:111], v[110:111], v[114:115] op_sel_hi:[1,0]
	v_pk_mul_f32 v[108:109], v[108:109], v[114:115] op_sel_hi:[1,0]
	v_pk_mul_f32 v[106:107], v[106:107], v[114:115] op_sel_hi:[1,0]
	v_pk_mul_f32 v[104:105], v[104:105], v[114:115] op_sel_hi:[1,0]
	v_pk_mul_f32 v[102:103], v[102:103], v[114:115] op_sel_hi:[1,0]
	v_pk_mul_f32 v[100:101], v[100:101], v[114:115] op_sel_hi:[1,0]
	v_pk_mul_f32 v[116:117], v[98:99], v[114:115] op_sel_hi:[1,0]
	v_pk_mul_f32 v[114:115], v[96:97], v[114:115] op_sel_hi:[1,0]
	v_cvt_pk_bf16_f32 v96, v108, v109
	v_cvt_pk_bf16_f32 v97, v110, v111
	v_cvt_pk_bf16_f32 v98, v104, v105
	v_cvt_pk_bf16_f32 v99, v106, v107
	v_cvt_pk_bf16_f32 v100, v100, v101
	v_cvt_pk_bf16_f32 v101, v102, v103
	s_nop 0
	v_cvt_pk_bf16_f32 v102, v114, v115
	v_cvt_pk_bf16_f32 v103, v116, v117
	global_store_dwordx4 v[118:119], v[96:99], off
	global_store_dwordx4 v[112:113], v[100:103], off
	s_nop 1
	v_mov_b32_e32 v96, v230
	s_nop 0
	v_mov_b32_e32 v98, v231
	v_mov_b32_e32 v97, v232
	v_mov_b32_e32 v99, v233
	v_lshl_add_u64 v[100:101], v[144:145], 0, s[22:23]
	v_lshl_add_u64 v[102:103], s[40:41], 0, v[100:101]
	v_lshl_add_u64 v[102:103], v[102:103], 0, s[10:11]
	v_lshl_add_u64 v[102:103], v[102:103], 0, v[136:137]
	v_pk_add_f32 v[96:97], v[96:97], v[98:99]
	s_nop 0
	v_add_f32_e32 v96, v96, v97
	v_fmamk_f32 v96, v96, 0x3a800000, v159
	v_mul_f32_e32 v97, 0x4b800000, v96
	v_cmp_gt_f32_e32 vcc, s69, v96
	s_nop 1
	v_cndmask_b32_e32 v96, v96, v97, vcc
	v_rsq_f32_e32 v98, v96
	v_lshl_add_u64 v[96:97], s[42:43], 0, v[100:101]
	v_lshl_add_u64 v[96:97], v[96:97], 0, s[10:11]
	v_lshl_add_u64 v[96:97], v[96:97], 0, v[136:137]
	v_mul_f32_e32 v99, 0x45800000, v98
	v_cndmask_b32_e32 v98, v98, v99, vcc
	v_pk_mul_f32 v[94:95], v[94:95], v[98:99] op_sel_hi:[1,0]
	v_pk_mul_f32 v[92:93], v[92:93], v[98:99] op_sel_hi:[1,0]
	v_pk_mul_f32 v[90:91], v[90:91], v[98:99] op_sel_hi:[1,0]
	v_pk_mul_f32 v[88:89], v[88:89], v[98:99] op_sel_hi:[1,0]
	v_pk_mul_f32 v[86:87], v[86:87], v[98:99] op_sel_hi:[1,0]
	v_pk_mul_f32 v[84:85], v[84:85], v[98:99] op_sel_hi:[1,0]
	v_pk_mul_f32 v[100:101], v[82:83], v[98:99] op_sel_hi:[1,0]
	v_pk_mul_f32 v[98:99], v[80:81], v[98:99] op_sel_hi:[1,0]
	v_cvt_pk_bf16_f32 v80, v92, v93
	v_cvt_pk_bf16_f32 v81, v94, v95
	v_cvt_pk_bf16_f32 v82, v88, v89
	v_cvt_pk_bf16_f32 v83, v90, v91
	v_cvt_pk_bf16_f32 v84, v84, v85
	v_cvt_pk_bf16_f32 v85, v86, v87
	s_nop 0
	v_cvt_pk_bf16_f32 v86, v98, v99
	v_cvt_pk_bf16_f32 v87, v100, v101
	global_store_dwordx4 v[102:103], v[80:83], off
	global_store_dwordx4 v[96:97], v[84:87], off
	s_nop 1
	v_mov_b32_e32 v80, v234
	s_nop 0
	v_mov_b32_e32 v82, v235
	v_mov_b32_e32 v81, v236
	v_mov_b32_e32 v83, v237
	v_lshl_add_u64 v[84:85], v[144:145], 0, s[24:25]
	v_lshl_add_u64 v[86:87], s[40:41], 0, v[84:85]
	v_lshl_add_u64 v[86:87], v[86:87], 0, s[10:11]
	v_lshl_add_u64 v[86:87], v[86:87], 0, v[136:137]
	v_pk_add_f32 v[80:81], v[80:81], v[82:83]
	s_nop 0
	v_add_f32_e32 v80, v80, v81
	v_fmamk_f32 v80, v80, 0x3a800000, v159
	v_mul_f32_e32 v81, 0x4b800000, v80
	v_cmp_gt_f32_e32 vcc, s69, v80
	s_nop 1
	v_cndmask_b32_e32 v80, v80, v81, vcc
	v_rsq_f32_e32 v82, v80
	v_lshl_add_u64 v[80:81], s[42:43], 0, v[84:85]
	v_lshl_add_u64 v[80:81], v[80:81], 0, s[10:11]
	v_lshl_add_u64 v[80:81], v[80:81], 0, v[136:137]
	v_mul_f32_e32 v83, 0x45800000, v82
	v_cndmask_b32_e32 v82, v82, v83, vcc
	v_pk_mul_f32 v[78:79], v[78:79], v[82:83] op_sel_hi:[1,0]
	v_pk_mul_f32 v[76:77], v[76:77], v[82:83] op_sel_hi:[1,0]
	v_pk_mul_f32 v[74:75], v[74:75], v[82:83] op_sel_hi:[1,0]
	v_pk_mul_f32 v[72:73], v[72:73], v[82:83] op_sel_hi:[1,0]
	v_pk_mul_f32 v[70:71], v[70:71], v[82:83] op_sel_hi:[1,0]
	v_pk_mul_f32 v[68:69], v[68:69], v[82:83] op_sel_hi:[1,0]
	v_pk_mul_f32 v[84:85], v[66:67], v[82:83] op_sel_hi:[1,0]
	v_pk_mul_f32 v[82:83], v[64:65], v[82:83] op_sel_hi:[1,0]
	v_cvt_pk_bf16_f32 v64, v76, v77
	v_cvt_pk_bf16_f32 v65, v78, v79
	v_cvt_pk_bf16_f32 v66, v72, v73
	v_cvt_pk_bf16_f32 v67, v74, v75
	v_cvt_pk_bf16_f32 v68, v68, v69
	v_cvt_pk_bf16_f32 v69, v70, v71
	s_nop 0
	v_cvt_pk_bf16_f32 v70, v82, v83
	v_cvt_pk_bf16_f32 v71, v84, v85
	global_store_dwordx4 v[86:87], v[64:67], off
	global_store_dwordx4 v[80:81], v[68:71], off
	s_nop 1
	v_mov_b32_e32 v64, v238
	s_nop 0
	v_mov_b32_e32 v66, v239
	v_mov_b32_e32 v65, v240
	v_mov_b32_e32 v67, v241
	v_lshl_add_u64 v[68:69], v[144:145], 0, s[26:27]
	v_lshl_add_u64 v[70:71], s[40:41], 0, v[68:69]
	v_lshl_add_u64 v[70:71], v[70:71], 0, s[10:11]
	v_lshl_add_u64 v[70:71], v[70:71], 0, v[136:137]
	v_pk_add_f32 v[64:65], v[64:65], v[66:67]
	s_nop 0
	v_add_f32_e32 v64, v64, v65
	v_fmamk_f32 v64, v64, 0x3a800000, v159
	v_mul_f32_e32 v65, 0x4b800000, v64
	v_cmp_gt_f32_e32 vcc, s69, v64
	s_nop 1
	v_cndmask_b32_e32 v64, v64, v65, vcc
	v_rsq_f32_e32 v66, v64
	v_lshl_add_u64 v[64:65], s[42:43], 0, v[68:69]
	v_lshl_add_u64 v[64:65], v[64:65], 0, s[10:11]
	v_lshl_add_u64 v[64:65], v[64:65], 0, v[136:137]
	v_mul_f32_e32 v67, 0x45800000, v66
	v_cndmask_b32_e32 v66, v66, v67, vcc
	v_pk_mul_f32 v[62:63], v[62:63], v[66:67] op_sel_hi:[1,0]
	v_pk_mul_f32 v[60:61], v[60:61], v[66:67] op_sel_hi:[1,0]
	v_pk_mul_f32 v[58:59], v[58:59], v[66:67] op_sel_hi:[1,0]
	v_pk_mul_f32 v[56:57], v[56:57], v[66:67] op_sel_hi:[1,0]
	v_pk_mul_f32 v[54:55], v[54:55], v[66:67] op_sel_hi:[1,0]
	v_pk_mul_f32 v[52:53], v[52:53], v[66:67] op_sel_hi:[1,0]
	v_pk_mul_f32 v[68:69], v[50:51], v[66:67] op_sel_hi:[1,0]
	v_pk_mul_f32 v[66:67], v[48:49], v[66:67] op_sel_hi:[1,0]
	v_cvt_pk_bf16_f32 v48, v60, v61
	v_cvt_pk_bf16_f32 v49, v62, v63
	v_cvt_pk_bf16_f32 v50, v56, v57
	v_cvt_pk_bf16_f32 v51, v58, v59
	v_cvt_pk_bf16_f32 v52, v52, v53
	v_cvt_pk_bf16_f32 v53, v54, v55
	s_nop 0
	v_cvt_pk_bf16_f32 v54, v66, v67
	v_cvt_pk_bf16_f32 v55, v68, v69
	global_store_dwordx4 v[70:71], v[48:51], off
	global_store_dwordx4 v[64:65], v[52:55], off
	s_nop 1
	v_mov_b32_e32 v48, v242
	s_nop 0
	v_mov_b32_e32 v50, v243
	v_mov_b32_e32 v49, v244
	v_mov_b32_e32 v51, v245
	v_lshl_add_u64 v[52:53], v[144:145], 0, s[28:29]
	v_lshl_add_u64 v[54:55], s[40:41], 0, v[52:53]
	v_lshl_add_u64 v[54:55], v[54:55], 0, s[10:11]
	v_lshl_add_u64 v[54:55], v[54:55], 0, v[136:137]
	v_pk_add_f32 v[48:49], v[48:49], v[50:51]
	s_nop 0
	v_add_f32_e32 v48, v48, v49
	v_fmamk_f32 v48, v48, 0x3a800000, v159
	v_mul_f32_e32 v49, 0x4b800000, v48
	v_cmp_gt_f32_e32 vcc, s69, v48
	s_nop 1
	v_cndmask_b32_e32 v48, v48, v49, vcc
	v_rsq_f32_e32 v50, v48
	v_lshl_add_u64 v[48:49], s[42:43], 0, v[52:53]
	v_lshl_add_u64 v[48:49], v[48:49], 0, s[10:11]
	v_lshl_add_u64 v[48:49], v[48:49], 0, v[136:137]
	v_mul_f32_e32 v51, 0x45800000, v50
	v_cndmask_b32_e32 v50, v50, v51, vcc
	v_pk_mul_f32 v[46:47], v[46:47], v[50:51] op_sel_hi:[1,0]
	v_pk_mul_f32 v[44:45], v[44:45], v[50:51] op_sel_hi:[1,0]
	v_pk_mul_f32 v[42:43], v[42:43], v[50:51] op_sel_hi:[1,0]
	v_pk_mul_f32 v[40:41], v[40:41], v[50:51] op_sel_hi:[1,0]
	v_pk_mul_f32 v[38:39], v[38:39], v[50:51] op_sel_hi:[1,0]
	v_pk_mul_f32 v[36:37], v[36:37], v[50:51] op_sel_hi:[1,0]
	v_pk_mul_f32 v[52:53], v[34:35], v[50:51] op_sel_hi:[1,0]
	v_pk_mul_f32 v[50:51], v[32:33], v[50:51] op_sel_hi:[1,0]
	v_cvt_pk_bf16_f32 v32, v44, v45
	v_cvt_pk_bf16_f32 v33, v46, v47
	v_cvt_pk_bf16_f32 v34, v40, v41
	v_cvt_pk_bf16_f32 v35, v42, v43
	v_cvt_pk_bf16_f32 v36, v36, v37
	v_cvt_pk_bf16_f32 v37, v38, v39
	s_nop 0
	v_cvt_pk_bf16_f32 v38, v50, v51
	v_cvt_pk_bf16_f32 v39, v52, v53
	global_store_dwordx4 v[54:55], v[32:35], off
	global_store_dwordx4 v[48:49], v[36:39], off
	s_nop 1
	v_mov_b32_e32 v32, v246
	s_nop 0
	v_mov_b32_e32 v34, v247
	v_mov_b32_e32 v33, v248
	v_mov_b32_e32 v35, v249
	v_lshl_add_u64 v[36:37], v[144:145], 0, s[30:31]
	v_lshl_add_u64 v[38:39], s[40:41], 0, v[36:37]
	v_lshl_add_u64 v[38:39], v[38:39], 0, s[10:11]
	v_lshl_add_u64 v[38:39], v[38:39], 0, v[136:137]
	v_pk_add_f32 v[32:33], v[32:33], v[34:35]
	s_nop 0
	v_add_f32_e32 v32, v32, v33
	v_fmamk_f32 v32, v32, 0x3a800000, v159
	v_mul_f32_e32 v33, 0x4b800000, v32
	v_cmp_gt_f32_e32 vcc, s69, v32
	s_nop 1
	v_cndmask_b32_e32 v32, v32, v33, vcc
	v_rsq_f32_e32 v34, v32
	v_lshl_add_u64 v[32:33], s[42:43], 0, v[36:37]
	v_lshl_add_u64 v[32:33], v[32:33], 0, s[10:11]
	v_lshl_add_u64 v[32:33], v[32:33], 0, v[136:137]
	v_mul_f32_e32 v35, 0x45800000, v34
	v_cndmask_b32_e32 v34, v34, v35, vcc
	v_pk_mul_f32 v[30:31], v[30:31], v[34:35] op_sel_hi:[1,0]
	v_pk_mul_f32 v[28:29], v[28:29], v[34:35] op_sel_hi:[1,0]
	v_pk_mul_f32 v[26:27], v[26:27], v[34:35] op_sel_hi:[1,0]
	v_pk_mul_f32 v[24:25], v[24:25], v[34:35] op_sel_hi:[1,0]
	v_pk_mul_f32 v[22:23], v[22:23], v[34:35] op_sel_hi:[1,0]
	v_pk_mul_f32 v[20:21], v[20:21], v[34:35] op_sel_hi:[1,0]
	v_pk_mul_f32 v[36:37], v[18:19], v[34:35] op_sel_hi:[1,0]
	v_pk_mul_f32 v[34:35], v[16:17], v[34:35] op_sel_hi:[1,0]
	v_cvt_pk_bf16_f32 v16, v28, v29
	v_cvt_pk_bf16_f32 v17, v30, v31
	v_cvt_pk_bf16_f32 v18, v24, v25
	v_cvt_pk_bf16_f32 v19, v26, v27
	v_cvt_pk_bf16_f32 v20, v20, v21
	v_cvt_pk_bf16_f32 v21, v22, v23
	s_nop 0
	v_cvt_pk_bf16_f32 v22, v34, v35
	v_cvt_pk_bf16_f32 v23, v36, v37
	global_store_dwordx4 v[38:39], v[16:19], off
	global_store_dwordx4 v[32:33], v[20:23], off
	s_nop 1
	v_mov_b32_e32 v16, v250
	s_nop 0
	v_mov_b32_e32 v18, v251
	v_mov_b32_e32 v17, v252
	v_mov_b32_e32 v19, v253
	s_and_b64 vcc, exec, s[4:5]
	v_lshl_add_u64 v[20:21], v[144:145], 0, s[34:35]
	v_lshl_add_u64 v[22:23], s[40:41], 0, v[20:21]
	v_lshl_add_u64 v[22:23], v[22:23], 0, s[10:11]
	v_lshl_add_u64 v[22:23], v[22:23], 0, v[136:137]
	v_pk_add_f32 v[16:17], v[16:17], v[18:19]
	s_nop 0
	v_add_f32_e32 v16, v16, v17
	v_fmamk_f32 v16, v16, 0x3a800000, v159
	v_mul_f32_e32 v17, 0x4b800000, v16
	v_cmp_gt_f32_e64 s[4:5], s69, v16
	s_nop 1
	v_cndmask_b32_e64 v16, v16, v17, s[4:5]
	v_rsq_f32_e32 v18, v16
	v_lshl_add_u64 v[16:17], s[42:43], 0, v[20:21]
	v_lshl_add_u64 v[16:17], v[16:17], 0, s[10:11]
	v_lshl_add_u64 v[16:17], v[16:17], 0, v[136:137]
	v_mul_f32_e32 v19, 0x45800000, v18
	v_cndmask_b32_e64 v18, v18, v19, s[4:5]
	v_pk_mul_f32 v[14:15], v[14:15], v[18:19] op_sel_hi:[1,0]
	v_pk_mul_f32 v[12:13], v[12:13], v[18:19] op_sel_hi:[1,0]
	v_pk_mul_f32 v[10:11], v[10:11], v[18:19] op_sel_hi:[1,0]
	v_pk_mul_f32 v[8:9], v[8:9], v[18:19] op_sel_hi:[1,0]
	v_pk_mul_f32 v[6:7], v[6:7], v[18:19] op_sel_hi:[1,0]
	v_pk_mul_f32 v[4:5], v[4:5], v[18:19] op_sel_hi:[1,0]
	v_pk_mul_f32 v[20:21], v[2:3], v[18:19] op_sel_hi:[1,0]
	v_pk_mul_f32 v[18:19], v[0:1], v[18:19] op_sel_hi:[1,0]
	v_cvt_pk_bf16_f32 v0, v12, v13
	v_cvt_pk_bf16_f32 v1, v14, v15
	v_cvt_pk_bf16_f32 v2, v8, v9
	v_cvt_pk_bf16_f32 v3, v10, v11
	v_cvt_pk_bf16_f32 v4, v4, v5
	v_cvt_pk_bf16_f32 v5, v6, v7
	s_nop 0
	v_cvt_pk_bf16_f32 v6, v18, v19
	v_cvt_pk_bf16_f32 v7, v20, v21
	global_store_dwordx4 v[22:23], v[0:3], off
	global_store_dwordx4 v[16:17], v[4:7], off
	s_cbranch_vccz .LBB0_664
	s_waitcnt vmcnt(0)
	s_cmpk_gt_u32 s33, 0xff
	s_cbranch_scc1 .LBB0_671
	s_barrier

.LBB0_926:
	s_add_u32 s38, s36, 0xfffc0080
	s_addc_u32 s39, s37, -1
	s_add_i32 s78, 0, 0x10000
	v_add_u32_e32 v146, s78, v159
	ds_read_b128 v[138:141], v146
	ds_read_b128 v[142:145], v146 offset:1024
	ds_read_b128 v[154:157], v146 offset:2048
	ds_read_b128 v[162:165], v146 offset:3072
	s_cmp_eq_u32 s77, 12
	s_cselect_b32 s41, s9, s39
	s_cselect_b32 s40, s8, s38
	s_cselect_b32 s39, s35, s76
	s_cselect_b32 s38, s34, s75
	v_lshl_add_u64 v[146:147], s[36:37], 0, v[134:135]
	s_add_i32 m0, s64, 0xc000
	ds_read_b128 v[166:169], v161
	ds_read_b128 v[170:173], v161 offset:1024
	ds_read_b128 v[178:181], v161 offset:2048
	ds_read_b128 v[182:185], v161 offset:3072
	ds_read_b128 v[186:189], v161 offset:4096
	ds_read_b128 v[190:193], v161 offset:5120
	ds_read_b128 v[200:203], v161 offset:6144
	ds_read_b128 v[204:207], v161 offset:7168
	global_load_lds_dwordx4 v[146:147], off
	v_lshl_add_u64 v[146:147], s[36:37], 0, v[136:137]
	s_add_i32 m0, s64, 0xe000
	s_nop 0
	global_load_lds_dwordx4 v[146:147], off
	s_waitcnt lgkmcnt(8)
	s_barrier
	s_waitcnt lgkmcnt(0)
	s_setprio 1
	s_waitcnt lgkmcnt(0)
	v_mfma_f32_16x16x32_bf16 v[124:127], v[138:141], v[166:169], v[124:127]
	v_mfma_f32_16x16x32_bf16 v[120:123], v[154:157], v[166:169], v[120:123]
	v_mfma_f32_16x16x32_bf16 v[108:111], v[138:141], v[178:181], v[108:111]
	v_mfma_f32_16x16x32_bf16 v[104:107], v[154:157], v[178:181], v[104:107]
	v_mfma_f32_16x16x32_bf16 v[92:95], v[138:141], v[186:189], v[92:95]
	v_mfma_f32_16x16x32_bf16 v[88:91], v[154:157], v[186:189], v[88:91]
	v_mfma_f32_16x16x32_bf16 v[76:79], v[138:141], v[200:203], v[76:79]
	v_mfma_f32_16x16x32_bf16 v[72:75], v[154:157], v[200:203], v[72:75]
	v_mfma_f32_16x16x32_bf16 v[124:127], v[142:145], v[170:173], v[124:127]
	v_mfma_f32_16x16x32_bf16 v[120:123], v[162:165], v[170:173], v[120:123]
	v_mfma_f32_16x16x32_bf16 v[108:111], v[142:145], v[182:185], v[108:111]
	v_mfma_f32_16x16x32_bf16 v[104:107], v[162:165], v[182:185], v[104:107]
	v_mfma_f32_16x16x32_bf16 v[92:95], v[142:145], v[190:193], v[92:95]
	v_mfma_f32_16x16x32_bf16 v[88:91], v[162:165], v[190:193], v[88:91]
	v_mfma_f32_16x16x32_bf16 v[76:79], v[142:145], v[204:207], v[76:79]
	v_mfma_f32_16x16x32_bf16 v[72:75], v[162:165], v[204:207], v[72:75]
	s_setprio 0
	s_barrier
	s_add_i32 s80, 0, 0x14000
	v_add_u32_e32 v146, s80, v159
	s_add_i32 s78, s78, s45
	ds_read_b128 v[208:211], v146
	ds_read_b128 v[212:215], v146 offset:1024
	ds_read_b128 v[216:219], v146 offset:2048
	ds_read_b128 v[220:223], v146 offset:3072
	v_lshl_add_u64 v[146:147], s[38:39], 0, v[148:149]
	s_mov_b32 m0, s78
	v_lshl_add_u64 v[174:175], s[38:39], 0, v[128:129]
	global_load_lds_dwordx4 v[146:147], off
	s_add_i32 m0, s78, 0x2000
	s_nop 0
	global_load_lds_dwordx4 v[174:175], off
	s_barrier
	s_waitcnt lgkmcnt(0)
	s_setprio 1
	s_waitcnt lgkmcnt(0)
	v_mfma_f32_16x16x32_bf16 v[116:119], v[208:211], v[166:169], v[116:119]
	v_mfma_f32_16x16x32_bf16 v[112:115], v[216:219], v[166:169], v[112:115]
	v_mfma_f32_16x16x32_bf16 v[100:103], v[208:211], v[178:181], v[100:103]
	v_mfma_f32_16x16x32_bf16 v[96:99], v[216:219], v[178:181], v[96:99]
	v_mfma_f32_16x16x32_bf16 v[84:87], v[208:211], v[186:189], v[84:87]
	v_mfma_f32_16x16x32_bf16 v[80:83], v[216:219], v[186:189], v[80:83]
	v_mfma_f32_16x16x32_bf16 v[68:71], v[208:211], v[200:203], v[68:71]
	v_mfma_f32_16x16x32_bf16 v[64:67], v[216:219], v[200:203], v[64:67]
	v_mfma_f32_16x16x32_bf16 v[116:119], v[212:215], v[170:173], v[116:119]
	v_mfma_f32_16x16x32_bf16 v[112:115], v[220:223], v[170:173], v[112:115]
	v_mfma_f32_16x16x32_bf16 v[100:103], v[212:215], v[182:185], v[100:103]
	v_mfma_f32_16x16x32_bf16 v[96:99], v[220:223], v[182:185], v[96:99]
	v_mfma_f32_16x16x32_bf16 v[84:87], v[212:215], v[190:193], v[84:87]
	v_mfma_f32_16x16x32_bf16 v[80:83], v[220:223], v[190:193], v[80:83]
	v_mfma_f32_16x16x32_bf16 v[68:71], v[212:215], v[204:207], v[68:71]
	v_mfma_f32_16x16x32_bf16 v[64:67], v[220:223], v[204:207], v[64:67]
	s_setprio 0
	s_mov_b32 m0, s64
	v_lshl_add_u64 v[194:195], s[40:41], 0, v[132:133]
	s_barrier
	ds_read_b128 v[166:169], v161 offset:16384
	ds_read_b128 v[170:173], v161 offset:17408
	ds_read_b128 v[178:181], v161 offset:18432
	ds_read_b128 v[182:185], v161 offset:19456
	ds_read_b128 v[186:189], v161 offset:20480
	ds_read_b128 v[190:193], v161 offset:21504
	ds_read_b128 v[200:203], v161 offset:22528
	ds_read_b128 v[204:207], v161 offset:23552
	global_load_lds_dwordx4 v[194:195], off
	v_lshl_add_u64 v[224:225], s[40:41], 0, v[130:131]
	s_mov_b32 m0, s65
	s_nop 0
	global_load_lds_dwordx4 v[224:225], off
	s_barrier
	s_waitcnt lgkmcnt(0)
	s_setprio 1
	s_waitcnt lgkmcnt(0)
	v_mfma_f32_16x16x32_bf16 v[60:63], v[138:141], v[166:169], v[60:63]
	v_mfma_f32_16x16x32_bf16 v[56:59], v[154:157], v[166:169], v[56:59]
	v_mfma_f32_16x16x32_bf16 v[44:47], v[138:141], v[178:181], v[44:47]
	v_mfma_f32_16x16x32_bf16 v[40:43], v[154:157], v[178:181], v[40:43]
	v_mfma_f32_16x16x32_bf16 v[28:31], v[138:141], v[186:189], v[28:31]
	v_mfma_f32_16x16x32_bf16 v[24:27], v[154:157], v[186:189], v[24:27]
	v_mfma_f32_16x16x32_bf16 v[12:15], v[138:141], v[200:203], v[12:15]
	v_mfma_f32_16x16x32_bf16 v[8:11], v[154:157], v[200:203], v[8:11]
	v_mfma_f32_16x16x32_bf16 v[60:63], v[142:145], v[170:173], v[60:63]
	v_mfma_f32_16x16x32_bf16 v[56:59], v[162:165], v[170:173], v[56:59]
	v_mfma_f32_16x16x32_bf16 v[44:47], v[142:145], v[182:185], v[44:47]
	v_mfma_f32_16x16x32_bf16 v[40:43], v[162:165], v[182:185], v[40:43]
	v_mfma_f32_16x16x32_bf16 v[28:31], v[142:145], v[190:193], v[28:31]
	v_mfma_f32_16x16x32_bf16 v[24:27], v[162:165], v[190:193], v[24:27]
	v_mfma_f32_16x16x32_bf16 v[12:15], v[142:145], v[204:207], v[12:15]
	v_mfma_f32_16x16x32_bf16 v[8:11], v[162:165], v[204:207], v[8:11]
	s_setprio 0
	s_barrier
	s_add_u32 s78, s38, 0x40000
	s_addc_u32 s79, s39, 0
	s_add_i32 s80, s80, s45
	v_lshl_add_u64 v[138:139], s[78:79], 0, v[148:149]
	s_mov_b32 m0, s80
	s_nop 0
	global_load_lds_dwordx4 v[138:139], off
	v_lshl_add_u64 v[138:139], s[78:79], 0, v[128:129]
	s_add_i32 m0, s80, 0x2000
	s_nop 0
	global_load_lds_dwordx4 v[138:139], off
	s_waitcnt vmcnt(6)
	s_barrier
	s_setprio 1
	v_mfma_f32_16x16x32_bf16 v[52:55], v[208:211], v[166:169], v[52:55]
	v_mfma_f32_16x16x32_bf16 v[48:51], v[216:219], v[166:169], v[48:51]
	v_mfma_f32_16x16x32_bf16 v[36:39], v[208:211], v[178:181], v[36:39]
	v_mfma_f32_16x16x32_bf16 v[32:35], v[216:219], v[178:181], v[32:35]
	v_mfma_f32_16x16x32_bf16 v[20:23], v[208:211], v[186:189], v[20:23]
	v_mfma_f32_16x16x32_bf16 v[16:19], v[216:219], v[186:189], v[16:19]
	v_mfma_f32_16x16x32_bf16 v[4:7], v[208:211], v[200:203], v[4:7]
	v_mfma_f32_16x16x32_bf16 v[0:3], v[216:219], v[200:203], v[0:3]
	v_mfma_f32_16x16x32_bf16 v[52:55], v[212:215], v[170:173], v[52:55]
	v_mfma_f32_16x16x32_bf16 v[48:51], v[220:223], v[170:173], v[48:51]
	v_mfma_f32_16x16x32_bf16 v[36:39], v[212:215], v[182:185], v[36:39]
	v_mfma_f32_16x16x32_bf16 v[32:35], v[220:223], v[182:185], v[32:35]
	v_mfma_f32_16x16x32_bf16 v[20:23], v[212:215], v[190:193], v[20:23]
	v_mfma_f32_16x16x32_bf16 v[16:19], v[220:223], v[190:193], v[16:19]
	v_mfma_f32_16x16x32_bf16 v[4:7], v[212:215], v[204:207], v[4:7]
	v_mfma_f32_16x16x32_bf16 v[0:3], v[220:223], v[204:207], v[0:3]
	s_setprio 0
	s_add_i32 s78, 0, 0x18000
	v_add_u32_e32 v162, s78, v159
	s_barrier
	ds_read_b128 v[138:141], v162
	ds_read_b128 v[142:145], v162 offset:1024
	ds_read_b128 v[154:157], v162 offset:2048
	ds_read_b128 v[162:165], v162 offset:3072
	s_add_u32 s40, s40, 0x40000
	s_addc_u32 s41, s41, 0
	s_mov_b32 m0, s66
	v_lshl_add_u64 v[208:209], s[40:41], 0, v[132:133]
	ds_read_b128 v[166:169], v161 offset:32768
	ds_read_b128 v[170:173], v161 offset:33792
	ds_read_b128 v[178:181], v161 offset:34816
	ds_read_b128 v[182:185], v161 offset:35840
	ds_read_b128 v[186:189], v161 offset:36864
	ds_read_b128 v[190:193], v161 offset:37888
	ds_read_b128 v[200:203], v161 offset:38912
	ds_read_b128 v[204:207], v161 offset:39936
	global_load_lds_dwordx4 v[208:209], off
	v_lshl_add_u64 v[208:209], s[40:41], 0, v[130:131]
	s_mov_b32 m0, s67
	s_nop 0
	global_load_lds_dwordx4 v[208:209], off
	s_waitcnt lgkmcnt(8)
	s_barrier
	s_waitcnt lgkmcnt(0)
	s_setprio 1
	s_waitcnt lgkmcnt(0)
	v_mfma_f32_16x16x32_bf16 v[124:127], v[138:141], v[166:169], v[124:127]
	v_mfma_f32_16x16x32_bf16 v[120:123], v[154:157], v[166:169], v[120:123]
	v_mfma_f32_16x16x32_bf16 v[108:111], v[138:141], v[178:181], v[108:111]
	v_mfma_f32_16x16x32_bf16 v[104:107], v[154:157], v[178:181], v[104:107]
	v_mfma_f32_16x16x32_bf16 v[92:95], v[138:141], v[186:189], v[92:95]
	v_mfma_f32_16x16x32_bf16 v[88:91], v[154:157], v[186:189], v[88:91]
	v_mfma_f32_16x16x32_bf16 v[76:79], v[138:141], v[200:203], v[76:79]
	v_mfma_f32_16x16x32_bf16 v[72:75], v[154:157], v[200:203], v[72:75]
	v_mfma_f32_16x16x32_bf16 v[124:127], v[142:145], v[170:173], v[124:127]
	v_mfma_f32_16x16x32_bf16 v[120:123], v[162:165], v[170:173], v[120:123]
	v_mfma_f32_16x16x32_bf16 v[108:111], v[142:145], v[182:185], v[108:111]
	v_mfma_f32_16x16x32_bf16 v[104:107], v[162:165], v[182:185], v[104:107]
	v_mfma_f32_16x16x32_bf16 v[92:95], v[142:145], v[190:193], v[92:95]
	v_mfma_f32_16x16x32_bf16 v[88:91], v[162:165], v[190:193], v[88:91]
	v_mfma_f32_16x16x32_bf16 v[76:79], v[142:145], v[204:207], v[76:79]
	v_mfma_f32_16x16x32_bf16 v[72:75], v[162:165], v[204:207], v[72:75]
	s_setprio 0
	s_barrier
	s_add_i32 s40, 0, 0x1c000
	s_add_i32 s41, s78, s45
	v_add_u32_e32 v199, s40, v159
	v_lshl_add_u64 v[146:147], v[146:147], 0, s[26:27]
	s_mov_b32 m0, s41
	ds_read_b128 v[208:211], v199
	ds_read_b128 v[212:215], v199 offset:1024
	ds_read_b128 v[216:219], v199 offset:2048
	ds_read_b128 v[220:223], v199 offset:3072
	global_load_lds_dwordx4 v[146:147], off
	v_lshl_add_u64 v[146:147], v[174:175], 0, s[26:27]
	s_add_i32 m0, s41, 0x2000
	s_nop 0
	global_load_lds_dwordx4 v[146:147], off
	s_barrier
	s_waitcnt lgkmcnt(0)
	s_setprio 1
	s_waitcnt lgkmcnt(0)
	v_mfma_f32_16x16x32_bf16 v[116:119], v[208:211], v[166:169], v[116:119]
	v_mfma_f32_16x16x32_bf16 v[112:115], v[216:219], v[166:169], v[112:115]
	v_mfma_f32_16x16x32_bf16 v[100:103], v[208:211], v[178:181], v[100:103]
	v_mfma_f32_16x16x32_bf16 v[96:99], v[216:219], v[178:181], v[96:99]
	v_mfma_f32_16x16x32_bf16 v[84:87], v[208:211], v[186:189], v[84:87]
	v_mfma_f32_16x16x32_bf16 v[80:83], v[216:219], v[186:189], v[80:83]
	v_mfma_f32_16x16x32_bf16 v[68:71], v[208:211], v[200:203], v[68:71]
	v_mfma_f32_16x16x32_bf16 v[64:67], v[216:219], v[200:203], v[64:67]
	v_mfma_f32_16x16x32_bf16 v[116:119], v[212:215], v[170:173], v[116:119]
	v_mfma_f32_16x16x32_bf16 v[112:115], v[220:223], v[170:173], v[112:115]
	v_mfma_f32_16x16x32_bf16 v[100:103], v[212:215], v[182:185], v[100:103]
	v_mfma_f32_16x16x32_bf16 v[96:99], v[220:223], v[182:185], v[96:99]
	v_mfma_f32_16x16x32_bf16 v[84:87], v[212:215], v[190:193], v[84:87]
	v_mfma_f32_16x16x32_bf16 v[80:83], v[220:223], v[190:193], v[80:83]
	v_mfma_f32_16x16x32_bf16 v[68:71], v[212:215], v[204:207], v[68:71]
	v_mfma_f32_16x16x32_bf16 v[64:67], v[220:223], v[204:207], v[64:67]
	s_setprio 0
	s_mov_b32 m0, s68
	v_lshl_add_u64 v[146:147], v[194:195], 0, s[26:27]
	s_barrier
	ds_read_b128 v[166:169], v161 offset:49152
	ds_read_b128 v[170:173], v161 offset:50176
	ds_read_b128 v[178:181], v161 offset:51200
	ds_read_b128 v[182:185], v161 offset:52224
	ds_read_b128 v[186:189], v161 offset:53248
	ds_read_b128 v[190:193], v161 offset:54272
	ds_read_b128 v[200:203], v161 offset:55296
	ds_read_b128 v[204:207], v161 offset:56320
	global_load_lds_dwordx4 v[146:147], off
	v_lshl_add_u64 v[146:147], v[224:225], 0, s[26:27]
	s_mov_b32 m0, s69
	s_nop 0
	global_load_lds_dwordx4 v[146:147], off
	s_barrier
	s_waitcnt lgkmcnt(0)
	s_setprio 1
	s_waitcnt lgkmcnt(0)
	v_mfma_f32_16x16x32_bf16 v[60:63], v[138:141], v[166:169], v[60:63]
	v_mfma_f32_16x16x32_bf16 v[56:59], v[154:157], v[166:169], v[56:59]
	v_mfma_f32_16x16x32_bf16 v[44:47], v[138:141], v[178:181], v[44:47]
	v_mfma_f32_16x16x32_bf16 v[40:43], v[154:157], v[178:181], v[40:43]
	v_mfma_f32_16x16x32_bf16 v[28:31], v[138:141], v[186:189], v[28:31]
	v_mfma_f32_16x16x32_bf16 v[24:27], v[154:157], v[186:189], v[24:27]
	v_mfma_f32_16x16x32_bf16 v[12:15], v[138:141], v[200:203], v[12:15]
	v_mfma_f32_16x16x32_bf16 v[8:11], v[154:157], v[200:203], v[8:11]
	v_mfma_f32_16x16x32_bf16 v[60:63], v[142:145], v[170:173], v[60:63]
	v_mfma_f32_16x16x32_bf16 v[56:59], v[162:165], v[170:173], v[56:59]
	v_mfma_f32_16x16x32_bf16 v[44:47], v[142:145], v[182:185], v[44:47]
	v_mfma_f32_16x16x32_bf16 v[40:43], v[162:165], v[182:185], v[40:43]
	v_mfma_f32_16x16x32_bf16 v[28:31], v[142:145], v[190:193], v[28:31]
	v_mfma_f32_16x16x32_bf16 v[24:27], v[162:165], v[190:193], v[24:27]
	v_mfma_f32_16x16x32_bf16 v[12:15], v[142:145], v[204:207], v[12:15]
	v_mfma_f32_16x16x32_bf16 v[8:11], v[162:165], v[204:207], v[8:11]
	s_setprio 0
	s_barrier
	s_add_u32 s38, s38, 0x40080
	s_addc_u32 s39, s39, 0
	s_add_i32 s40, s40, s45
	v_lshl_add_u64 v[138:139], s[38:39], 0, v[148:149]
	s_mov_b32 m0, s40
	s_nop 0
	global_load_lds_dwordx4 v[138:139], off
	v_lshl_add_u64 v[138:139], s[38:39], 0, v[128:129]
	s_add_i32 m0, s40, 0x2000
	s_nop 0
	global_load_lds_dwordx4 v[138:139], off
	s_waitcnt vmcnt(6)
	s_barrier
	s_setprio 1
	v_mfma_f32_16x16x32_bf16 v[52:55], v[208:211], v[166:169], v[52:55]
	v_mfma_f32_16x16x32_bf16 v[48:51], v[216:219], v[166:169], v[48:51]
	v_mfma_f32_16x16x32_bf16 v[36:39], v[208:211], v[178:181], v[36:39]
	v_mfma_f32_16x16x32_bf16 v[32:35], v[216:219], v[178:181], v[32:35]
	v_mfma_f32_16x16x32_bf16 v[20:23], v[208:211], v[186:189], v[20:23]
	v_mfma_f32_16x16x32_bf16 v[16:19], v[216:219], v[186:189], v[16:19]
	v_mfma_f32_16x16x32_bf16 v[4:7], v[208:211], v[200:203], v[4:7]
	v_mfma_f32_16x16x32_bf16 v[0:3], v[216:219], v[200:203], v[0:3]
	v_mfma_f32_16x16x32_bf16 v[52:55], v[212:215], v[170:173], v[52:55]
	v_mfma_f32_16x16x32_bf16 v[48:51], v[220:223], v[170:173], v[48:51]
	v_mfma_f32_16x16x32_bf16 v[36:39], v[212:215], v[182:185], v[36:39]
	v_mfma_f32_16x16x32_bf16 v[32:35], v[220:223], v[182:185], v[32:35]
	v_mfma_f32_16x16x32_bf16 v[20:23], v[212:215], v[190:193], v[20:23]
	v_mfma_f32_16x16x32_bf16 v[16:19], v[220:223], v[190:193], v[16:19]
	v_mfma_f32_16x16x32_bf16 v[4:7], v[212:215], v[204:207], v[4:7]
	v_mfma_f32_16x16x32_bf16 v[0:3], v[220:223], v[204:207], v[0:3]
	s_setprio 0
	s_add_i32 s77, s77, 2
	s_add_u32 s36, s36, 0x100
	s_addc_u32 s37, s37, 0
	s_add_u32 s75, s75, 0x100
	s_addc_u32 s76, s76, 0
	s_cmp_gt_u32 s77, 13
	s_barrier
	s_cbranch_scc0 .LBB0_926
	v_add_u32_e32 v138, s74, v158
	v_ashrrev_i32_e32 v139, 31, v138
	v_lshl_add_u64 v[142:143], v[138:139], 2, s[10:11]
	v_add_co_u32_e32 v144, vcc, 0x40000, v142
	v_subrev_u32_e32 v138, s70, v138
	s_nop 0
	v_addc_co_u32_e32 v145, vcc, 0, v143, vcc
	v_add_co_u32_e32 v146, vcc, 0x80000, v142
	v_ashrrev_i32_e32 v139, 31, v138
	s_nop 0
	v_addc_co_u32_e32 v147, vcc, 0, v143, vcc
	v_add_co_u32_e32 v154, vcc, 0xc0000, v142
	v_add_u32_e32 v140, s33, v160
	s_nop 0
	v_addc_co_u32_e32 v155, vcc, 0, v143, vcc
	global_load_dword v156, v[142:143], off
	global_load_dword v162, v[144:145], off
	global_load_dword v157, v[146:147], off
	global_load_dword v163, v[154:155], off
	global_load_dword v226, v[142:143], off offset:64
	global_load_dword v227, v[144:145], off offset:64
	global_load_dword v228, v[146:147], off offset:64
	global_load_dword v229, v[154:155], off offset:64
	global_load_dword v230, v[142:143], off offset:128
	global_load_dword v231, v[144:145], off offset:128
	global_load_dword v232, v[146:147], off offset:128
	global_load_dword v233, v[154:155], off offset:128
	global_load_dword v234, v[142:143], off offset:192
	global_load_dword v235, v[144:145], off offset:192
	global_load_dword v236, v[146:147], off offset:192
	global_load_dword v237, v[154:155], off offset:192
	global_load_dword v238, v[142:143], off offset:512
	global_load_dword v239, v[144:145], off offset:512
	global_load_dword v240, v[146:147], off offset:512
	global_load_dword v241, v[154:155], off offset:512
	global_load_dword v242, v[142:143], off offset:576
	global_load_dword v243, v[144:145], off offset:576
	global_load_dword v244, v[146:147], off offset:576
	global_load_dword v245, v[154:155], off offset:576
	global_load_dword v246, v[142:143], off offset:640
	global_load_dword v247, v[144:145], off offset:640
	global_load_dword v248, v[146:147], off offset:640
	global_load_dword v249, v[154:155], off offset:640
	global_load_dword v250, v[142:143], off offset:704
	global_load_dword v251, v[144:145], off offset:704
	global_load_dword v252, v[146:147], off offset:704
	global_load_dword v253, v[154:155], off offset:704
	v_ashrrev_i32_e32 v141, 31, v140
	v_lshlrev_b64 v[140:141], 1, v[140:141]
	s_mov_b32 s33, s72
	s_mov_b32 s74, s73
	s_mov_b64 s[38:39], s[34:35]
	s_mov_b64 s[36:37], s[8:9]
	s_waitcnt vmcnt(0)
	v_pk_add_f32 v[156:157], v[156:157], v[162:163]
	s_nop 0
	v_add_f32_e32 v156, v156, v157
	v_fmamk_f32 v156, v156, 0x3a800000, v176
	v_mul_f32_e32 v157, 0x4b800000, v156
	v_cmp_gt_f32_e32 vcc, s53, v156
	s_nop 1
	v_cndmask_b32_e32 v156, v156, v157, vcc
	v_rsq_f32_e32 v162, v156
	v_lshlrev_b64 v[156:157], 13, v[138:139]
	v_lshl_add_u64 v[156:157], s[92:93], 0, v[156:157]
	v_lshl_add_u64 v[156:157], v[156:157], 0, v[140:141]
	v_mul_f32_e32 v139, 0x45800000, v162
	v_cndmask_b32_e32 v162, v162, v139, vcc
	v_pk_mul_f32 v[126:127], v[126:127], v[162:163] op_sel_hi:[1,0]
	v_pk_mul_f32 v[124:125], v[124:125], v[162:163] op_sel_hi:[1,0]
	v_pk_mul_f32 v[122:123], v[122:123], v[162:163] op_sel_hi:[1,0]
	v_pk_mul_f32 v[120:121], v[120:121], v[162:163] op_sel_hi:[1,0]
	v_pk_mul_f32 v[118:119], v[118:119], v[162:163] op_sel_hi:[1,0]
	v_pk_mul_f32 v[116:117], v[116:117], v[162:163] op_sel_hi:[1,0]
	v_pk_mul_f32 v[114:115], v[114:115], v[162:163] op_sel_hi:[1,0]
	v_pk_mul_f32 v[112:113], v[112:113], v[162:163] op_sel_hi:[1,0]
	v_max_f32_e32 v124, 0, v124
	v_max_f32_e32 v120, 0, v120
	v_max_f32_e32 v125, 0, v125
	v_max_f32_e32 v121, 0, v121
	v_max_f32_e32 v126, 0, v126
	v_max_f32_e32 v122, 0, v122
	v_max_f32_e32 v127, 0, v127
	v_max_f32_e32 v123, 0, v123
	v_max_f32_e32 v116, 0, v116
	v_max_f32_e32 v112, 0, v112
	v_max_f32_e32 v117, 0, v117
	v_max_f32_e32 v113, 0, v113
	v_max_f32_e32 v118, 0, v118
	v_max_f32_e32 v114, 0, v114
	v_max_f32_e32 v119, 0, v119
	v_max_f32_e32 v115, 0, v115
	v_mul_f32_e32 v124, v124, v124
	v_mul_f32_e32 v120, v120, v120
	v_mul_f32_e32 v125, v125, v125
	v_mul_f32_e32 v121, v121, v121
	v_mul_f32_e32 v126, v126, v126
	v_mul_f32_e32 v122, v122, v122
	v_mul_f32_e32 v127, v127, v127
	v_mul_f32_e32 v123, v123, v123
	v_mul_f32_e32 v116, v116, v116
	v_mul_f32_e32 v139, v112, v112
	v_mul_f32_e32 v117, v117, v117
	v_mul_f32_e32 v162, v113, v113
	v_mul_f32_e32 v118, v118, v118
	v_mul_f32_e32 v163, v114, v114
	v_mul_f32_e32 v119, v119, v119
	v_mul_f32_e32 v164, v115, v115
	v_cvt_pk_bf16_f32 v112, v124, v125
	v_cvt_pk_bf16_f32 v113, v126, v127
	v_cvt_pk_bf16_f32 v114, v120, v121
	v_cvt_pk_bf16_f32 v115, v122, v123
	v_cvt_pk_bf16_f32 v116, v116, v117
	v_cvt_pk_bf16_f32 v117, v118, v119
	v_cvt_pk_bf16_f32 v118, v139, v162
	v_cvt_pk_bf16_f32 v119, v163, v164
	global_store_dwordx4 v[156:157], v[112:115], off
	global_store_dwordx4 v[156:157], v[116:119], off offset:256
	s_nop 1
	v_mov_b32_e32 v112, v226
	s_nop 0
	v_mov_b32_e32 v114, v227
	v_mov_b32_e32 v113, v228
	v_mov_b32_e32 v115, v229
	v_add_u32_e32 v116, 16, v138
	v_ashrrev_i32_e32 v117, 31, v116
	v_pk_add_f32 v[112:113], v[112:113], v[114:115]
	s_nop 0
	v_add_f32_e32 v112, v112, v113
	v_fmamk_f32 v112, v112, 0x3a800000, v176
	v_mul_f32_e32 v113, 0x4b800000, v112
	v_cmp_gt_f32_e32 vcc, s53, v112
	s_nop 1
	v_cndmask_b32_e32 v112, v112, v113, vcc
	v_rsq_f32_e32 v114, v112
	v_lshlrev_b64 v[112:113], 13, v[116:117]
	v_lshl_add_u64 v[112:113], s[92:93], 0, v[112:113]
	v_lshl_add_u64 v[112:113], v[112:113], 0, v[140:141]
	v_mul_f32_e32 v115, 0x45800000, v114
	v_cndmask_b32_e32 v114, v114, v115, vcc
	v_pk_mul_f32 v[110:111], v[110:111], v[114:115] op_sel_hi:[1,0]
	v_pk_mul_f32 v[108:109], v[108:109], v[114:115] op_sel_hi:[1,0]
	v_pk_mul_f32 v[106:107], v[106:107], v[114:115] op_sel_hi:[1,0]
	v_pk_mul_f32 v[104:105], v[104:105], v[114:115] op_sel_hi:[1,0]
	v_pk_mul_f32 v[102:103], v[102:103], v[114:115] op_sel_hi:[1,0]
	v_pk_mul_f32 v[100:101], v[100:101], v[114:115] op_sel_hi:[1,0]
	v_pk_mul_f32 v[98:99], v[98:99], v[114:115] op_sel_hi:[1,0]
	v_pk_mul_f32 v[96:97], v[96:97], v[114:115] op_sel_hi:[1,0]
	v_max_f32_e32 v108, 0, v108
	v_max_f32_e32 v104, 0, v104
	v_max_f32_e32 v109, 0, v109
	v_max_f32_e32 v105, 0, v105
	v_max_f32_e32 v110, 0, v110
	v_max_f32_e32 v106, 0, v106
	v_max_f32_e32 v111, 0, v111
	v_max_f32_e32 v107, 0, v107
	v_max_f32_e32 v100, 0, v100
	v_max_f32_e32 v96, 0, v96
	v_max_f32_e32 v101, 0, v101
	v_max_f32_e32 v97, 0, v97
	v_max_f32_e32 v102, 0, v102
	v_max_f32_e32 v98, 0, v98
	v_max_f32_e32 v103, 0, v103
	v_max_f32_e32 v99, 0, v99
	v_mul_f32_e32 v108, v108, v108
	v_mul_f32_e32 v104, v104, v104
	v_mul_f32_e32 v109, v109, v109
	v_mul_f32_e32 v105, v105, v105
	v_mul_f32_e32 v110, v110, v110
	v_mul_f32_e32 v106, v106, v106
	v_mul_f32_e32 v111, v111, v111
	v_mul_f32_e32 v107, v107, v107
	v_mul_f32_e32 v100, v100, v100
	v_mul_f32_e32 v114, v96, v96
	v_mul_f32_e32 v101, v101, v101
	v_mul_f32_e32 v115, v97, v97
	v_mul_f32_e32 v102, v102, v102
	v_mul_f32_e32 v116, v98, v98
	v_mul_f32_e32 v103, v103, v103
	v_mul_f32_e32 v117, v99, v99
	v_cvt_pk_bf16_f32 v96, v108, v109
	v_cvt_pk_bf16_f32 v97, v110, v111
	v_cvt_pk_bf16_f32 v98, v104, v105
	v_cvt_pk_bf16_f32 v99, v106, v107
	v_cvt_pk_bf16_f32 v100, v100, v101
	v_cvt_pk_bf16_f32 v101, v102, v103
	v_cvt_pk_bf16_f32 v102, v114, v115
	v_cvt_pk_bf16_f32 v103, v116, v117
	global_store_dwordx4 v[112:113], v[96:99], off
	global_store_dwordx4 v[112:113], v[100:103], off offset:256
	s_nop 1
	v_mov_b32_e32 v96, v230
	s_nop 0
	v_mov_b32_e32 v98, v231
	v_mov_b32_e32 v97, v232
	v_mov_b32_e32 v99, v233
	v_add_u32_e32 v100, 32, v138
	v_ashrrev_i32_e32 v101, 31, v100
	v_pk_add_f32 v[96:97], v[96:97], v[98:99]
	s_nop 0
	v_add_f32_e32 v96, v96, v97
	v_fmamk_f32 v96, v96, 0x3a800000, v176
	v_mul_f32_e32 v97, 0x4b800000, v96
	v_cmp_gt_f32_e32 vcc, s53, v96
	s_nop 1
	v_cndmask_b32_e32 v96, v96, v97, vcc
	v_rsq_f32_e32 v98, v96
	v_lshlrev_b64 v[96:97], 13, v[100:101]
	v_lshl_add_u64 v[96:97], s[92:93], 0, v[96:97]
	v_lshl_add_u64 v[96:97], v[96:97], 0, v[140:141]
	v_mul_f32_e32 v99, 0x45800000, v98
	v_cndmask_b32_e32 v98, v98, v99, vcc
	v_pk_mul_f32 v[94:95], v[94:95], v[98:99] op_sel_hi:[1,0]
	v_pk_mul_f32 v[92:93], v[92:93], v[98:99] op_sel_hi:[1,0]
	v_pk_mul_f32 v[90:91], v[90:91], v[98:99] op_sel_hi:[1,0]
	v_pk_mul_f32 v[88:89], v[88:89], v[98:99] op_sel_hi:[1,0]
	v_pk_mul_f32 v[86:87], v[86:87], v[98:99] op_sel_hi:[1,0]
	v_pk_mul_f32 v[84:85], v[84:85], v[98:99] op_sel_hi:[1,0]
	v_pk_mul_f32 v[82:83], v[82:83], v[98:99] op_sel_hi:[1,0]
	v_pk_mul_f32 v[80:81], v[80:81], v[98:99] op_sel_hi:[1,0]
	v_max_f32_e32 v92, 0, v92
	v_max_f32_e32 v88, 0, v88
	v_max_f32_e32 v93, 0, v93
	v_max_f32_e32 v89, 0, v89
	v_max_f32_e32 v94, 0, v94
	v_max_f32_e32 v90, 0, v90
	v_max_f32_e32 v95, 0, v95
	v_max_f32_e32 v91, 0, v91
	v_max_f32_e32 v84, 0, v84
	v_max_f32_e32 v80, 0, v80
	v_max_f32_e32 v85, 0, v85
	v_max_f32_e32 v81, 0, v81
	v_max_f32_e32 v86, 0, v86
	v_max_f32_e32 v82, 0, v82
	v_max_f32_e32 v87, 0, v87
	v_max_f32_e32 v83, 0, v83
	v_mul_f32_e32 v92, v92, v92
	v_mul_f32_e32 v88, v88, v88
	v_mul_f32_e32 v93, v93, v93
	v_mul_f32_e32 v89, v89, v89
	v_mul_f32_e32 v94, v94, v94
	v_mul_f32_e32 v90, v90, v90
	v_mul_f32_e32 v95, v95, v95
	v_mul_f32_e32 v91, v91, v91
	v_mul_f32_e32 v84, v84, v84
	v_mul_f32_e32 v98, v80, v80
	v_mul_f32_e32 v85, v85, v85
	v_mul_f32_e32 v99, v81, v81
	v_mul_f32_e32 v86, v86, v86
	v_mul_f32_e32 v100, v82, v82
	v_mul_f32_e32 v87, v87, v87
	v_mul_f32_e32 v101, v83, v83
	v_cvt_pk_bf16_f32 v80, v92, v93
	v_cvt_pk_bf16_f32 v81, v94, v95
	v_cvt_pk_bf16_f32 v82, v88, v89
	v_cvt_pk_bf16_f32 v83, v90, v91
	v_cvt_pk_bf16_f32 v84, v84, v85
	v_cvt_pk_bf16_f32 v85, v86, v87
	v_cvt_pk_bf16_f32 v86, v98, v99
	v_cvt_pk_bf16_f32 v87, v100, v101
	global_store_dwordx4 v[96:97], v[80:83], off
	global_store_dwordx4 v[96:97], v[84:87], off offset:256
	s_nop 1
	v_mov_b32_e32 v80, v234
	s_nop 0
	v_mov_b32_e32 v82, v235
	v_mov_b32_e32 v81, v236
	v_mov_b32_e32 v83, v237
	v_add_u32_e32 v84, 48, v138
	v_ashrrev_i32_e32 v85, 31, v84
	v_pk_add_f32 v[80:81], v[80:81], v[82:83]
	s_nop 0
	v_add_f32_e32 v80, v80, v81
	v_fmamk_f32 v80, v80, 0x3a800000, v176
	v_mul_f32_e32 v81, 0x4b800000, v80
	v_cmp_gt_f32_e32 vcc, s53, v80
	s_nop 1
	v_cndmask_b32_e32 v80, v80, v81, vcc
	v_rsq_f32_e32 v82, v80
	v_lshlrev_b64 v[80:81], 13, v[84:85]
	v_lshl_add_u64 v[80:81], s[92:93], 0, v[80:81]
	v_lshl_add_u64 v[80:81], v[80:81], 0, v[140:141]
	v_mul_f32_e32 v83, 0x45800000, v82
	v_cndmask_b32_e32 v82, v82, v83, vcc
	v_pk_mul_f32 v[78:79], v[78:79], v[82:83] op_sel_hi:[1,0]
	v_pk_mul_f32 v[76:77], v[76:77], v[82:83] op_sel_hi:[1,0]
	v_pk_mul_f32 v[74:75], v[74:75], v[82:83] op_sel_hi:[1,0]
	v_pk_mul_f32 v[72:73], v[72:73], v[82:83] op_sel_hi:[1,0]
	v_pk_mul_f32 v[70:71], v[70:71], v[82:83] op_sel_hi:[1,0]
	v_pk_mul_f32 v[68:69], v[68:69], v[82:83] op_sel_hi:[1,0]
	v_pk_mul_f32 v[66:67], v[66:67], v[82:83] op_sel_hi:[1,0]
	v_pk_mul_f32 v[64:65], v[64:65], v[82:83] op_sel_hi:[1,0]
	v_max_f32_e32 v76, 0, v76
	v_max_f32_e32 v72, 0, v72
	v_max_f32_e32 v77, 0, v77
	v_max_f32_e32 v73, 0, v73
	v_max_f32_e32 v78, 0, v78
	v_max_f32_e32 v74, 0, v74
	v_max_f32_e32 v79, 0, v79
	v_max_f32_e32 v75, 0, v75
	v_max_f32_e32 v68, 0, v68
	v_max_f32_e32 v64, 0, v64
	v_max_f32_e32 v69, 0, v69
	v_max_f32_e32 v65, 0, v65
	v_max_f32_e32 v70, 0, v70
	v_max_f32_e32 v66, 0, v66
	v_max_f32_e32 v71, 0, v71
	v_max_f32_e32 v67, 0, v67
	v_mul_f32_e32 v76, v76, v76
	v_mul_f32_e32 v72, v72, v72
	v_mul_f32_e32 v77, v77, v77
	v_mul_f32_e32 v73, v73, v73
	v_mul_f32_e32 v78, v78, v78
	v_mul_f32_e32 v74, v74, v74
	v_mul_f32_e32 v79, v79, v79
	v_mul_f32_e32 v75, v75, v75
	v_mul_f32_e32 v68, v68, v68
	v_mul_f32_e32 v82, v64, v64
	v_mul_f32_e32 v69, v69, v69
	v_mul_f32_e32 v83, v65, v65
	v_mul_f32_e32 v70, v70, v70
	v_mul_f32_e32 v84, v66, v66
	v_mul_f32_e32 v71, v71, v71
	v_mul_f32_e32 v85, v67, v67
	v_cvt_pk_bf16_f32 v64, v76, v77
	v_cvt_pk_bf16_f32 v65, v78, v79
	v_cvt_pk_bf16_f32 v66, v72, v73
	v_cvt_pk_bf16_f32 v67, v74, v75
	v_cvt_pk_bf16_f32 v68, v68, v69
	v_cvt_pk_bf16_f32 v69, v70, v71
	v_cvt_pk_bf16_f32 v70, v82, v83
	v_cvt_pk_bf16_f32 v71, v84, v85
	global_store_dwordx4 v[80:81], v[64:67], off
	global_store_dwordx4 v[80:81], v[68:71], off offset:256
	s_nop 1
	v_mov_b32_e32 v64, v238
	s_nop 0
	v_mov_b32_e32 v66, v239
	v_mov_b32_e32 v65, v240
	v_mov_b32_e32 v67, v241
	v_add_u32_e32 v68, 0x80, v138
	v_ashrrev_i32_e32 v69, 31, v68
	v_pk_add_f32 v[64:65], v[64:65], v[66:67]
	s_nop 0
	v_add_f32_e32 v64, v64, v65
	v_fmamk_f32 v64, v64, 0x3a800000, v176
	v_mul_f32_e32 v65, 0x4b800000, v64
	v_cmp_gt_f32_e32 vcc, s53, v64
	s_nop 1
	v_cndmask_b32_e32 v64, v64, v65, vcc
	v_rsq_f32_e32 v66, v64
	v_lshlrev_b64 v[64:65], 13, v[68:69]
	v_lshl_add_u64 v[64:65], s[92:93], 0, v[64:65]
	v_lshl_add_u64 v[64:65], v[64:65], 0, v[140:141]
	v_mul_f32_e32 v67, 0x45800000, v66
	v_cndmask_b32_e32 v66, v66, v67, vcc
	v_pk_mul_f32 v[62:63], v[62:63], v[66:67] op_sel_hi:[1,0]
	v_pk_mul_f32 v[60:61], v[60:61], v[66:67] op_sel_hi:[1,0]
	v_pk_mul_f32 v[58:59], v[58:59], v[66:67] op_sel_hi:[1,0]
	v_pk_mul_f32 v[56:57], v[56:57], v[66:67] op_sel_hi:[1,0]
	v_pk_mul_f32 v[54:55], v[54:55], v[66:67] op_sel_hi:[1,0]
	v_pk_mul_f32 v[52:53], v[52:53], v[66:67] op_sel_hi:[1,0]
	v_pk_mul_f32 v[50:51], v[50:51], v[66:67] op_sel_hi:[1,0]
	v_pk_mul_f32 v[48:49], v[48:49], v[66:67] op_sel_hi:[1,0]
	v_max_f32_e32 v60, 0, v60
	v_max_f32_e32 v56, 0, v56
	v_max_f32_e32 v61, 0, v61
	v_max_f32_e32 v57, 0, v57
	v_max_f32_e32 v62, 0, v62
	v_max_f32_e32 v58, 0, v58
	v_max_f32_e32 v63, 0, v63
	v_max_f32_e32 v59, 0, v59
	v_max_f32_e32 v52, 0, v52
	v_max_f32_e32 v48, 0, v48
	v_max_f32_e32 v53, 0, v53
	v_max_f32_e32 v49, 0, v49
	v_max_f32_e32 v54, 0, v54
	v_max_f32_e32 v50, 0, v50
	v_max_f32_e32 v55, 0, v55
	v_max_f32_e32 v51, 0, v51
	v_mul_f32_e32 v60, v60, v60
	v_mul_f32_e32 v56, v56, v56
	v_mul_f32_e32 v61, v61, v61
	v_mul_f32_e32 v57, v57, v57
	v_mul_f32_e32 v62, v62, v62
	v_mul_f32_e32 v58, v58, v58
	v_mul_f32_e32 v63, v63, v63
	v_mul_f32_e32 v59, v59, v59
	v_mul_f32_e32 v52, v52, v52
	v_mul_f32_e32 v66, v48, v48
	v_mul_f32_e32 v53, v53, v53
	v_mul_f32_e32 v67, v49, v49
	v_mul_f32_e32 v54, v54, v54
	v_mul_f32_e32 v68, v50, v50
	v_mul_f32_e32 v55, v55, v55
	v_mul_f32_e32 v69, v51, v51
	v_cvt_pk_bf16_f32 v48, v60, v61
	v_cvt_pk_bf16_f32 v49, v62, v63
	v_cvt_pk_bf16_f32 v50, v56, v57
	v_cvt_pk_bf16_f32 v51, v58, v59
	v_cvt_pk_bf16_f32 v52, v52, v53
	v_cvt_pk_bf16_f32 v53, v54, v55
	v_cvt_pk_bf16_f32 v54, v66, v67
	v_cvt_pk_bf16_f32 v55, v68, v69
	global_store_dwordx4 v[64:65], v[48:51], off
	global_store_dwordx4 v[64:65], v[52:55], off offset:256
	s_nop 1
	v_mov_b32_e32 v48, v242
	s_nop 0
	v_mov_b32_e32 v50, v243
	v_mov_b32_e32 v49, v244
	v_mov_b32_e32 v51, v245
	v_add_u32_e32 v52, 0x90, v138
	v_ashrrev_i32_e32 v53, 31, v52
	v_pk_add_f32 v[48:49], v[48:49], v[50:51]
	s_nop 0
	v_add_f32_e32 v48, v48, v49
	v_fmamk_f32 v48, v48, 0x3a800000, v176
	v_mul_f32_e32 v49, 0x4b800000, v48
	v_cmp_gt_f32_e32 vcc, s53, v48
	s_nop 1
	v_cndmask_b32_e32 v48, v48, v49, vcc
	v_rsq_f32_e32 v50, v48
	v_lshlrev_b64 v[48:49], 13, v[52:53]
	v_lshl_add_u64 v[48:49], s[92:93], 0, v[48:49]
	v_lshl_add_u64 v[48:49], v[48:49], 0, v[140:141]
	v_mul_f32_e32 v51, 0x45800000, v50
	v_cndmask_b32_e32 v50, v50, v51, vcc
	v_pk_mul_f32 v[46:47], v[46:47], v[50:51] op_sel_hi:[1,0]
	v_pk_mul_f32 v[44:45], v[44:45], v[50:51] op_sel_hi:[1,0]
	v_pk_mul_f32 v[42:43], v[42:43], v[50:51] op_sel_hi:[1,0]
	v_pk_mul_f32 v[40:41], v[40:41], v[50:51] op_sel_hi:[1,0]
	v_pk_mul_f32 v[38:39], v[38:39], v[50:51] op_sel_hi:[1,0]
	v_pk_mul_f32 v[36:37], v[36:37], v[50:51] op_sel_hi:[1,0]
	v_pk_mul_f32 v[34:35], v[34:35], v[50:51] op_sel_hi:[1,0]
	v_pk_mul_f32 v[32:33], v[32:33], v[50:51] op_sel_hi:[1,0]
	v_max_f32_e32 v44, 0, v44
	v_max_f32_e32 v40, 0, v40
	v_max_f32_e32 v45, 0, v45
	v_max_f32_e32 v41, 0, v41
	v_max_f32_e32 v46, 0, v46
	v_max_f32_e32 v42, 0, v42
	v_max_f32_e32 v47, 0, v47
	v_max_f32_e32 v43, 0, v43
	v_max_f32_e32 v36, 0, v36
	v_max_f32_e32 v32, 0, v32
	v_max_f32_e32 v37, 0, v37
	v_max_f32_e32 v33, 0, v33
	v_max_f32_e32 v38, 0, v38
	v_max_f32_e32 v34, 0, v34
	v_max_f32_e32 v39, 0, v39
	v_max_f32_e32 v35, 0, v35
	v_mul_f32_e32 v44, v44, v44
	v_mul_f32_e32 v40, v40, v40
	v_mul_f32_e32 v45, v45, v45
	v_mul_f32_e32 v41, v41, v41
	v_mul_f32_e32 v46, v46, v46
	v_mul_f32_e32 v42, v42, v42
	v_mul_f32_e32 v47, v47, v47
	v_mul_f32_e32 v43, v43, v43
	v_mul_f32_e32 v36, v36, v36
	v_mul_f32_e32 v50, v32, v32
	v_mul_f32_e32 v37, v37, v37
	v_mul_f32_e32 v51, v33, v33
	v_mul_f32_e32 v38, v38, v38
	v_mul_f32_e32 v52, v34, v34
	v_mul_f32_e32 v39, v39, v39
	v_mul_f32_e32 v53, v35, v35
	v_cvt_pk_bf16_f32 v32, v44, v45
	v_cvt_pk_bf16_f32 v33, v46, v47
	v_cvt_pk_bf16_f32 v34, v40, v41
	v_cvt_pk_bf16_f32 v35, v42, v43
	v_cvt_pk_bf16_f32 v36, v36, v37
	v_cvt_pk_bf16_f32 v37, v38, v39
	v_cvt_pk_bf16_f32 v38, v50, v51
	v_cvt_pk_bf16_f32 v39, v52, v53
	global_store_dwordx4 v[48:49], v[32:35], off
	global_store_dwordx4 v[48:49], v[36:39], off offset:256
	s_nop 1
	v_mov_b32_e32 v32, v246
	s_nop 0
	v_mov_b32_e32 v34, v247
	v_mov_b32_e32 v33, v248
	v_mov_b32_e32 v35, v249
	v_add_u32_e32 v36, 0xa0, v138
	v_ashrrev_i32_e32 v37, 31, v36
	v_pk_add_f32 v[32:33], v[32:33], v[34:35]
	s_nop 0
	v_add_f32_e32 v32, v32, v33
	v_fmamk_f32 v32, v32, 0x3a800000, v176
	v_mul_f32_e32 v33, 0x4b800000, v32
	v_cmp_gt_f32_e32 vcc, s53, v32
	s_nop 1
	v_cndmask_b32_e32 v32, v32, v33, vcc
	v_rsq_f32_e32 v34, v32
	v_lshlrev_b64 v[32:33], 13, v[36:37]
	v_lshl_add_u64 v[32:33], s[92:93], 0, v[32:33]
	v_lshl_add_u64 v[32:33], v[32:33], 0, v[140:141]
	v_mul_f32_e32 v35, 0x45800000, v34
	v_cndmask_b32_e32 v34, v34, v35, vcc
	v_pk_mul_f32 v[30:31], v[30:31], v[34:35] op_sel_hi:[1,0]
	v_pk_mul_f32 v[28:29], v[28:29], v[34:35] op_sel_hi:[1,0]
	v_pk_mul_f32 v[26:27], v[26:27], v[34:35] op_sel_hi:[1,0]
	v_pk_mul_f32 v[24:25], v[24:25], v[34:35] op_sel_hi:[1,0]
	v_pk_mul_f32 v[22:23], v[22:23], v[34:35] op_sel_hi:[1,0]
	v_pk_mul_f32 v[20:21], v[20:21], v[34:35] op_sel_hi:[1,0]
	v_pk_mul_f32 v[18:19], v[18:19], v[34:35] op_sel_hi:[1,0]
	v_pk_mul_f32 v[16:17], v[16:17], v[34:35] op_sel_hi:[1,0]
	v_max_f32_e32 v28, 0, v28
	v_max_f32_e32 v24, 0, v24
	v_max_f32_e32 v29, 0, v29
	v_max_f32_e32 v25, 0, v25
	v_max_f32_e32 v30, 0, v30
	v_max_f32_e32 v26, 0, v26
	v_max_f32_e32 v31, 0, v31
	v_max_f32_e32 v27, 0, v27
	v_max_f32_e32 v20, 0, v20
	v_max_f32_e32 v16, 0, v16
	v_max_f32_e32 v21, 0, v21
	v_max_f32_e32 v17, 0, v17
	v_max_f32_e32 v22, 0, v22
	v_max_f32_e32 v18, 0, v18
	v_max_f32_e32 v23, 0, v23
	v_max_f32_e32 v19, 0, v19
	v_mul_f32_e32 v28, v28, v28
	v_mul_f32_e32 v24, v24, v24
	v_mul_f32_e32 v29, v29, v29
	v_mul_f32_e32 v25, v25, v25
	v_mul_f32_e32 v30, v30, v30
	v_mul_f32_e32 v26, v26, v26
	v_mul_f32_e32 v31, v31, v31
	v_mul_f32_e32 v27, v27, v27
	v_mul_f32_e32 v20, v20, v20
	v_mul_f32_e32 v34, v16, v16
	v_mul_f32_e32 v21, v21, v21
	v_mul_f32_e32 v35, v17, v17
	v_mul_f32_e32 v22, v22, v22
	v_mul_f32_e32 v36, v18, v18
	v_mul_f32_e32 v23, v23, v23
	v_mul_f32_e32 v37, v19, v19
	v_cvt_pk_bf16_f32 v16, v28, v29
	v_cvt_pk_bf16_f32 v17, v30, v31
	v_cvt_pk_bf16_f32 v18, v24, v25
	v_cvt_pk_bf16_f32 v19, v26, v27
	v_cvt_pk_bf16_f32 v20, v20, v21
	v_cvt_pk_bf16_f32 v21, v22, v23
	v_cvt_pk_bf16_f32 v22, v34, v35
	v_cvt_pk_bf16_f32 v23, v36, v37
	global_store_dwordx4 v[32:33], v[16:19], off
	global_store_dwordx4 v[32:33], v[20:23], off offset:256
	s_nop 1
	v_mov_b32_e32 v16, v250
	s_nop 0
	v_mov_b32_e32 v18, v251
	v_mov_b32_e32 v17, v252
	v_mov_b32_e32 v19, v253
	s_and_b64 vcc, exec, s[4:5]
	v_add_u32_e32 v20, 0xb0, v138
	v_ashrrev_i32_e32 v21, 31, v20
	v_pk_add_f32 v[16:17], v[16:17], v[18:19]
	s_nop 0
	v_add_f32_e32 v16, v16, v17
	v_fmamk_f32 v16, v16, 0x3a800000, v176
	v_mul_f32_e32 v17, 0x4b800000, v16
	v_cmp_gt_f32_e64 s[4:5], s53, v16
	s_nop 1
	v_cndmask_b32_e64 v16, v16, v17, s[4:5]
	v_rsq_f32_e32 v18, v16
	v_lshlrev_b64 v[16:17], 13, v[20:21]
	v_lshl_add_u64 v[16:17], s[92:93], 0, v[16:17]
	v_lshl_add_u64 v[16:17], v[16:17], 0, v[140:141]
	v_mul_f32_e32 v19, 0x45800000, v18
	v_cndmask_b32_e64 v18, v18, v19, s[4:5]
	v_pk_mul_f32 v[14:15], v[14:15], v[18:19] op_sel_hi:[1,0]
	v_pk_mul_f32 v[12:13], v[12:13], v[18:19] op_sel_hi:[1,0]
	v_pk_mul_f32 v[10:11], v[10:11], v[18:19] op_sel_hi:[1,0]
	v_pk_mul_f32 v[8:9], v[8:9], v[18:19] op_sel_hi:[1,0]
	v_pk_mul_f32 v[6:7], v[6:7], v[18:19] op_sel_hi:[1,0]
	v_pk_mul_f32 v[4:5], v[4:5], v[18:19] op_sel_hi:[1,0]
	v_pk_mul_f32 v[2:3], v[2:3], v[18:19] op_sel_hi:[1,0]
	v_pk_mul_f32 v[0:1], v[0:1], v[18:19] op_sel_hi:[1,0]
	v_max_f32_e32 v12, 0, v12
	v_max_f32_e32 v8, 0, v8
	v_max_f32_e32 v13, 0, v13
	v_max_f32_e32 v9, 0, v9
	v_max_f32_e32 v14, 0, v14
	v_max_f32_e32 v10, 0, v10
	v_max_f32_e32 v15, 0, v15
	v_max_f32_e32 v11, 0, v11
	v_max_f32_e32 v4, 0, v4
	v_max_f32_e32 v0, 0, v0
	v_max_f32_e32 v5, 0, v5
	v_max_f32_e32 v1, 0, v1
	v_max_f32_e32 v6, 0, v6
	v_max_f32_e32 v2, 0, v2
	v_max_f32_e32 v7, 0, v7
	v_max_f32_e32 v3, 0, v3
	v_mul_f32_e32 v12, v12, v12
	v_mul_f32_e32 v8, v8, v8
	v_mul_f32_e32 v13, v13, v13
	v_mul_f32_e32 v9, v9, v9
	v_mul_f32_e32 v14, v14, v14
	v_mul_f32_e32 v10, v10, v10
	v_mul_f32_e32 v15, v15, v15
	v_mul_f32_e32 v11, v11, v11
	v_mul_f32_e32 v4, v4, v4
	v_mul_f32_e32 v18, v0, v0
	v_mul_f32_e32 v5, v5, v5
	v_mul_f32_e32 v19, v1, v1
	v_mul_f32_e32 v6, v6, v6
	v_mul_f32_e32 v20, v2, v2
	v_mul_f32_e32 v7, v7, v7
	v_mul_f32_e32 v21, v3, v3
	v_cvt_pk_bf16_f32 v0, v12, v13
	v_cvt_pk_bf16_f32 v1, v14, v15
	v_cvt_pk_bf16_f32 v2, v8, v9
	v_cvt_pk_bf16_f32 v3, v10, v11
	v_cvt_pk_bf16_f32 v4, v4, v5
	v_cvt_pk_bf16_f32 v5, v6, v7
	v_cvt_pk_bf16_f32 v6, v18, v19
	v_cvt_pk_bf16_f32 v7, v20, v21
	global_store_dwordx4 v[16:17], v[0:3], off
	global_store_dwordx4 v[16:17], v[4:7], off offset:256
	s_cbranch_vccz .LBB0_919
	s_waitcnt vmcnt(0)
	s_cmpk_gt_u32 s43, 0xff
	s_cbranch_scc1 .LBB0_930
	s_barrier
